# GEMM K-loops: s_setprio 1 moved before the pre-MFMA barrier, redundant post-barrier lgkmcnt(0) removed, s_setprio 0 moved after the post-MFMA barrier (fewer issue slots in the MFMA hand-over gap)
# speedup vs baseline: 1.0027x; 1.0027x over previous
.LBB0_103:
	ds_read_b128 v[150:153], v147
	ds_read_b128 v[154:157], v147 offset:1024
	ds_read_b128 v[158:161], v147 offset:2048
	ds_read_b128 v[162:165], v147 offset:3072
	ds_read_b128 v[166:169], v148
	ds_read_b128 v[170:173], v148 offset:1024
	ds_read_b128 v[174:177], v148 offset:2048
	ds_read_b128 v[178:181], v148 offset:3072
	s_add_u32 s26, s24, 0xfff80080
	s_addc_u32 s27, s25, -1
	s_cmp_eq_u32 s65, 28
	s_cselect_b32 s29, s19, s27
	s_cselect_b32 s28, s47, s26
	s_cselect_b32 s27, s17, s64
	s_cselect_b32 s26, s48, s49
	v_lshl_add_u64 v[216:217], s[24:25], 0, v[136:137]
	s_add_i32 m0, s15, 0xc000
	ds_read_b128 v[182:185], v149
	ds_read_b128 v[186:189], v149 offset:1024
	ds_read_b128 v[192:195], v149 offset:2048
	ds_read_b128 v[196:199], v149 offset:3072
	ds_read_b128 v[200:203], v149 offset:4096
	ds_read_b128 v[204:207], v149 offset:5120
	ds_read_b128 v[208:211], v149 offset:6144
	ds_read_b128 v[212:215], v149 offset:7168
	global_load_lds_dwordx4 v[216:217], off
	v_lshl_add_u64 v[216:217], s[24:25], 0, v[138:139]
	s_add_i32 m0, s15, 0xe000
	s_nop 0
	global_load_lds_dwordx4 v[216:217], off
	s_waitcnt vmcnt(8)
	s_waitcnt lgkmcnt(0)
	s_setprio 1
	s_barrier
	v_mfma_f32_16x16x32_bf16 v[124:127], v[150:153], v[182:185], v[124:127]
	v_mfma_f32_16x16x32_bf16 v[120:123], v[158:161], v[182:185], v[120:123]
	v_mfma_f32_16x16x32_bf16 v[116:119], v[150:153], v[192:195], v[116:119]
	v_mfma_f32_16x16x32_bf16 v[112:115], v[158:161], v[192:195], v[112:115]
	v_mfma_f32_16x16x32_bf16 v[100:103], v[150:153], v[200:203], v[100:103]
	v_mfma_f32_16x16x32_bf16 v[96:99], v[158:161], v[200:203], v[96:99]
	v_mfma_f32_16x16x32_bf16 v[84:87], v[150:153], v[208:211], v[84:87]
	v_mfma_f32_16x16x32_bf16 v[80:83], v[158:161], v[208:211], v[80:83]
	v_mfma_f32_16x16x32_bf16 v[124:127], v[154:157], v[186:189], v[124:127]
	v_mfma_f32_16x16x32_bf16 v[120:123], v[162:165], v[186:189], v[120:123]
	v_mfma_f32_16x16x32_bf16 v[116:119], v[154:157], v[196:199], v[116:119]
	v_mfma_f32_16x16x32_bf16 v[112:115], v[162:165], v[196:199], v[112:115]
	v_mfma_f32_16x16x32_bf16 v[100:103], v[154:157], v[204:207], v[100:103]
	v_mfma_f32_16x16x32_bf16 v[96:99], v[162:165], v[204:207], v[96:99]
	v_mfma_f32_16x16x32_bf16 v[84:87], v[154:157], v[212:215], v[84:87]
	v_mfma_f32_16x16x32_bf16 v[80:83], v[162:165], v[212:215], v[80:83]
	s_setprio 0
	s_setprio 1
	v_mfma_f32_16x16x32_bf16 v[108:111], v[166:169], v[182:185], v[108:111]
	v_mfma_f32_16x16x32_bf16 v[104:107], v[174:177], v[182:185], v[104:107]
	v_mfma_f32_16x16x32_bf16 v[92:95], v[166:169], v[192:195], v[92:95]
	v_mfma_f32_16x16x32_bf16 v[88:91], v[174:177], v[192:195], v[88:91]
	v_mfma_f32_16x16x32_bf16 v[76:79], v[166:169], v[200:203], v[76:79]
	v_mfma_f32_16x16x32_bf16 v[72:75], v[174:177], v[200:203], v[72:75]
	v_mfma_f32_16x16x32_bf16 v[68:71], v[166:169], v[208:211], v[68:71]
	v_mfma_f32_16x16x32_bf16 v[64:67], v[174:177], v[208:211], v[64:67]
	v_mfma_f32_16x16x32_bf16 v[108:111], v[170:173], v[186:189], v[108:111]
	v_mfma_f32_16x16x32_bf16 v[104:107], v[178:181], v[186:189], v[104:107]
	v_mfma_f32_16x16x32_bf16 v[92:95], v[170:173], v[196:199], v[92:95]
	v_mfma_f32_16x16x32_bf16 v[88:91], v[178:181], v[196:199], v[88:91]
	v_mfma_f32_16x16x32_bf16 v[76:79], v[170:173], v[204:207], v[76:79]
	v_mfma_f32_16x16x32_bf16 v[72:75], v[178:181], v[204:207], v[72:75]
	v_mfma_f32_16x16x32_bf16 v[68:71], v[170:173], v[212:215], v[68:71]
	v_mfma_f32_16x16x32_bf16 v[64:67], v[178:181], v[212:215], v[64:67]
	s_barrier
	s_setprio 0
	s_add_i32 s69, s44, s35
	v_lshl_add_u64 v[216:217], s[26:27], 0, v[130:131]
	s_mov_b32 m0, s69
	ds_read_b128 v[182:185], v149 offset:16384
	ds_read_b128 v[186:189], v149 offset:17408
	ds_read_b128 v[192:195], v149 offset:18432
	ds_read_b128 v[196:199], v149 offset:19456
	ds_read_b128 v[200:203], v149 offset:20480
	ds_read_b128 v[204:207], v149 offset:21504
	ds_read_b128 v[208:211], v149 offset:22528
	ds_read_b128 v[212:215], v149 offset:23552
	global_load_lds_dwordx4 v[216:217], off
	s_add_i32 m0, s69, 0x2000
	s_add_u32 s72, s26, 0x80000
	v_lshl_add_u64 v[218:219], s[26:27], 0, v[134:135]
	s_addc_u32 s73, s27, 0
	s_add_i32 s69, s45, s35
	global_load_lds_dwordx4 v[218:219], off
	v_lshl_add_u64 v[220:221], s[72:73], 0, v[130:131]
	s_mov_b32 m0, s69
	v_lshl_add_u64 v[222:223], s[28:29], 0, v[132:133]
	global_load_lds_dwordx4 v[220:221], off
	v_lshl_add_u64 v[220:221], s[72:73], 0, v[134:135]
	s_add_i32 m0, s69, 0x2000
	s_nop 0
	global_load_lds_dwordx4 v[220:221], off
	v_lshl_add_u64 v[220:221], s[28:29], 0, v[128:129]
	s_mov_b32 m0, s15
	s_nop 0
	global_load_lds_dwordx4 v[220:221], off
	s_mov_b32 m0, s36
	s_nop 0
	global_load_lds_dwordx4 v[222:223], off
	s_waitcnt vmcnt(8)
	s_waitcnt lgkmcnt(0)
	s_setprio 1
	s_barrier
	v_mfma_f32_16x16x32_bf16 v[60:63], v[150:153], v[182:185], v[60:63]
	v_mfma_f32_16x16x32_bf16 v[56:59], v[158:161], v[182:185], v[56:59]
	v_mfma_f32_16x16x32_bf16 v[52:55], v[150:153], v[192:195], v[52:55]
	v_mfma_f32_16x16x32_bf16 v[48:51], v[158:161], v[192:195], v[48:51]
	v_mfma_f32_16x16x32_bf16 v[36:39], v[150:153], v[200:203], v[36:39]
	v_mfma_f32_16x16x32_bf16 v[32:35], v[158:161], v[200:203], v[32:35]
	v_mfma_f32_16x16x32_bf16 v[20:23], v[150:153], v[208:211], v[20:23]
	v_mfma_f32_16x16x32_bf16 v[16:19], v[158:161], v[208:211], v[16:19]
	v_mfma_f32_16x16x32_bf16 v[60:63], v[154:157], v[186:189], v[60:63]
	v_mfma_f32_16x16x32_bf16 v[56:59], v[162:165], v[186:189], v[56:59]
	v_mfma_f32_16x16x32_bf16 v[52:55], v[154:157], v[196:199], v[52:55]
	v_mfma_f32_16x16x32_bf16 v[48:51], v[162:165], v[196:199], v[48:51]
	v_mfma_f32_16x16x32_bf16 v[36:39], v[154:157], v[204:207], v[36:39]
	v_mfma_f32_16x16x32_bf16 v[32:35], v[162:165], v[204:207], v[32:35]
	v_mfma_f32_16x16x32_bf16 v[20:23], v[154:157], v[212:215], v[20:23]
	v_mfma_f32_16x16x32_bf16 v[16:19], v[162:165], v[212:215], v[16:19]
	s_setprio 0
	s_setprio 1
	v_mfma_f32_16x16x32_bf16 v[44:47], v[166:169], v[182:185], v[44:47]
	v_mfma_f32_16x16x32_bf16 v[40:43], v[174:177], v[182:185], v[40:43]
	v_mfma_f32_16x16x32_bf16 v[28:31], v[166:169], v[192:195], v[28:31]
	v_mfma_f32_16x16x32_bf16 v[24:27], v[174:177], v[192:195], v[24:27]
	v_mfma_f32_16x16x32_bf16 v[12:15], v[166:169], v[200:203], v[12:15]
	v_mfma_f32_16x16x32_bf16 v[8:11], v[174:177], v[200:203], v[8:11]
	v_mfma_f32_16x16x32_bf16 v[4:7], v[166:169], v[208:211], v[4:7]
	v_mfma_f32_16x16x32_bf16 v[0:3], v[174:177], v[208:211], v[0:3]
	v_mfma_f32_16x16x32_bf16 v[44:47], v[170:173], v[186:189], v[44:47]
	v_mfma_f32_16x16x32_bf16 v[40:43], v[178:181], v[186:189], v[40:43]
	v_mfma_f32_16x16x32_bf16 v[28:31], v[170:173], v[196:199], v[28:31]
	v_mfma_f32_16x16x32_bf16 v[24:27], v[178:181], v[196:199], v[24:27]
	v_mfma_f32_16x16x32_bf16 v[12:15], v[170:173], v[204:207], v[12:15]
	v_mfma_f32_16x16x32_bf16 v[8:11], v[178:181], v[204:207], v[8:11]
	v_mfma_f32_16x16x32_bf16 v[4:7], v[170:173], v[212:215], v[4:7]
	v_mfma_f32_16x16x32_bf16 v[0:3], v[178:181], v[212:215], v[0:3]
	s_barrier
	s_setprio 0
	s_add_i32 s69, 0, 0x18000
	s_add_i32 s71, 0, 0x1c000
	v_add_u32_e32 v162, s69, v145
	v_add_u32_e32 v178, s71, v145
	ds_read_b128 v[150:153], v162
	ds_read_b128 v[154:157], v162 offset:1024
	ds_read_b128 v[158:161], v162 offset:2048
	ds_read_b128 v[162:165], v162 offset:3072
	ds_read_b128 v[166:169], v178
	ds_read_b128 v[170:173], v178 offset:1024
	ds_read_b128 v[174:177], v178 offset:2048
	ds_read_b128 v[178:181], v178 offset:3072
	s_add_u32 s28, s28, 0x80000
	s_addc_u32 s29, s29, 0
	s_mov_b32 m0, s37
	v_lshl_add_u64 v[224:225], s[28:29], 0, v[128:129]
	ds_read_b128 v[182:185], v149 offset:32768
	ds_read_b128 v[186:189], v149 offset:33792
	ds_read_b128 v[192:195], v149 offset:34816
	ds_read_b128 v[196:199], v149 offset:35840
	ds_read_b128 v[200:203], v149 offset:36864
	ds_read_b128 v[204:207], v149 offset:37888
	ds_read_b128 v[208:211], v149 offset:38912
	ds_read_b128 v[212:215], v149 offset:39936
	global_load_lds_dwordx4 v[224:225], off
	v_lshl_add_u64 v[224:225], s[28:29], 0, v[132:133]
	s_mov_b32 m0, s38
	s_nop 0
	global_load_lds_dwordx4 v[224:225], off
	s_waitcnt vmcnt(8)
	s_waitcnt lgkmcnt(0)
	s_setprio 1
	s_barrier
	v_mfma_f32_16x16x32_bf16 v[124:127], v[150:153], v[182:185], v[124:127]
	v_mfma_f32_16x16x32_bf16 v[120:123], v[158:161], v[182:185], v[120:123]
	v_mfma_f32_16x16x32_bf16 v[116:119], v[150:153], v[192:195], v[116:119]
	v_mfma_f32_16x16x32_bf16 v[112:115], v[158:161], v[192:195], v[112:115]
	v_mfma_f32_16x16x32_bf16 v[100:103], v[150:153], v[200:203], v[100:103]
	v_mfma_f32_16x16x32_bf16 v[96:99], v[158:161], v[200:203], v[96:99]
	v_mfma_f32_16x16x32_bf16 v[84:87], v[150:153], v[208:211], v[84:87]
	v_mfma_f32_16x16x32_bf16 v[80:83], v[158:161], v[208:211], v[80:83]
	v_mfma_f32_16x16x32_bf16 v[124:127], v[154:157], v[186:189], v[124:127]
	v_mfma_f32_16x16x32_bf16 v[120:123], v[162:165], v[186:189], v[120:123]
	v_mfma_f32_16x16x32_bf16 v[116:119], v[154:157], v[196:199], v[116:119]
	v_mfma_f32_16x16x32_bf16 v[112:115], v[162:165], v[196:199], v[112:115]
	v_mfma_f32_16x16x32_bf16 v[100:103], v[154:157], v[204:207], v[100:103]
	v_mfma_f32_16x16x32_bf16 v[96:99], v[162:165], v[204:207], v[96:99]
	v_mfma_f32_16x16x32_bf16 v[84:87], v[154:157], v[212:215], v[84:87]
	v_mfma_f32_16x16x32_bf16 v[80:83], v[162:165], v[212:215], v[80:83]
	s_setprio 0
	s_setprio 1
	v_mfma_f32_16x16x32_bf16 v[108:111], v[166:169], v[182:185], v[108:111]
	v_mfma_f32_16x16x32_bf16 v[104:107], v[174:177], v[182:185], v[104:107]
	v_mfma_f32_16x16x32_bf16 v[92:95], v[166:169], v[192:195], v[92:95]
	v_mfma_f32_16x16x32_bf16 v[88:91], v[174:177], v[192:195], v[88:91]
	v_mfma_f32_16x16x32_bf16 v[76:79], v[166:169], v[200:203], v[76:79]
	v_mfma_f32_16x16x32_bf16 v[72:75], v[174:177], v[200:203], v[72:75]
	v_mfma_f32_16x16x32_bf16 v[68:71], v[166:169], v[208:211], v[68:71]
	v_mfma_f32_16x16x32_bf16 v[64:67], v[174:177], v[208:211], v[64:67]
	v_mfma_f32_16x16x32_bf16 v[108:111], v[170:173], v[186:189], v[108:111]
	v_mfma_f32_16x16x32_bf16 v[104:107], v[178:181], v[186:189], v[104:107]
	v_mfma_f32_16x16x32_bf16 v[92:95], v[170:173], v[196:199], v[92:95]
	v_mfma_f32_16x16x32_bf16 v[88:91], v[178:181], v[196:199], v[88:91]
	v_mfma_f32_16x16x32_bf16 v[76:79], v[170:173], v[204:207], v[76:79]
	v_mfma_f32_16x16x32_bf16 v[72:75], v[178:181], v[204:207], v[72:75]
	v_mfma_f32_16x16x32_bf16 v[68:71], v[170:173], v[212:215], v[68:71]
	v_mfma_f32_16x16x32_bf16 v[64:67], v[178:181], v[212:215], v[64:67]
	s_barrier
	s_setprio 0
	s_add_i32 s28, s69, s35
	v_lshl_add_u64 v[216:217], v[216:217], 0, s[8:9]
	s_mov_b32 m0, s28
	ds_read_b128 v[182:185], v149 offset:49152
	ds_read_b128 v[186:189], v149 offset:50176
	ds_read_b128 v[192:195], v149 offset:51200
	ds_read_b128 v[196:199], v149 offset:52224
	ds_read_b128 v[200:203], v149 offset:53248
	ds_read_b128 v[204:207], v149 offset:54272
	ds_read_b128 v[208:211], v149 offset:55296
	ds_read_b128 v[212:215], v149 offset:56320
	global_load_lds_dwordx4 v[216:217], off
	s_add_i32 m0, s28, 0x2000
	s_add_u32 s26, s26, 0x80080
	v_lshl_add_u64 v[216:217], v[218:219], 0, s[8:9]
	s_addc_u32 s27, s27, 0
	s_add_i32 s28, s71, s35
	global_load_lds_dwordx4 v[216:217], off
	v_lshl_add_u64 v[216:217], s[26:27], 0, v[130:131]
	s_mov_b32 m0, s28
	s_nop 0
	global_load_lds_dwordx4 v[216:217], off
	v_lshl_add_u64 v[216:217], s[26:27], 0, v[134:135]
	s_add_i32 m0, s28, 0x2000
	s_nop 0
	global_load_lds_dwordx4 v[216:217], off
	v_lshl_add_u64 v[216:217], v[220:221], 0, s[8:9]
	s_mov_b32 m0, s40
	s_nop 0
	global_load_lds_dwordx4 v[216:217], off
	v_lshl_add_u64 v[216:217], v[222:223], 0, s[8:9]
	s_mov_b32 m0, s41
	s_nop 0
	global_load_lds_dwordx4 v[216:217], off
	s_waitcnt vmcnt(8)
	s_waitcnt lgkmcnt(0)
	s_setprio 1
	s_barrier
	v_mfma_f32_16x16x32_bf16 v[60:63], v[150:153], v[182:185], v[60:63]
	v_mfma_f32_16x16x32_bf16 v[56:59], v[158:161], v[182:185], v[56:59]
	v_mfma_f32_16x16x32_bf16 v[52:55], v[150:153], v[192:195], v[52:55]
	v_mfma_f32_16x16x32_bf16 v[48:51], v[158:161], v[192:195], v[48:51]
	v_mfma_f32_16x16x32_bf16 v[36:39], v[150:153], v[200:203], v[36:39]
	v_mfma_f32_16x16x32_bf16 v[32:35], v[158:161], v[200:203], v[32:35]
	v_mfma_f32_16x16x32_bf16 v[20:23], v[150:153], v[208:211], v[20:23]
	v_mfma_f32_16x16x32_bf16 v[16:19], v[158:161], v[208:211], v[16:19]
	v_mfma_f32_16x16x32_bf16 v[60:63], v[154:157], v[186:189], v[60:63]
	v_mfma_f32_16x16x32_bf16 v[56:59], v[162:165], v[186:189], v[56:59]
	v_mfma_f32_16x16x32_bf16 v[52:55], v[154:157], v[196:199], v[52:55]
	v_mfma_f32_16x16x32_bf16 v[48:51], v[162:165], v[196:199], v[48:51]
	v_mfma_f32_16x16x32_bf16 v[36:39], v[154:157], v[204:207], v[36:39]
	v_mfma_f32_16x16x32_bf16 v[32:35], v[162:165], v[204:207], v[32:35]
	v_mfma_f32_16x16x32_bf16 v[20:23], v[154:157], v[212:215], v[20:23]
	v_mfma_f32_16x16x32_bf16 v[16:19], v[162:165], v[212:215], v[16:19]
	s_setprio 0
	s_setprio 1
	v_mfma_f32_16x16x32_bf16 v[44:47], v[166:169], v[182:185], v[44:47]
	v_mfma_f32_16x16x32_bf16 v[40:43], v[174:177], v[182:185], v[40:43]
	v_mfma_f32_16x16x32_bf16 v[28:31], v[166:169], v[192:195], v[28:31]
	v_mfma_f32_16x16x32_bf16 v[24:27], v[174:177], v[192:195], v[24:27]
	v_mfma_f32_16x16x32_bf16 v[12:15], v[166:169], v[200:203], v[12:15]
	v_mfma_f32_16x16x32_bf16 v[8:11], v[174:177], v[200:203], v[8:11]
	v_mfma_f32_16x16x32_bf16 v[4:7], v[166:169], v[208:211], v[4:7]
	v_mfma_f32_16x16x32_bf16 v[0:3], v[174:177], v[208:211], v[0:3]
	v_mfma_f32_16x16x32_bf16 v[44:47], v[170:173], v[186:189], v[44:47]
	v_mfma_f32_16x16x32_bf16 v[40:43], v[178:181], v[186:189], v[40:43]
	v_mfma_f32_16x16x32_bf16 v[28:31], v[170:173], v[196:199], v[28:31]
	v_mfma_f32_16x16x32_bf16 v[24:27], v[178:181], v[196:199], v[24:27]
	v_mfma_f32_16x16x32_bf16 v[12:15], v[170:173], v[204:207], v[12:15]
	v_mfma_f32_16x16x32_bf16 v[8:11], v[178:181], v[204:207], v[8:11]
	v_mfma_f32_16x16x32_bf16 v[4:7], v[170:173], v[212:215], v[4:7]
	v_mfma_f32_16x16x32_bf16 v[0:3], v[178:181], v[212:215], v[0:3]
	s_barrier
	s_setprio 0
	s_add_i32 s65, s65, 2
	s_add_u32 s24, s24, 0x100
	s_addc_u32 s25, s25, 0
	s_add_u32 s49, s49, 0x100
	s_addc_u32 s64, s64, 0
	s_cmp_gt_u32 s65, 29
	s_cbranch_scc0 .LBB0_103
	s_and_b64 vcc, exec, s[12:13]
	s_cbranch_vccz .LBB0_106
	s_barrier

.LBB0_127:
	ds_read_b128 v[150:153], v147
	ds_read_b128 v[154:157], v147 offset:1024
	ds_read_b128 v[158:161], v147 offset:2048
	ds_read_b128 v[162:165], v147 offset:3072
	ds_read_b128 v[166:169], v148
	ds_read_b128 v[170:173], v148 offset:1024
	ds_read_b128 v[174:177], v148 offset:2048
	ds_read_b128 v[178:181], v148 offset:3072
	s_add_u32 s24, s22, 0xfff80080
	s_addc_u32 s25, s23, -1
	s_cmp_eq_u32 s64, 28
	s_cselect_b32 s27, s17, s25
	s_cselect_b32 s26, s46, s24
	s_cselect_b32 s25, s15, s49
	s_cselect_b32 s24, s47, s48
	v_lshl_add_u64 v[216:217], s[22:23], 0, v[136:137]
	s_add_i32 m0, s13, 0xc000
	ds_read_b128 v[182:185], v149
	ds_read_b128 v[186:189], v149 offset:1024
	ds_read_b128 v[192:195], v149 offset:2048
	ds_read_b128 v[196:199], v149 offset:3072
	ds_read_b128 v[200:203], v149 offset:4096
	ds_read_b128 v[204:207], v149 offset:5120
	ds_read_b128 v[208:211], v149 offset:6144
	ds_read_b128 v[212:215], v149 offset:7168
	global_load_lds_dwordx4 v[216:217], off
	v_lshl_add_u64 v[216:217], s[22:23], 0, v[138:139]
	s_add_i32 m0, s13, 0xe000
	s_nop 0
	global_load_lds_dwordx4 v[216:217], off
	s_waitcnt vmcnt(8)
	s_waitcnt lgkmcnt(0)
	s_setprio 1
	s_barrier
	v_mfma_f32_16x16x32_bf16 v[124:127], v[150:153], v[182:185], v[124:127]
	v_mfma_f32_16x16x32_bf16 v[120:123], v[158:161], v[182:185], v[120:123]
	v_mfma_f32_16x16x32_bf16 v[116:119], v[150:153], v[192:195], v[116:119]
	v_mfma_f32_16x16x32_bf16 v[112:115], v[158:161], v[192:195], v[112:115]
	v_mfma_f32_16x16x32_bf16 v[100:103], v[150:153], v[200:203], v[100:103]
	v_mfma_f32_16x16x32_bf16 v[96:99], v[158:161], v[200:203], v[96:99]
	v_mfma_f32_16x16x32_bf16 v[84:87], v[150:153], v[208:211], v[84:87]
	v_mfma_f32_16x16x32_bf16 v[80:83], v[158:161], v[208:211], v[80:83]
	v_mfma_f32_16x16x32_bf16 v[124:127], v[154:157], v[186:189], v[124:127]
	v_mfma_f32_16x16x32_bf16 v[120:123], v[162:165], v[186:189], v[120:123]
	v_mfma_f32_16x16x32_bf16 v[116:119], v[154:157], v[196:199], v[116:119]
	v_mfma_f32_16x16x32_bf16 v[112:115], v[162:165], v[196:199], v[112:115]
	v_mfma_f32_16x16x32_bf16 v[100:103], v[154:157], v[204:207], v[100:103]
	v_mfma_f32_16x16x32_bf16 v[96:99], v[162:165], v[204:207], v[96:99]
	v_mfma_f32_16x16x32_bf16 v[84:87], v[154:157], v[212:215], v[84:87]
	v_mfma_f32_16x16x32_bf16 v[80:83], v[162:165], v[212:215], v[80:83]
	s_setprio 0
	s_setprio 1
	v_mfma_f32_16x16x32_bf16 v[108:111], v[166:169], v[182:185], v[108:111]
	v_mfma_f32_16x16x32_bf16 v[104:107], v[174:177], v[182:185], v[104:107]
	v_mfma_f32_16x16x32_bf16 v[92:95], v[166:169], v[192:195], v[92:95]
	v_mfma_f32_16x16x32_bf16 v[88:91], v[174:177], v[192:195], v[88:91]
	v_mfma_f32_16x16x32_bf16 v[76:79], v[166:169], v[200:203], v[76:79]
	v_mfma_f32_16x16x32_bf16 v[72:75], v[174:177], v[200:203], v[72:75]
	v_mfma_f32_16x16x32_bf16 v[68:71], v[166:169], v[208:211], v[68:71]
	v_mfma_f32_16x16x32_bf16 v[64:67], v[174:177], v[208:211], v[64:67]
	v_mfma_f32_16x16x32_bf16 v[108:111], v[170:173], v[186:189], v[108:111]
	v_mfma_f32_16x16x32_bf16 v[104:107], v[178:181], v[186:189], v[104:107]
	v_mfma_f32_16x16x32_bf16 v[92:95], v[170:173], v[196:199], v[92:95]
	v_mfma_f32_16x16x32_bf16 v[88:91], v[178:181], v[196:199], v[88:91]
	v_mfma_f32_16x16x32_bf16 v[76:79], v[170:173], v[204:207], v[76:79]
	v_mfma_f32_16x16x32_bf16 v[72:75], v[178:181], v[204:207], v[72:75]
	v_mfma_f32_16x16x32_bf16 v[68:71], v[170:173], v[212:215], v[68:71]
	v_mfma_f32_16x16x32_bf16 v[64:67], v[178:181], v[212:215], v[64:67]
	s_barrier
	s_setprio 0
	s_add_i32 s65, s43, s34
	v_lshl_add_u64 v[216:217], s[24:25], 0, v[130:131]
	s_mov_b32 m0, s65
	ds_read_b128 v[182:185], v149 offset:16384
	ds_read_b128 v[186:189], v149 offset:17408
	ds_read_b128 v[192:195], v149 offset:18432
	ds_read_b128 v[196:199], v149 offset:19456
	ds_read_b128 v[200:203], v149 offset:20480
	ds_read_b128 v[204:207], v149 offset:21504
	ds_read_b128 v[208:211], v149 offset:22528
	ds_read_b128 v[212:215], v149 offset:23552
	global_load_lds_dwordx4 v[216:217], off
	s_add_i32 m0, s65, 0x2000
	s_add_u32 s72, s24, 0x80000
	v_lshl_add_u64 v[218:219], s[24:25], 0, v[134:135]
	s_addc_u32 s73, s25, 0
	s_add_i32 s65, s44, s34
	global_load_lds_dwordx4 v[218:219], off
	v_lshl_add_u64 v[220:221], s[72:73], 0, v[130:131]
	s_mov_b32 m0, s65
	v_lshl_add_u64 v[222:223], s[26:27], 0, v[132:133]
	global_load_lds_dwordx4 v[220:221], off
	v_lshl_add_u64 v[220:221], s[72:73], 0, v[134:135]
	s_add_i32 m0, s65, 0x2000
	s_nop 0
	global_load_lds_dwordx4 v[220:221], off
	v_lshl_add_u64 v[220:221], s[26:27], 0, v[128:129]
	s_mov_b32 m0, s13
	s_nop 0
	global_load_lds_dwordx4 v[220:221], off
	s_mov_b32 m0, s35
	s_nop 0
	global_load_lds_dwordx4 v[222:223], off
	s_waitcnt vmcnt(8)
	s_waitcnt lgkmcnt(0)
	s_setprio 1
	s_barrier
	v_mfma_f32_16x16x32_bf16 v[60:63], v[150:153], v[182:185], v[60:63]
	v_mfma_f32_16x16x32_bf16 v[56:59], v[158:161], v[182:185], v[56:59]
	v_mfma_f32_16x16x32_bf16 v[52:55], v[150:153], v[192:195], v[52:55]
	v_mfma_f32_16x16x32_bf16 v[48:51], v[158:161], v[192:195], v[48:51]
	v_mfma_f32_16x16x32_bf16 v[36:39], v[150:153], v[200:203], v[36:39]
	v_mfma_f32_16x16x32_bf16 v[32:35], v[158:161], v[200:203], v[32:35]
	v_mfma_f32_16x16x32_bf16 v[20:23], v[150:153], v[208:211], v[20:23]
	v_mfma_f32_16x16x32_bf16 v[16:19], v[158:161], v[208:211], v[16:19]
	v_mfma_f32_16x16x32_bf16 v[60:63], v[154:157], v[186:189], v[60:63]
	v_mfma_f32_16x16x32_bf16 v[56:59], v[162:165], v[186:189], v[56:59]
	v_mfma_f32_16x16x32_bf16 v[52:55], v[154:157], v[196:199], v[52:55]
	v_mfma_f32_16x16x32_bf16 v[48:51], v[162:165], v[196:199], v[48:51]
	v_mfma_f32_16x16x32_bf16 v[36:39], v[154:157], v[204:207], v[36:39]
	v_mfma_f32_16x16x32_bf16 v[32:35], v[162:165], v[204:207], v[32:35]
	v_mfma_f32_16x16x32_bf16 v[20:23], v[154:157], v[212:215], v[20:23]
	v_mfma_f32_16x16x32_bf16 v[16:19], v[162:165], v[212:215], v[16:19]
	s_setprio 0
	s_setprio 1
	v_mfma_f32_16x16x32_bf16 v[44:47], v[166:169], v[182:185], v[44:47]
	v_mfma_f32_16x16x32_bf16 v[40:43], v[174:177], v[182:185], v[40:43]
	v_mfma_f32_16x16x32_bf16 v[28:31], v[166:169], v[192:195], v[28:31]
	v_mfma_f32_16x16x32_bf16 v[24:27], v[174:177], v[192:195], v[24:27]
	v_mfma_f32_16x16x32_bf16 v[12:15], v[166:169], v[200:203], v[12:15]
	v_mfma_f32_16x16x32_bf16 v[8:11], v[174:177], v[200:203], v[8:11]
	v_mfma_f32_16x16x32_bf16 v[4:7], v[166:169], v[208:211], v[4:7]
	v_mfma_f32_16x16x32_bf16 v[0:3], v[174:177], v[208:211], v[0:3]
	v_mfma_f32_16x16x32_bf16 v[44:47], v[170:173], v[186:189], v[44:47]
	v_mfma_f32_16x16x32_bf16 v[40:43], v[178:181], v[186:189], v[40:43]
	v_mfma_f32_16x16x32_bf16 v[28:31], v[170:173], v[196:199], v[28:31]
	v_mfma_f32_16x16x32_bf16 v[24:27], v[178:181], v[196:199], v[24:27]
	v_mfma_f32_16x16x32_bf16 v[12:15], v[170:173], v[204:207], v[12:15]
	v_mfma_f32_16x16x32_bf16 v[8:11], v[178:181], v[204:207], v[8:11]
	v_mfma_f32_16x16x32_bf16 v[4:7], v[170:173], v[212:215], v[4:7]
	v_mfma_f32_16x16x32_bf16 v[0:3], v[178:181], v[212:215], v[0:3]
	s_barrier
	s_setprio 0
	s_add_i32 s65, 0, 0x18000
	s_add_i32 s69, 0, 0x1c000
	v_add_u32_e32 v162, s65, v145
	v_add_u32_e32 v178, s69, v145
	ds_read_b128 v[150:153], v162
	ds_read_b128 v[154:157], v162 offset:1024
	ds_read_b128 v[158:161], v162 offset:2048
	ds_read_b128 v[162:165], v162 offset:3072
	ds_read_b128 v[166:169], v178
	ds_read_b128 v[170:173], v178 offset:1024
	ds_read_b128 v[174:177], v178 offset:2048
	ds_read_b128 v[178:181], v178 offset:3072
	s_add_u32 s26, s26, 0x80000
	s_addc_u32 s27, s27, 0
	s_mov_b32 m0, s36
	v_lshl_add_u64 v[224:225], s[26:27], 0, v[128:129]
	ds_read_b128 v[182:185], v149 offset:32768
	ds_read_b128 v[186:189], v149 offset:33792
	ds_read_b128 v[192:195], v149 offset:34816
	ds_read_b128 v[196:199], v149 offset:35840
	ds_read_b128 v[200:203], v149 offset:36864
	ds_read_b128 v[204:207], v149 offset:37888
	ds_read_b128 v[208:211], v149 offset:38912
	ds_read_b128 v[212:215], v149 offset:39936
	global_load_lds_dwordx4 v[224:225], off
	v_lshl_add_u64 v[224:225], s[26:27], 0, v[132:133]
	s_mov_b32 m0, s37
	s_nop 0
	global_load_lds_dwordx4 v[224:225], off
	s_waitcnt vmcnt(8)
	s_waitcnt lgkmcnt(0)
	s_setprio 1
	s_barrier
	v_mfma_f32_16x16x32_bf16 v[124:127], v[150:153], v[182:185], v[124:127]
	v_mfma_f32_16x16x32_bf16 v[120:123], v[158:161], v[182:185], v[120:123]
	v_mfma_f32_16x16x32_bf16 v[116:119], v[150:153], v[192:195], v[116:119]
	v_mfma_f32_16x16x32_bf16 v[112:115], v[158:161], v[192:195], v[112:115]
	v_mfma_f32_16x16x32_bf16 v[100:103], v[150:153], v[200:203], v[100:103]
	v_mfma_f32_16x16x32_bf16 v[96:99], v[158:161], v[200:203], v[96:99]
	v_mfma_f32_16x16x32_bf16 v[84:87], v[150:153], v[208:211], v[84:87]
	v_mfma_f32_16x16x32_bf16 v[80:83], v[158:161], v[208:211], v[80:83]
	v_mfma_f32_16x16x32_bf16 v[124:127], v[154:157], v[186:189], v[124:127]
	v_mfma_f32_16x16x32_bf16 v[120:123], v[162:165], v[186:189], v[120:123]
	v_mfma_f32_16x16x32_bf16 v[116:119], v[154:157], v[196:199], v[116:119]
	v_mfma_f32_16x16x32_bf16 v[112:115], v[162:165], v[196:199], v[112:115]
	v_mfma_f32_16x16x32_bf16 v[100:103], v[154:157], v[204:207], v[100:103]
	v_mfma_f32_16x16x32_bf16 v[96:99], v[162:165], v[204:207], v[96:99]
	v_mfma_f32_16x16x32_bf16 v[84:87], v[154:157], v[212:215], v[84:87]
	v_mfma_f32_16x16x32_bf16 v[80:83], v[162:165], v[212:215], v[80:83]
	s_setprio 0
	s_setprio 1
	v_mfma_f32_16x16x32_bf16 v[108:111], v[166:169], v[182:185], v[108:111]
	v_mfma_f32_16x16x32_bf16 v[104:107], v[174:177], v[182:185], v[104:107]
	v_mfma_f32_16x16x32_bf16 v[92:95], v[166:169], v[192:195], v[92:95]
	v_mfma_f32_16x16x32_bf16 v[88:91], v[174:177], v[192:195], v[88:91]
	v_mfma_f32_16x16x32_bf16 v[76:79], v[166:169], v[200:203], v[76:79]
	v_mfma_f32_16x16x32_bf16 v[72:75], v[174:177], v[200:203], v[72:75]
	v_mfma_f32_16x16x32_bf16 v[68:71], v[166:169], v[208:211], v[68:71]
	v_mfma_f32_16x16x32_bf16 v[64:67], v[174:177], v[208:211], v[64:67]
	v_mfma_f32_16x16x32_bf16 v[108:111], v[170:173], v[186:189], v[108:111]
	v_mfma_f32_16x16x32_bf16 v[104:107], v[178:181], v[186:189], v[104:107]
	v_mfma_f32_16x16x32_bf16 v[92:95], v[170:173], v[196:199], v[92:95]
	v_mfma_f32_16x16x32_bf16 v[88:91], v[178:181], v[196:199], v[88:91]
	v_mfma_f32_16x16x32_bf16 v[76:79], v[170:173], v[204:207], v[76:79]
	v_mfma_f32_16x16x32_bf16 v[72:75], v[178:181], v[204:207], v[72:75]
	v_mfma_f32_16x16x32_bf16 v[68:71], v[170:173], v[212:215], v[68:71]
	v_mfma_f32_16x16x32_bf16 v[64:67], v[178:181], v[212:215], v[64:67]
	s_barrier
	s_setprio 0
	s_add_i32 s26, s65, s34
	v_lshl_add_u64 v[216:217], v[216:217], 0, s[8:9]
	s_mov_b32 m0, s26
	ds_read_b128 v[182:185], v149 offset:49152
	ds_read_b128 v[186:189], v149 offset:50176
	ds_read_b128 v[192:195], v149 offset:51200
	ds_read_b128 v[196:199], v149 offset:52224
	ds_read_b128 v[200:203], v149 offset:53248
	ds_read_b128 v[204:207], v149 offset:54272
	ds_read_b128 v[208:211], v149 offset:55296
	ds_read_b128 v[212:215], v149 offset:56320
	global_load_lds_dwordx4 v[216:217], off
	s_add_i32 m0, s26, 0x2000
	s_add_u32 s24, s24, 0x80080
	v_lshl_add_u64 v[216:217], v[218:219], 0, s[8:9]
	s_addc_u32 s25, s25, 0
	s_add_i32 s26, s69, s34
	global_load_lds_dwordx4 v[216:217], off
	v_lshl_add_u64 v[216:217], s[24:25], 0, v[130:131]
	s_mov_b32 m0, s26
	s_nop 0
	global_load_lds_dwordx4 v[216:217], off
	v_lshl_add_u64 v[216:217], s[24:25], 0, v[134:135]
	s_add_i32 m0, s26, 0x2000
	s_nop 0
	global_load_lds_dwordx4 v[216:217], off
	v_lshl_add_u64 v[216:217], v[220:221], 0, s[8:9]
	s_mov_b32 m0, s39
	s_nop 0
	global_load_lds_dwordx4 v[216:217], off
	v_lshl_add_u64 v[216:217], v[222:223], 0, s[8:9]
	s_mov_b32 m0, s40
	s_nop 0
	global_load_lds_dwordx4 v[216:217], off
	s_waitcnt vmcnt(8)
	s_waitcnt lgkmcnt(0)
	s_setprio 1
	s_barrier
	v_mfma_f32_16x16x32_bf16 v[60:63], v[150:153], v[182:185], v[60:63]
	v_mfma_f32_16x16x32_bf16 v[56:59], v[158:161], v[182:185], v[56:59]
	v_mfma_f32_16x16x32_bf16 v[52:55], v[150:153], v[192:195], v[52:55]
	v_mfma_f32_16x16x32_bf16 v[48:51], v[158:161], v[192:195], v[48:51]
	v_mfma_f32_16x16x32_bf16 v[36:39], v[150:153], v[200:203], v[36:39]
	v_mfma_f32_16x16x32_bf16 v[32:35], v[158:161], v[200:203], v[32:35]
	v_mfma_f32_16x16x32_bf16 v[20:23], v[150:153], v[208:211], v[20:23]
	v_mfma_f32_16x16x32_bf16 v[16:19], v[158:161], v[208:211], v[16:19]
	v_mfma_f32_16x16x32_bf16 v[60:63], v[154:157], v[186:189], v[60:63]
	v_mfma_f32_16x16x32_bf16 v[56:59], v[162:165], v[186:189], v[56:59]
	v_mfma_f32_16x16x32_bf16 v[52:55], v[154:157], v[196:199], v[52:55]
	v_mfma_f32_16x16x32_bf16 v[48:51], v[162:165], v[196:199], v[48:51]
	v_mfma_f32_16x16x32_bf16 v[36:39], v[154:157], v[204:207], v[36:39]
	v_mfma_f32_16x16x32_bf16 v[32:35], v[162:165], v[204:207], v[32:35]
	v_mfma_f32_16x16x32_bf16 v[20:23], v[154:157], v[212:215], v[20:23]
	v_mfma_f32_16x16x32_bf16 v[16:19], v[162:165], v[212:215], v[16:19]
	s_setprio 0
	s_setprio 1
	v_mfma_f32_16x16x32_bf16 v[44:47], v[166:169], v[182:185], v[44:47]
	v_mfma_f32_16x16x32_bf16 v[40:43], v[174:177], v[182:185], v[40:43]
	v_mfma_f32_16x16x32_bf16 v[28:31], v[166:169], v[192:195], v[28:31]
	v_mfma_f32_16x16x32_bf16 v[24:27], v[174:177], v[192:195], v[24:27]
	v_mfma_f32_16x16x32_bf16 v[12:15], v[166:169], v[200:203], v[12:15]
	v_mfma_f32_16x16x32_bf16 v[8:11], v[174:177], v[200:203], v[8:11]
	v_mfma_f32_16x16x32_bf16 v[4:7], v[166:169], v[208:211], v[4:7]
	v_mfma_f32_16x16x32_bf16 v[0:3], v[174:177], v[208:211], v[0:3]
	v_mfma_f32_16x16x32_bf16 v[44:47], v[170:173], v[186:189], v[44:47]
	v_mfma_f32_16x16x32_bf16 v[40:43], v[178:181], v[186:189], v[40:43]
	v_mfma_f32_16x16x32_bf16 v[28:31], v[170:173], v[196:199], v[28:31]
	v_mfma_f32_16x16x32_bf16 v[24:27], v[178:181], v[196:199], v[24:27]
	v_mfma_f32_16x16x32_bf16 v[12:15], v[170:173], v[204:207], v[12:15]
	v_mfma_f32_16x16x32_bf16 v[8:11], v[178:181], v[204:207], v[8:11]
	v_mfma_f32_16x16x32_bf16 v[4:7], v[170:173], v[212:215], v[4:7]
	v_mfma_f32_16x16x32_bf16 v[0:3], v[178:181], v[212:215], v[0:3]
	s_barrier
	s_setprio 0
	s_add_i32 s64, s64, 2
	s_add_u32 s22, s22, 0x100
	s_addc_u32 s23, s23, 0
	s_add_u32 s48, s48, 0x100
	s_addc_u32 s49, s49, 0
	s_cmp_gt_u32 s64, 29
	s_cbranch_scc0 .LBB0_127
	s_and_b64 vcc, exec, s[10:11]
	s_cbranch_vccz .LBB0_130
	s_barrier

.LBB0_143:
	ds_read_b128 v[144:147], v153
	ds_read_b128 v[158:161], v153 offset:1024
	ds_read_b128 v[162:165], v153 offset:2048
	ds_read_b128 v[166:169], v153 offset:3072
	ds_read_b128 v[170:173], v154
	ds_read_b128 v[174:177], v154 offset:1024
	ds_read_b128 v[178:181], v154 offset:2048
	ds_read_b128 v[182:185], v154 offset:3072
	s_add_u32 s24, s22, 0xfff80080
	s_addc_u32 s25, s23, -1
	s_cmp_eq_u32 s64, 28
	s_cselect_b32 s27, s15, s25
	s_cselect_b32 s26, s46, s24
	s_cselect_b32 s25, s13, s49
	s_cselect_b32 s24, s47, s48
	v_lshl_add_u64 v[148:149], s[22:23], 0, v[136:137]
	s_add_i32 m0, s31, 0xc000
	ds_read_b128 v[186:189], v155
	ds_read_b128 v[192:195], v155 offset:1024
	ds_read_b128 v[196:199], v155 offset:2048
	ds_read_b128 v[200:203], v155 offset:3072
	ds_read_b128 v[204:207], v155 offset:4096
	ds_read_b128 v[208:211], v155 offset:5120
	ds_read_b128 v[212:215], v155 offset:6144
	ds_read_b128 v[216:219], v155 offset:7168
	global_load_lds_dwordx4 v[148:149], off
	v_lshl_add_u64 v[148:149], s[22:23], 0, v[138:139]
	s_add_i32 m0, s31, 0xe000
	s_nop 0
	global_load_lds_dwordx4 v[148:149], off
	s_waitcnt vmcnt(8)
	s_waitcnt lgkmcnt(0)
	s_setprio 1
	s_barrier
	v_mfma_f32_16x16x32_bf16 v[124:127], v[144:147], v[186:189], v[124:127]
	v_mfma_f32_16x16x32_bf16 v[120:123], v[162:165], v[186:189], v[120:123]
	v_mfma_f32_16x16x32_bf16 v[108:111], v[144:147], v[196:199], v[108:111]
	v_mfma_f32_16x16x32_bf16 v[104:107], v[162:165], v[196:199], v[104:107]
	v_mfma_f32_16x16x32_bf16 v[92:95], v[144:147], v[204:207], v[92:95]
	v_mfma_f32_16x16x32_bf16 v[88:91], v[162:165], v[204:207], v[88:91]
	v_mfma_f32_16x16x32_bf16 v[76:79], v[144:147], v[212:215], v[76:79]
	v_mfma_f32_16x16x32_bf16 v[72:75], v[162:165], v[212:215], v[72:75]
	v_mfma_f32_16x16x32_bf16 v[124:127], v[158:161], v[192:195], v[124:127]
	v_mfma_f32_16x16x32_bf16 v[120:123], v[166:169], v[192:195], v[120:123]
	v_mfma_f32_16x16x32_bf16 v[108:111], v[158:161], v[200:203], v[108:111]
	v_mfma_f32_16x16x32_bf16 v[104:107], v[166:169], v[200:203], v[104:107]
	v_mfma_f32_16x16x32_bf16 v[92:95], v[158:161], v[208:211], v[92:95]
	v_mfma_f32_16x16x32_bf16 v[88:91], v[166:169], v[208:211], v[88:91]
	v_mfma_f32_16x16x32_bf16 v[76:79], v[158:161], v[216:219], v[76:79]
	v_mfma_f32_16x16x32_bf16 v[72:75], v[166:169], v[216:219], v[72:75]
	s_setprio 0
	s_setprio 1
	v_mfma_f32_16x16x32_bf16 v[116:119], v[170:173], v[186:189], v[116:119]
	v_mfma_f32_16x16x32_bf16 v[112:115], v[178:181], v[186:189], v[112:115]
	v_mfma_f32_16x16x32_bf16 v[100:103], v[170:173], v[196:199], v[100:103]
	v_mfma_f32_16x16x32_bf16 v[96:99], v[178:181], v[196:199], v[96:99]
	v_mfma_f32_16x16x32_bf16 v[84:87], v[170:173], v[204:207], v[84:87]
	v_mfma_f32_16x16x32_bf16 v[80:83], v[178:181], v[204:207], v[80:83]
	v_mfma_f32_16x16x32_bf16 v[68:71], v[170:173], v[212:215], v[68:71]
	v_mfma_f32_16x16x32_bf16 v[64:67], v[178:181], v[212:215], v[64:67]
	v_mfma_f32_16x16x32_bf16 v[116:119], v[174:177], v[192:195], v[116:119]
	v_mfma_f32_16x16x32_bf16 v[112:115], v[182:185], v[192:195], v[112:115]
	v_mfma_f32_16x16x32_bf16 v[100:103], v[174:177], v[200:203], v[100:103]
	v_mfma_f32_16x16x32_bf16 v[96:99], v[182:185], v[200:203], v[96:99]
	v_mfma_f32_16x16x32_bf16 v[84:87], v[174:177], v[208:211], v[84:87]
	v_mfma_f32_16x16x32_bf16 v[80:83], v[182:185], v[208:211], v[80:83]
	v_mfma_f32_16x16x32_bf16 v[68:71], v[174:177], v[216:219], v[68:71]
	v_mfma_f32_16x16x32_bf16 v[64:67], v[182:185], v[216:219], v[64:67]
	s_barrier
	s_setprio 0
	s_add_i32 s65, s42, s28
	v_lshl_add_u64 v[148:149], s[24:25], 0, v[132:133]
	s_mov_b32 m0, s65
	ds_read_b128 v[186:189], v155 offset:16384
	ds_read_b128 v[192:195], v155 offset:17408
	ds_read_b128 v[196:199], v155 offset:18432
	ds_read_b128 v[200:203], v155 offset:19456
	ds_read_b128 v[204:207], v155 offset:20480
	ds_read_b128 v[208:211], v155 offset:21504
	ds_read_b128 v[212:215], v155 offset:22528
	ds_read_b128 v[216:219], v155 offset:23552
	global_load_lds_dwordx4 v[148:149], off
	s_add_i32 m0, s65, 0x2000
	s_add_u32 s80, s24, 0x80000
	v_lshl_add_u64 v[220:221], s[24:25], 0, v[128:129]
	s_addc_u32 s81, s25, 0
	s_add_i32 s65, s43, s28
	global_load_lds_dwordx4 v[220:221], off
	v_lshl_add_u64 v[222:223], s[80:81], 0, v[132:133]
	s_mov_b32 m0, s65
	v_lshl_add_u64 v[224:225], s[26:27], 0, v[130:131]
	global_load_lds_dwordx4 v[222:223], off
	v_lshl_add_u64 v[222:223], s[80:81], 0, v[128:129]
	s_add_i32 m0, s65, 0x2000
	s_nop 0
	global_load_lds_dwordx4 v[222:223], off
	v_lshl_add_u64 v[222:223], s[26:27], 0, v[134:135]
	s_mov_b32 m0, s31
	s_nop 0
	global_load_lds_dwordx4 v[222:223], off
	s_mov_b32 m0, s34
	s_nop 0
	global_load_lds_dwordx4 v[224:225], off
	s_waitcnt vmcnt(8)
	s_waitcnt lgkmcnt(0)
	s_setprio 1
	s_barrier
	v_mfma_f32_16x16x32_bf16 v[60:63], v[144:147], v[186:189], v[60:63]
	v_mfma_f32_16x16x32_bf16 v[56:59], v[162:165], v[186:189], v[56:59]
	v_mfma_f32_16x16x32_bf16 v[44:47], v[144:147], v[196:199], v[44:47]
	v_mfma_f32_16x16x32_bf16 v[40:43], v[162:165], v[196:199], v[40:43]
	v_mfma_f32_16x16x32_bf16 v[28:31], v[144:147], v[204:207], v[28:31]
	v_mfma_f32_16x16x32_bf16 v[24:27], v[162:165], v[204:207], v[24:27]
	v_mfma_f32_16x16x32_bf16 v[12:15], v[144:147], v[212:215], v[12:15]
	v_mfma_f32_16x16x32_bf16 v[8:11], v[162:165], v[212:215], v[8:11]
	v_mfma_f32_16x16x32_bf16 v[60:63], v[158:161], v[192:195], v[60:63]
	v_mfma_f32_16x16x32_bf16 v[56:59], v[166:169], v[192:195], v[56:59]
	v_mfma_f32_16x16x32_bf16 v[44:47], v[158:161], v[200:203], v[44:47]
	v_mfma_f32_16x16x32_bf16 v[40:43], v[166:169], v[200:203], v[40:43]
	v_mfma_f32_16x16x32_bf16 v[28:31], v[158:161], v[208:211], v[28:31]
	v_mfma_f32_16x16x32_bf16 v[24:27], v[166:169], v[208:211], v[24:27]
	v_mfma_f32_16x16x32_bf16 v[12:15], v[158:161], v[216:219], v[12:15]
	v_mfma_f32_16x16x32_bf16 v[8:11], v[166:169], v[216:219], v[8:11]
	s_setprio 0
	s_setprio 1
	v_mfma_f32_16x16x32_bf16 v[52:55], v[170:173], v[186:189], v[52:55]
	v_mfma_f32_16x16x32_bf16 v[48:51], v[178:181], v[186:189], v[48:51]
	v_mfma_f32_16x16x32_bf16 v[36:39], v[170:173], v[196:199], v[36:39]
	v_mfma_f32_16x16x32_bf16 v[32:35], v[178:181], v[196:199], v[32:35]
	v_mfma_f32_16x16x32_bf16 v[20:23], v[170:173], v[204:207], v[20:23]
	v_mfma_f32_16x16x32_bf16 v[16:19], v[178:181], v[204:207], v[16:19]
	v_mfma_f32_16x16x32_bf16 v[4:7], v[170:173], v[212:215], v[4:7]
	v_mfma_f32_16x16x32_bf16 v[0:3], v[178:181], v[212:215], v[0:3]
	v_mfma_f32_16x16x32_bf16 v[52:55], v[174:177], v[192:195], v[52:55]
	v_mfma_f32_16x16x32_bf16 v[48:51], v[182:185], v[192:195], v[48:51]
	v_mfma_f32_16x16x32_bf16 v[36:39], v[174:177], v[200:203], v[36:39]
	v_mfma_f32_16x16x32_bf16 v[32:35], v[182:185], v[200:203], v[32:35]
	v_mfma_f32_16x16x32_bf16 v[20:23], v[174:177], v[208:211], v[20:23]
	v_mfma_f32_16x16x32_bf16 v[16:19], v[182:185], v[208:211], v[16:19]
	v_mfma_f32_16x16x32_bf16 v[4:7], v[174:177], v[216:219], v[4:7]
	v_mfma_f32_16x16x32_bf16 v[0:3], v[182:185], v[216:219], v[0:3]
	s_barrier
	s_setprio 0
	s_add_i32 s65, 0, 0x18000
	v_add_u32_e32 v157, s65, v151
	s_add_i32 s69, 0, 0x1c000
	ds_read_b128 v[144:147], v157
	ds_read_b128 v[158:161], v157 offset:1024
	ds_read_b128 v[162:165], v157 offset:2048
	ds_read_b128 v[166:169], v157 offset:3072
	v_add_u32_e32 v157, s69, v151
	ds_read_b128 v[170:173], v157
	ds_read_b128 v[174:177], v157 offset:1024
	ds_read_b128 v[178:181], v157 offset:2048
	ds_read_b128 v[182:185], v157 offset:3072
	s_add_u32 s26, s26, 0x80000
	s_addc_u32 s27, s27, 0
	s_mov_b32 m0, s35
	v_lshl_add_u64 v[226:227], s[26:27], 0, v[134:135]
	ds_read_b128 v[186:189], v155 offset:32768
	ds_read_b128 v[192:195], v155 offset:33792
	ds_read_b128 v[196:199], v155 offset:34816
	ds_read_b128 v[200:203], v155 offset:35840
	ds_read_b128 v[204:207], v155 offset:36864
	ds_read_b128 v[208:211], v155 offset:37888
	ds_read_b128 v[212:215], v155 offset:38912
	ds_read_b128 v[216:219], v155 offset:39936
	global_load_lds_dwordx4 v[226:227], off
	v_lshl_add_u64 v[226:227], s[26:27], 0, v[130:131]
	s_mov_b32 m0, s36
	s_nop 0
	global_load_lds_dwordx4 v[226:227], off
	s_waitcnt vmcnt(8)
	s_waitcnt lgkmcnt(0)
	s_setprio 1
	s_barrier
	v_mfma_f32_16x16x32_bf16 v[124:127], v[144:147], v[186:189], v[124:127]
	v_mfma_f32_16x16x32_bf16 v[120:123], v[162:165], v[186:189], v[120:123]
	v_mfma_f32_16x16x32_bf16 v[108:111], v[144:147], v[196:199], v[108:111]
	v_mfma_f32_16x16x32_bf16 v[104:107], v[162:165], v[196:199], v[104:107]
	v_mfma_f32_16x16x32_bf16 v[92:95], v[144:147], v[204:207], v[92:95]
	v_mfma_f32_16x16x32_bf16 v[88:91], v[162:165], v[204:207], v[88:91]
	v_mfma_f32_16x16x32_bf16 v[76:79], v[144:147], v[212:215], v[76:79]
	v_mfma_f32_16x16x32_bf16 v[72:75], v[162:165], v[212:215], v[72:75]
	v_mfma_f32_16x16x32_bf16 v[124:127], v[158:161], v[192:195], v[124:127]
	v_mfma_f32_16x16x32_bf16 v[120:123], v[166:169], v[192:195], v[120:123]
	v_mfma_f32_16x16x32_bf16 v[108:111], v[158:161], v[200:203], v[108:111]
	v_mfma_f32_16x16x32_bf16 v[104:107], v[166:169], v[200:203], v[104:107]
	v_mfma_f32_16x16x32_bf16 v[92:95], v[158:161], v[208:211], v[92:95]
	v_mfma_f32_16x16x32_bf16 v[88:91], v[166:169], v[208:211], v[88:91]
	v_mfma_f32_16x16x32_bf16 v[76:79], v[158:161], v[216:219], v[76:79]
	v_mfma_f32_16x16x32_bf16 v[72:75], v[166:169], v[216:219], v[72:75]
	s_setprio 0
	s_setprio 1
	v_mfma_f32_16x16x32_bf16 v[116:119], v[170:173], v[186:189], v[116:119]
	v_mfma_f32_16x16x32_bf16 v[112:115], v[178:181], v[186:189], v[112:115]
	v_mfma_f32_16x16x32_bf16 v[100:103], v[170:173], v[196:199], v[100:103]
	v_mfma_f32_16x16x32_bf16 v[96:99], v[178:181], v[196:199], v[96:99]
	v_mfma_f32_16x16x32_bf16 v[84:87], v[170:173], v[204:207], v[84:87]
	v_mfma_f32_16x16x32_bf16 v[80:83], v[178:181], v[204:207], v[80:83]
	v_mfma_f32_16x16x32_bf16 v[68:71], v[170:173], v[212:215], v[68:71]
	v_mfma_f32_16x16x32_bf16 v[64:67], v[178:181], v[212:215], v[64:67]
	v_mfma_f32_16x16x32_bf16 v[116:119], v[174:177], v[192:195], v[116:119]
	v_mfma_f32_16x16x32_bf16 v[112:115], v[182:185], v[192:195], v[112:115]
	v_mfma_f32_16x16x32_bf16 v[100:103], v[174:177], v[200:203], v[100:103]
	v_mfma_f32_16x16x32_bf16 v[96:99], v[182:185], v[200:203], v[96:99]
	v_mfma_f32_16x16x32_bf16 v[84:87], v[174:177], v[208:211], v[84:87]
	v_mfma_f32_16x16x32_bf16 v[80:83], v[182:185], v[208:211], v[80:83]
	v_mfma_f32_16x16x32_bf16 v[68:71], v[174:177], v[216:219], v[68:71]
	v_mfma_f32_16x16x32_bf16 v[64:67], v[182:185], v[216:219], v[64:67]
	s_barrier
	s_setprio 0
	s_add_i32 s26, s65, s28
	v_lshl_add_u64 v[148:149], v[148:149], 0, s[8:9]
	s_mov_b32 m0, s26
	ds_read_b128 v[186:189], v155 offset:49152
	ds_read_b128 v[192:195], v155 offset:50176
	ds_read_b128 v[196:199], v155 offset:51200
	ds_read_b128 v[200:203], v155 offset:52224
	ds_read_b128 v[204:207], v155 offset:53248
	ds_read_b128 v[208:211], v155 offset:54272
	ds_read_b128 v[212:215], v155 offset:55296
	ds_read_b128 v[216:219], v155 offset:56320
	global_load_lds_dwordx4 v[148:149], off
	s_add_i32 m0, s26, 0x2000
	s_add_u32 s24, s24, 0x80080
	v_lshl_add_u64 v[148:149], v[220:221], 0, s[8:9]
	s_addc_u32 s25, s25, 0
	s_add_i32 s26, s69, s28
	global_load_lds_dwordx4 v[148:149], off
	v_lshl_add_u64 v[148:149], s[24:25], 0, v[132:133]
	s_mov_b32 m0, s26
	s_nop 0
	global_load_lds_dwordx4 v[148:149], off
	v_lshl_add_u64 v[148:149], s[24:25], 0, v[128:129]
	s_add_i32 m0, s26, 0x2000
	s_nop 0
	global_load_lds_dwordx4 v[148:149], off
	v_lshl_add_u64 v[148:149], v[222:223], 0, s[8:9]
	s_mov_b32 m0, s38
	s_nop 0
	global_load_lds_dwordx4 v[148:149], off
	v_lshl_add_u64 v[148:149], v[224:225], 0, s[8:9]
	s_mov_b32 m0, s39
	s_nop 0
	global_load_lds_dwordx4 v[148:149], off
	s_waitcnt vmcnt(8)
	s_waitcnt lgkmcnt(0)
	s_setprio 1
	s_barrier
	v_mfma_f32_16x16x32_bf16 v[60:63], v[144:147], v[186:189], v[60:63]
	v_mfma_f32_16x16x32_bf16 v[56:59], v[162:165], v[186:189], v[56:59]
	v_mfma_f32_16x16x32_bf16 v[44:47], v[144:147], v[196:199], v[44:47]
	v_mfma_f32_16x16x32_bf16 v[40:43], v[162:165], v[196:199], v[40:43]
	v_mfma_f32_16x16x32_bf16 v[28:31], v[144:147], v[204:207], v[28:31]
	v_mfma_f32_16x16x32_bf16 v[24:27], v[162:165], v[204:207], v[24:27]
	v_mfma_f32_16x16x32_bf16 v[12:15], v[144:147], v[212:215], v[12:15]
	v_mfma_f32_16x16x32_bf16 v[8:11], v[162:165], v[212:215], v[8:11]
	v_mfma_f32_16x16x32_bf16 v[60:63], v[158:161], v[192:195], v[60:63]
	v_mfma_f32_16x16x32_bf16 v[56:59], v[166:169], v[192:195], v[56:59]
	v_mfma_f32_16x16x32_bf16 v[44:47], v[158:161], v[200:203], v[44:47]
	v_mfma_f32_16x16x32_bf16 v[40:43], v[166:169], v[200:203], v[40:43]
	v_mfma_f32_16x16x32_bf16 v[28:31], v[158:161], v[208:211], v[28:31]
	v_mfma_f32_16x16x32_bf16 v[24:27], v[166:169], v[208:211], v[24:27]
	v_mfma_f32_16x16x32_bf16 v[12:15], v[158:161], v[216:219], v[12:15]
	v_mfma_f32_16x16x32_bf16 v[8:11], v[166:169], v[216:219], v[8:11]
	s_setprio 0
	s_setprio 1
	v_mfma_f32_16x16x32_bf16 v[52:55], v[170:173], v[186:189], v[52:55]
	v_mfma_f32_16x16x32_bf16 v[48:51], v[178:181], v[186:189], v[48:51]
	v_mfma_f32_16x16x32_bf16 v[36:39], v[170:173], v[196:199], v[36:39]
	v_mfma_f32_16x16x32_bf16 v[32:35], v[178:181], v[196:199], v[32:35]
	v_mfma_f32_16x16x32_bf16 v[20:23], v[170:173], v[204:207], v[20:23]
	v_mfma_f32_16x16x32_bf16 v[16:19], v[178:181], v[204:207], v[16:19]
	v_mfma_f32_16x16x32_bf16 v[4:7], v[170:173], v[212:215], v[4:7]
	v_mfma_f32_16x16x32_bf16 v[0:3], v[178:181], v[212:215], v[0:3]
	v_mfma_f32_16x16x32_bf16 v[52:55], v[174:177], v[192:195], v[52:55]
	v_mfma_f32_16x16x32_bf16 v[48:51], v[182:185], v[192:195], v[48:51]
	v_mfma_f32_16x16x32_bf16 v[36:39], v[174:177], v[200:203], v[36:39]
	v_mfma_f32_16x16x32_bf16 v[32:35], v[182:185], v[200:203], v[32:35]
	v_mfma_f32_16x16x32_bf16 v[20:23], v[174:177], v[208:211], v[20:23]
	v_mfma_f32_16x16x32_bf16 v[16:19], v[182:185], v[208:211], v[16:19]
	v_mfma_f32_16x16x32_bf16 v[4:7], v[174:177], v[216:219], v[4:7]
	v_mfma_f32_16x16x32_bf16 v[0:3], v[182:185], v[216:219], v[0:3]
	s_barrier
	s_setprio 0
	s_add_i32 s64, s64, 2
	s_add_u32 s22, s22, 0x100
	s_addc_u32 s23, s23, 0
	s_add_u32 s48, s48, 0x100
	s_addc_u32 s49, s49, 0
	s_cmp_gt_u32 s64, 29
	s_cbranch_scc0 .LBB0_143
	s_and_b64 vcc, exec, s[10:11]
	s_cbranch_vccz .LBB0_146
	s_barrier

.LBB0_225:
	ds_read_b128 v[170:173], v165
	ds_read_b128 v[174:177], v165 offset:1024
	ds_read_b128 v[178:181], v165 offset:2048
	ds_read_b128 v[182:185], v165 offset:3072
	ds_read_b128 v[186:189], v166
	ds_read_b128 v[192:195], v166 offset:1024
	ds_read_b128 v[196:199], v166 offset:2048
	ds_read_b128 v[200:203], v166 offset:3072
	s_add_u32 s24, s22, 0x100
	s_addc_u32 s25, s23, 0
	s_cmpk_eq_i32 s49, 0x52
	s_cselect_b32 s29, s1, s25
	s_cselect_b32 s28, s0, s24
	s_cselect_b32 s27, s21, s48
	s_cselect_b32 s26, s20, s47
	v_lshl_add_u64 v[144:145], s[22:23], 0, v[136:137]
	s_add_i32 m0, s31, 0xc000
	ds_read_b128 v[204:207], v167
	ds_read_b128 v[208:211], v167 offset:1024
	ds_read_b128 v[212:215], v167 offset:2048
	ds_read_b128 v[216:219], v167 offset:3072
	ds_read_b128 v[220:223], v167 offset:4096
	ds_read_b128 v[224:227], v167 offset:5120
	ds_read_b128 v[228:231], v167 offset:6144
	ds_read_b128 v[232:235], v167 offset:7168
	global_load_lds_dwordx4 v[144:145], off
	v_lshl_add_u64 v[144:145], s[22:23], 0, v[138:139]
	s_add_i32 m0, s31, 0xe000
	s_nop 0
	global_load_lds_dwordx4 v[144:145], off
	s_waitcnt vmcnt(8)
	s_waitcnt lgkmcnt(0)
	s_setprio 1
	s_barrier
	v_mfma_f32_16x16x32_bf16 v[124:127], v[170:173], v[204:207], v[124:127]
	v_mfma_f32_16x16x32_bf16 v[120:123], v[178:181], v[204:207], v[120:123]
	v_mfma_f32_16x16x32_bf16 v[108:111], v[170:173], v[212:215], v[108:111]
	v_mfma_f32_16x16x32_bf16 v[104:107], v[178:181], v[212:215], v[104:107]
	v_mfma_f32_16x16x32_bf16 v[92:95], v[170:173], v[220:223], v[92:95]
	v_mfma_f32_16x16x32_bf16 v[88:91], v[178:181], v[220:223], v[88:91]
	v_mfma_f32_16x16x32_bf16 v[76:79], v[170:173], v[228:231], v[76:79]
	v_mfma_f32_16x16x32_bf16 v[72:75], v[178:181], v[228:231], v[72:75]
	v_mfma_f32_16x16x32_bf16 v[124:127], v[174:177], v[208:211], v[124:127]
	v_mfma_f32_16x16x32_bf16 v[120:123], v[182:185], v[208:211], v[120:123]
	v_mfma_f32_16x16x32_bf16 v[108:111], v[174:177], v[216:219], v[108:111]
	v_mfma_f32_16x16x32_bf16 v[104:107], v[182:185], v[216:219], v[104:107]
	v_mfma_f32_16x16x32_bf16 v[92:95], v[174:177], v[224:227], v[92:95]
	v_mfma_f32_16x16x32_bf16 v[88:91], v[182:185], v[224:227], v[88:91]
	v_mfma_f32_16x16x32_bf16 v[76:79], v[174:177], v[232:235], v[76:79]
	v_mfma_f32_16x16x32_bf16 v[72:75], v[182:185], v[232:235], v[72:75]
	s_setprio 0
	s_setprio 1
	v_mfma_f32_16x16x32_bf16 v[116:119], v[186:189], v[204:207], v[116:119]
	v_mfma_f32_16x16x32_bf16 v[112:115], v[196:199], v[204:207], v[112:115]
	v_mfma_f32_16x16x32_bf16 v[100:103], v[186:189], v[212:215], v[100:103]
	v_mfma_f32_16x16x32_bf16 v[96:99], v[196:199], v[212:215], v[96:99]
	v_mfma_f32_16x16x32_bf16 v[84:87], v[186:189], v[220:223], v[84:87]
	v_mfma_f32_16x16x32_bf16 v[80:83], v[196:199], v[220:223], v[80:83]
	v_mfma_f32_16x16x32_bf16 v[68:71], v[186:189], v[228:231], v[68:71]
	v_mfma_f32_16x16x32_bf16 v[64:67], v[196:199], v[228:231], v[64:67]
	v_mfma_f32_16x16x32_bf16 v[116:119], v[192:195], v[208:211], v[116:119]
	v_mfma_f32_16x16x32_bf16 v[112:115], v[200:203], v[208:211], v[112:115]
	v_mfma_f32_16x16x32_bf16 v[100:103], v[192:195], v[216:219], v[100:103]
	v_mfma_f32_16x16x32_bf16 v[96:99], v[200:203], v[216:219], v[96:99]
	v_mfma_f32_16x16x32_bf16 v[84:87], v[192:195], v[224:227], v[84:87]
	v_mfma_f32_16x16x32_bf16 v[80:83], v[200:203], v[224:227], v[80:83]
	v_mfma_f32_16x16x32_bf16 v[68:71], v[192:195], v[232:235], v[68:71]
	v_mfma_f32_16x16x32_bf16 v[64:67], v[200:203], v[232:235], v[64:67]
	s_barrier
	s_setprio 0
	s_add_i32 s22, s43, s30
	v_lshl_add_u64 v[144:145], s[26:27], 0, v[130:131]
	s_mov_b32 m0, s22
	ds_read_b128 v[204:207], v167 offset:16384
	ds_read_b128 v[208:211], v167 offset:17408
	ds_read_b128 v[212:215], v167 offset:18432
	ds_read_b128 v[216:219], v167 offset:19456
	ds_read_b128 v[220:223], v167 offset:20480
	ds_read_b128 v[224:227], v167 offset:21504
	ds_read_b128 v[228:231], v167 offset:22528
	ds_read_b128 v[232:235], v167 offset:23552
	global_load_lds_dwordx4 v[144:145], off
	s_add_i32 m0, s22, 0x2000
	s_add_u32 s22, s26, 0x158000
	v_lshl_add_u64 v[236:237], s[26:27], 0, v[134:135]
	s_addc_u32 s23, s27, 0
	s_add_i32 s64, s44, s30
	global_load_lds_dwordx4 v[236:237], off
	v_lshl_add_u64 v[238:239], s[22:23], 0, v[130:131]
	s_mov_b32 m0, s64
	v_lshl_add_u64 v[240:241], s[28:29], 0, v[132:133]
	global_load_lds_dwordx4 v[238:239], off
	v_lshl_add_u64 v[238:239], s[22:23], 0, v[134:135]
	s_add_i32 m0, s64, 0x2000
	s_nop 0
	global_load_lds_dwordx4 v[238:239], off
	v_lshl_add_u64 v[238:239], s[28:29], 0, v[128:129]
	s_mov_b32 m0, s31
	s_nop 0
	global_load_lds_dwordx4 v[238:239], off
	s_mov_b32 m0, s34
	s_nop 0
	global_load_lds_dwordx4 v[240:241], off
	s_waitcnt vmcnt(8)
	s_waitcnt lgkmcnt(0)
	s_setprio 1
	s_barrier
	v_mfma_f32_16x16x32_bf16 v[60:63], v[170:173], v[204:207], v[60:63]
	v_mfma_f32_16x16x32_bf16 v[56:59], v[178:181], v[204:207], v[56:59]
	v_mfma_f32_16x16x32_bf16 v[44:47], v[170:173], v[212:215], v[44:47]
	v_mfma_f32_16x16x32_bf16 v[40:43], v[178:181], v[212:215], v[40:43]
	v_mfma_f32_16x16x32_bf16 v[28:31], v[170:173], v[220:223], v[28:31]
	v_mfma_f32_16x16x32_bf16 v[24:27], v[178:181], v[220:223], v[24:27]
	v_mfma_f32_16x16x32_bf16 v[12:15], v[170:173], v[228:231], v[12:15]
	v_mfma_f32_16x16x32_bf16 v[8:11], v[178:181], v[228:231], v[8:11]
	v_mfma_f32_16x16x32_bf16 v[60:63], v[174:177], v[208:211], v[60:63]
	v_mfma_f32_16x16x32_bf16 v[56:59], v[182:185], v[208:211], v[56:59]
	v_mfma_f32_16x16x32_bf16 v[44:47], v[174:177], v[216:219], v[44:47]
	v_mfma_f32_16x16x32_bf16 v[40:43], v[182:185], v[216:219], v[40:43]
	v_mfma_f32_16x16x32_bf16 v[28:31], v[174:177], v[224:227], v[28:31]
	v_mfma_f32_16x16x32_bf16 v[24:27], v[182:185], v[224:227], v[24:27]
	v_mfma_f32_16x16x32_bf16 v[12:15], v[174:177], v[232:235], v[12:15]
	v_mfma_f32_16x16x32_bf16 v[8:11], v[182:185], v[232:235], v[8:11]
	s_setprio 0
	s_setprio 1
	v_mfma_f32_16x16x32_bf16 v[52:55], v[186:189], v[204:207], v[52:55]
	v_mfma_f32_16x16x32_bf16 v[48:51], v[196:199], v[204:207], v[48:51]
	v_mfma_f32_16x16x32_bf16 v[36:39], v[186:189], v[212:215], v[36:39]
	v_mfma_f32_16x16x32_bf16 v[32:35], v[196:199], v[212:215], v[32:35]
	v_mfma_f32_16x16x32_bf16 v[20:23], v[186:189], v[220:223], v[20:23]
	v_mfma_f32_16x16x32_bf16 v[16:19], v[196:199], v[220:223], v[16:19]
	v_mfma_f32_16x16x32_bf16 v[4:7], v[186:189], v[228:231], v[4:7]
	v_mfma_f32_16x16x32_bf16 v[0:3], v[196:199], v[228:231], v[0:3]
	v_mfma_f32_16x16x32_bf16 v[52:55], v[192:195], v[208:211], v[52:55]
	v_mfma_f32_16x16x32_bf16 v[48:51], v[200:203], v[208:211], v[48:51]
	v_mfma_f32_16x16x32_bf16 v[36:39], v[192:195], v[216:219], v[36:39]
	v_mfma_f32_16x16x32_bf16 v[32:35], v[200:203], v[216:219], v[32:35]
	v_mfma_f32_16x16x32_bf16 v[20:23], v[192:195], v[224:227], v[20:23]
	v_mfma_f32_16x16x32_bf16 v[16:19], v[200:203], v[224:227], v[16:19]
	v_mfma_f32_16x16x32_bf16 v[4:7], v[192:195], v[232:235], v[4:7]
	v_mfma_f32_16x16x32_bf16 v[0:3], v[200:203], v[232:235], v[0:3]
	s_barrier
	s_setprio 0
	s_add_i32 s64, 0, 0x18000
	s_add_i32 s65, 0, 0x1c000
	v_add_u32_e32 v182, s64, v147
	v_add_u32_e32 v200, s65, v147
	ds_read_b128 v[170:173], v182
	ds_read_b128 v[174:177], v182 offset:1024
	ds_read_b128 v[178:181], v182 offset:2048
	ds_read_b128 v[182:185], v182 offset:3072
	ds_read_b128 v[186:189], v200
	ds_read_b128 v[192:195], v200 offset:1024
	ds_read_b128 v[196:199], v200 offset:2048
	ds_read_b128 v[200:203], v200 offset:3072
	s_add_u32 s22, s28, 0x158000
	s_addc_u32 s23, s29, 0
	s_mov_b32 m0, s35
	v_lshl_add_u64 v[242:243], s[22:23], 0, v[128:129]
	ds_read_b128 v[204:207], v167 offset:32768
	ds_read_b128 v[208:211], v167 offset:33792
	ds_read_b128 v[212:215], v167 offset:34816
	ds_read_b128 v[216:219], v167 offset:35840
	ds_read_b128 v[220:223], v167 offset:36864
	ds_read_b128 v[224:227], v167 offset:37888
	ds_read_b128 v[228:231], v167 offset:38912
	ds_read_b128 v[232:235], v167 offset:39936
	global_load_lds_dwordx4 v[242:243], off
	v_lshl_add_u64 v[242:243], s[22:23], 0, v[132:133]
	s_mov_b32 m0, s36
	s_nop 0
	global_load_lds_dwordx4 v[242:243], off
	s_waitcnt vmcnt(8)
	s_waitcnt lgkmcnt(0)
	s_setprio 1
	s_barrier
	v_mfma_f32_16x16x32_bf16 v[124:127], v[170:173], v[204:207], v[124:127]
	v_mfma_f32_16x16x32_bf16 v[120:123], v[178:181], v[204:207], v[120:123]
	v_mfma_f32_16x16x32_bf16 v[108:111], v[170:173], v[212:215], v[108:111]
	v_mfma_f32_16x16x32_bf16 v[104:107], v[178:181], v[212:215], v[104:107]
	v_mfma_f32_16x16x32_bf16 v[92:95], v[170:173], v[220:223], v[92:95]
	v_mfma_f32_16x16x32_bf16 v[88:91], v[178:181], v[220:223], v[88:91]
	v_mfma_f32_16x16x32_bf16 v[76:79], v[170:173], v[228:231], v[76:79]
	v_mfma_f32_16x16x32_bf16 v[72:75], v[178:181], v[228:231], v[72:75]
	v_mfma_f32_16x16x32_bf16 v[124:127], v[174:177], v[208:211], v[124:127]
	v_mfma_f32_16x16x32_bf16 v[120:123], v[182:185], v[208:211], v[120:123]
	v_mfma_f32_16x16x32_bf16 v[108:111], v[174:177], v[216:219], v[108:111]
	v_mfma_f32_16x16x32_bf16 v[104:107], v[182:185], v[216:219], v[104:107]
	v_mfma_f32_16x16x32_bf16 v[92:95], v[174:177], v[224:227], v[92:95]
	v_mfma_f32_16x16x32_bf16 v[88:91], v[182:185], v[224:227], v[88:91]
	v_mfma_f32_16x16x32_bf16 v[76:79], v[174:177], v[232:235], v[76:79]
	v_mfma_f32_16x16x32_bf16 v[72:75], v[182:185], v[232:235], v[72:75]
	s_setprio 0
	s_setprio 1
	v_mfma_f32_16x16x32_bf16 v[116:119], v[186:189], v[204:207], v[116:119]
	v_mfma_f32_16x16x32_bf16 v[112:115], v[196:199], v[204:207], v[112:115]
	v_mfma_f32_16x16x32_bf16 v[100:103], v[186:189], v[212:215], v[100:103]
	v_mfma_f32_16x16x32_bf16 v[96:99], v[196:199], v[212:215], v[96:99]
	v_mfma_f32_16x16x32_bf16 v[84:87], v[186:189], v[220:223], v[84:87]
	v_mfma_f32_16x16x32_bf16 v[80:83], v[196:199], v[220:223], v[80:83]
	v_mfma_f32_16x16x32_bf16 v[68:71], v[186:189], v[228:231], v[68:71]
	v_mfma_f32_16x16x32_bf16 v[64:67], v[196:199], v[228:231], v[64:67]
	v_mfma_f32_16x16x32_bf16 v[116:119], v[192:195], v[208:211], v[116:119]
	v_mfma_f32_16x16x32_bf16 v[112:115], v[200:203], v[208:211], v[112:115]
	v_mfma_f32_16x16x32_bf16 v[100:103], v[192:195], v[216:219], v[100:103]
	v_mfma_f32_16x16x32_bf16 v[96:99], v[200:203], v[216:219], v[96:99]
	v_mfma_f32_16x16x32_bf16 v[84:87], v[192:195], v[224:227], v[84:87]
	v_mfma_f32_16x16x32_bf16 v[80:83], v[200:203], v[224:227], v[80:83]
	v_mfma_f32_16x16x32_bf16 v[68:71], v[192:195], v[232:235], v[68:71]
	v_mfma_f32_16x16x32_bf16 v[64:67], v[200:203], v[232:235], v[64:67]
	s_barrier
	s_setprio 0
	s_add_i32 s22, s64, s30
	v_lshl_add_u64 v[144:145], v[144:145], 0, s[16:17]
	s_mov_b32 m0, s22
	ds_read_b128 v[204:207], v167 offset:49152
	ds_read_b128 v[208:211], v167 offset:50176
	ds_read_b128 v[212:215], v167 offset:51200
	ds_read_b128 v[216:219], v167 offset:52224
	ds_read_b128 v[220:223], v167 offset:53248
	ds_read_b128 v[224:227], v167 offset:54272
	ds_read_b128 v[228:231], v167 offset:55296
	ds_read_b128 v[232:235], v167 offset:56320
	global_load_lds_dwordx4 v[144:145], off
	s_add_i32 m0, s22, 0x2000
	s_add_u32 s22, s26, 0x158080
	v_lshl_add_u64 v[144:145], v[236:237], 0, s[16:17]
	s_addc_u32 s23, s27, 0
	s_add_i32 s26, s65, s30
	global_load_lds_dwordx4 v[144:145], off
	v_lshl_add_u64 v[144:145], s[22:23], 0, v[130:131]
	s_mov_b32 m0, s26
	s_nop 0
	global_load_lds_dwordx4 v[144:145], off
	v_lshl_add_u64 v[144:145], s[22:23], 0, v[134:135]
	s_add_i32 m0, s26, 0x2000
	s_nop 0
	global_load_lds_dwordx4 v[144:145], off
	v_lshl_add_u64 v[144:145], v[238:239], 0, s[16:17]
	s_mov_b32 m0, s38
	s_nop 0
	global_load_lds_dwordx4 v[144:145], off
	v_lshl_add_u64 v[144:145], v[240:241], 0, s[16:17]
	s_mov_b32 m0, s39
	s_nop 0
	global_load_lds_dwordx4 v[144:145], off
	s_waitcnt vmcnt(8)
	s_waitcnt lgkmcnt(0)
	s_setprio 1
	s_barrier
	v_mfma_f32_16x16x32_bf16 v[60:63], v[170:173], v[204:207], v[60:63]
	v_mfma_f32_16x16x32_bf16 v[56:59], v[178:181], v[204:207], v[56:59]
	v_mfma_f32_16x16x32_bf16 v[44:47], v[170:173], v[212:215], v[44:47]
	v_mfma_f32_16x16x32_bf16 v[40:43], v[178:181], v[212:215], v[40:43]
	v_mfma_f32_16x16x32_bf16 v[28:31], v[170:173], v[220:223], v[28:31]
	v_mfma_f32_16x16x32_bf16 v[24:27], v[178:181], v[220:223], v[24:27]
	v_mfma_f32_16x16x32_bf16 v[12:15], v[170:173], v[228:231], v[12:15]
	v_mfma_f32_16x16x32_bf16 v[8:11], v[178:181], v[228:231], v[8:11]
	v_mfma_f32_16x16x32_bf16 v[60:63], v[174:177], v[208:211], v[60:63]
	v_mfma_f32_16x16x32_bf16 v[56:59], v[182:185], v[208:211], v[56:59]
	v_mfma_f32_16x16x32_bf16 v[44:47], v[174:177], v[216:219], v[44:47]
	v_mfma_f32_16x16x32_bf16 v[40:43], v[182:185], v[216:219], v[40:43]
	v_mfma_f32_16x16x32_bf16 v[28:31], v[174:177], v[224:227], v[28:31]
	v_mfma_f32_16x16x32_bf16 v[24:27], v[182:185], v[224:227], v[24:27]
	v_mfma_f32_16x16x32_bf16 v[12:15], v[174:177], v[232:235], v[12:15]
	v_mfma_f32_16x16x32_bf16 v[8:11], v[182:185], v[232:235], v[8:11]
	s_setprio 0
	s_setprio 1
	v_mfma_f32_16x16x32_bf16 v[52:55], v[186:189], v[204:207], v[52:55]
	v_mfma_f32_16x16x32_bf16 v[48:51], v[196:199], v[204:207], v[48:51]
	v_mfma_f32_16x16x32_bf16 v[36:39], v[186:189], v[212:215], v[36:39]
	v_mfma_f32_16x16x32_bf16 v[32:35], v[196:199], v[212:215], v[32:35]
	v_mfma_f32_16x16x32_bf16 v[20:23], v[186:189], v[220:223], v[20:23]
	v_mfma_f32_16x16x32_bf16 v[16:19], v[196:199], v[220:223], v[16:19]
	v_mfma_f32_16x16x32_bf16 v[4:7], v[186:189], v[228:231], v[4:7]
	v_mfma_f32_16x16x32_bf16 v[0:3], v[196:199], v[228:231], v[0:3]
	v_mfma_f32_16x16x32_bf16 v[52:55], v[192:195], v[208:211], v[52:55]
	v_mfma_f32_16x16x32_bf16 v[48:51], v[200:203], v[208:211], v[48:51]
	v_mfma_f32_16x16x32_bf16 v[36:39], v[192:195], v[216:219], v[36:39]
	v_mfma_f32_16x16x32_bf16 v[32:35], v[200:203], v[216:219], v[32:35]
	v_mfma_f32_16x16x32_bf16 v[20:23], v[192:195], v[224:227], v[20:23]
	v_mfma_f32_16x16x32_bf16 v[16:19], v[200:203], v[224:227], v[16:19]
	v_mfma_f32_16x16x32_bf16 v[4:7], v[192:195], v[232:235], v[4:7]
	v_mfma_f32_16x16x32_bf16 v[0:3], v[200:203], v[232:235], v[0:3]
	s_barrier
	s_setprio 0
	s_add_i32 s49, s49, 2
	s_add_u32 s47, s47, 0x100
	s_addc_u32 s48, s48, 0
	s_cmpk_gt_u32 s49, 0x53
	s_mov_b64 s[22:23], s[24:25]
	s_cbranch_scc0 .LBB0_225
	s_and_b64 vcc, exec, s[18:19]
	s_cbranch_vccz .LBB0_228
	s_barrier

.LBB0_311:
	ds_read_b128 v[144:147], v153
	ds_read_b128 v[158:161], v153 offset:1024
	ds_read_b128 v[162:165], v153 offset:2048
	ds_read_b128 v[166:169], v153 offset:3072
	ds_read_b128 v[170:173], v154
	ds_read_b128 v[174:177], v154 offset:1024
	ds_read_b128 v[178:181], v154 offset:2048
	ds_read_b128 v[182:185], v154 offset:3072
	s_add_u32 s24, s22, 0xfff80080
	s_addc_u32 s25, s23, -1
	s_cmp_eq_u32 s64, 28
	s_cselect_b32 s27, s15, s25
	s_cselect_b32 s26, s46, s24
	s_cselect_b32 s25, s13, s49
	s_cselect_b32 s24, s47, s48
	v_lshl_add_u64 v[148:149], s[22:23], 0, v[136:137]
	s_add_i32 m0, s31, 0xc000
	ds_read_b128 v[186:189], v155
	ds_read_b128 v[192:195], v155 offset:1024
	ds_read_b128 v[196:199], v155 offset:2048
	ds_read_b128 v[200:203], v155 offset:3072
	ds_read_b128 v[204:207], v155 offset:4096
	ds_read_b128 v[208:211], v155 offset:5120
	ds_read_b128 v[212:215], v155 offset:6144
	ds_read_b128 v[216:219], v155 offset:7168
	global_load_lds_dwordx4 v[148:149], off
	v_lshl_add_u64 v[148:149], s[22:23], 0, v[138:139]
	s_add_i32 m0, s31, 0xe000
	s_nop 0
	global_load_lds_dwordx4 v[148:149], off
	s_waitcnt vmcnt(8)
	s_waitcnt lgkmcnt(0)
	s_setprio 1
	s_barrier
	v_mfma_f32_16x16x32_bf16 v[124:127], v[144:147], v[186:189], v[124:127]
	v_mfma_f32_16x16x32_bf16 v[120:123], v[162:165], v[186:189], v[120:123]
	v_mfma_f32_16x16x32_bf16 v[108:111], v[144:147], v[196:199], v[108:111]
	v_mfma_f32_16x16x32_bf16 v[104:107], v[162:165], v[196:199], v[104:107]
	v_mfma_f32_16x16x32_bf16 v[92:95], v[144:147], v[204:207], v[92:95]
	v_mfma_f32_16x16x32_bf16 v[88:91], v[162:165], v[204:207], v[88:91]
	v_mfma_f32_16x16x32_bf16 v[76:79], v[144:147], v[212:215], v[76:79]
	v_mfma_f32_16x16x32_bf16 v[72:75], v[162:165], v[212:215], v[72:75]
	v_mfma_f32_16x16x32_bf16 v[124:127], v[158:161], v[192:195], v[124:127]
	v_mfma_f32_16x16x32_bf16 v[120:123], v[166:169], v[192:195], v[120:123]
	v_mfma_f32_16x16x32_bf16 v[108:111], v[158:161], v[200:203], v[108:111]
	v_mfma_f32_16x16x32_bf16 v[104:107], v[166:169], v[200:203], v[104:107]
	v_mfma_f32_16x16x32_bf16 v[92:95], v[158:161], v[208:211], v[92:95]
	v_mfma_f32_16x16x32_bf16 v[88:91], v[166:169], v[208:211], v[88:91]
	v_mfma_f32_16x16x32_bf16 v[76:79], v[158:161], v[216:219], v[76:79]
	v_mfma_f32_16x16x32_bf16 v[72:75], v[166:169], v[216:219], v[72:75]
	s_setprio 0
	s_setprio 1
	v_mfma_f32_16x16x32_bf16 v[116:119], v[170:173], v[186:189], v[116:119]
	v_mfma_f32_16x16x32_bf16 v[112:115], v[178:181], v[186:189], v[112:115]
	v_mfma_f32_16x16x32_bf16 v[100:103], v[170:173], v[196:199], v[100:103]
	v_mfma_f32_16x16x32_bf16 v[96:99], v[178:181], v[196:199], v[96:99]
	v_mfma_f32_16x16x32_bf16 v[84:87], v[170:173], v[204:207], v[84:87]
	v_mfma_f32_16x16x32_bf16 v[80:83], v[178:181], v[204:207], v[80:83]
	v_mfma_f32_16x16x32_bf16 v[68:71], v[170:173], v[212:215], v[68:71]
	v_mfma_f32_16x16x32_bf16 v[64:67], v[178:181], v[212:215], v[64:67]
	v_mfma_f32_16x16x32_bf16 v[116:119], v[174:177], v[192:195], v[116:119]
	v_mfma_f32_16x16x32_bf16 v[112:115], v[182:185], v[192:195], v[112:115]
	v_mfma_f32_16x16x32_bf16 v[100:103], v[174:177], v[200:203], v[100:103]
	v_mfma_f32_16x16x32_bf16 v[96:99], v[182:185], v[200:203], v[96:99]
	v_mfma_f32_16x16x32_bf16 v[84:87], v[174:177], v[208:211], v[84:87]
	v_mfma_f32_16x16x32_bf16 v[80:83], v[182:185], v[208:211], v[80:83]
	v_mfma_f32_16x16x32_bf16 v[68:71], v[174:177], v[216:219], v[68:71]
	v_mfma_f32_16x16x32_bf16 v[64:67], v[182:185], v[216:219], v[64:67]
	s_barrier
	s_setprio 0
	s_add_i32 s65, s42, s28
	v_lshl_add_u64 v[148:149], s[24:25], 0, v[132:133]
	s_mov_b32 m0, s65
	ds_read_b128 v[186:189], v155 offset:16384
	ds_read_b128 v[192:195], v155 offset:17408
	ds_read_b128 v[196:199], v155 offset:18432
	ds_read_b128 v[200:203], v155 offset:19456
	ds_read_b128 v[204:207], v155 offset:20480
	ds_read_b128 v[208:211], v155 offset:21504
	ds_read_b128 v[212:215], v155 offset:22528
	ds_read_b128 v[216:219], v155 offset:23552
	global_load_lds_dwordx4 v[148:149], off
	s_add_i32 m0, s65, 0x2000
	s_add_u32 vcc_lo, s24, 0x80000
	v_lshl_add_u64 v[220:221], s[24:25], 0, v[128:129]
	s_addc_u32 vcc_hi, s25, 0
	s_add_i32 s65, s43, s28
	global_load_lds_dwordx4 v[220:221], off
	v_lshl_add_u64 v[222:223], vcc, 0, v[132:133]
	s_mov_b32 m0, s65
	v_lshl_add_u64 v[224:225], s[26:27], 0, v[130:131]
	global_load_lds_dwordx4 v[222:223], off
	v_lshl_add_u64 v[222:223], vcc, 0, v[128:129]
	s_add_i32 m0, s65, 0x2000
	s_nop 0
	global_load_lds_dwordx4 v[222:223], off
	v_lshl_add_u64 v[222:223], s[26:27], 0, v[134:135]
	s_mov_b32 m0, s31
	s_nop 0
	global_load_lds_dwordx4 v[222:223], off
	s_mov_b32 m0, s34
	s_nop 0
	global_load_lds_dwordx4 v[224:225], off
	s_waitcnt vmcnt(8)
	s_waitcnt lgkmcnt(0)
	s_setprio 1
	s_barrier
	v_mfma_f32_16x16x32_bf16 v[60:63], v[144:147], v[186:189], v[60:63]
	v_mfma_f32_16x16x32_bf16 v[56:59], v[162:165], v[186:189], v[56:59]
	v_mfma_f32_16x16x32_bf16 v[44:47], v[144:147], v[196:199], v[44:47]
	v_mfma_f32_16x16x32_bf16 v[40:43], v[162:165], v[196:199], v[40:43]
	v_mfma_f32_16x16x32_bf16 v[28:31], v[144:147], v[204:207], v[28:31]
	v_mfma_f32_16x16x32_bf16 v[24:27], v[162:165], v[204:207], v[24:27]
	v_mfma_f32_16x16x32_bf16 v[12:15], v[144:147], v[212:215], v[12:15]
	v_mfma_f32_16x16x32_bf16 v[8:11], v[162:165], v[212:215], v[8:11]
	v_mfma_f32_16x16x32_bf16 v[60:63], v[158:161], v[192:195], v[60:63]
	v_mfma_f32_16x16x32_bf16 v[56:59], v[166:169], v[192:195], v[56:59]
	v_mfma_f32_16x16x32_bf16 v[44:47], v[158:161], v[200:203], v[44:47]
	v_mfma_f32_16x16x32_bf16 v[40:43], v[166:169], v[200:203], v[40:43]
	v_mfma_f32_16x16x32_bf16 v[28:31], v[158:161], v[208:211], v[28:31]
	v_mfma_f32_16x16x32_bf16 v[24:27], v[166:169], v[208:211], v[24:27]
	v_mfma_f32_16x16x32_bf16 v[12:15], v[158:161], v[216:219], v[12:15]
	v_mfma_f32_16x16x32_bf16 v[8:11], v[166:169], v[216:219], v[8:11]
	s_setprio 0
	s_setprio 1
	v_mfma_f32_16x16x32_bf16 v[52:55], v[170:173], v[186:189], v[52:55]
	v_mfma_f32_16x16x32_bf16 v[48:51], v[178:181], v[186:189], v[48:51]
	v_mfma_f32_16x16x32_bf16 v[36:39], v[170:173], v[196:199], v[36:39]
	v_mfma_f32_16x16x32_bf16 v[32:35], v[178:181], v[196:199], v[32:35]
	v_mfma_f32_16x16x32_bf16 v[20:23], v[170:173], v[204:207], v[20:23]
	v_mfma_f32_16x16x32_bf16 v[16:19], v[178:181], v[204:207], v[16:19]
	v_mfma_f32_16x16x32_bf16 v[4:7], v[170:173], v[212:215], v[4:7]
	v_mfma_f32_16x16x32_bf16 v[0:3], v[178:181], v[212:215], v[0:3]
	v_mfma_f32_16x16x32_bf16 v[52:55], v[174:177], v[192:195], v[52:55]
	v_mfma_f32_16x16x32_bf16 v[48:51], v[182:185], v[192:195], v[48:51]
	v_mfma_f32_16x16x32_bf16 v[36:39], v[174:177], v[200:203], v[36:39]
	v_mfma_f32_16x16x32_bf16 v[32:35], v[182:185], v[200:203], v[32:35]
	v_mfma_f32_16x16x32_bf16 v[20:23], v[174:177], v[208:211], v[20:23]
	v_mfma_f32_16x16x32_bf16 v[16:19], v[182:185], v[208:211], v[16:19]
	v_mfma_f32_16x16x32_bf16 v[4:7], v[174:177], v[216:219], v[4:7]
	v_mfma_f32_16x16x32_bf16 v[0:3], v[182:185], v[216:219], v[0:3]
	s_barrier
	s_setprio 0
	s_add_i32 s65, 0, 0x18000
	v_add_u32_e32 v157, s65, v151
	s_add_i32 s69, 0, 0x1c000
	ds_read_b128 v[144:147], v157
	ds_read_b128 v[158:161], v157 offset:1024
	ds_read_b128 v[162:165], v157 offset:2048
	ds_read_b128 v[166:169], v157 offset:3072
	v_add_u32_e32 v157, s69, v151
	ds_read_b128 v[170:173], v157
	ds_read_b128 v[174:177], v157 offset:1024
	ds_read_b128 v[178:181], v157 offset:2048
	ds_read_b128 v[182:185], v157 offset:3072
	s_add_u32 s26, s26, 0x80000
	s_addc_u32 s27, s27, 0
	s_mov_b32 m0, s35
	v_lshl_add_u64 v[226:227], s[26:27], 0, v[134:135]
	ds_read_b128 v[186:189], v155 offset:32768
	ds_read_b128 v[192:195], v155 offset:33792
	ds_read_b128 v[196:199], v155 offset:34816
	ds_read_b128 v[200:203], v155 offset:35840
	ds_read_b128 v[204:207], v155 offset:36864
	ds_read_b128 v[208:211], v155 offset:37888
	ds_read_b128 v[212:215], v155 offset:38912
	ds_read_b128 v[216:219], v155 offset:39936
	global_load_lds_dwordx4 v[226:227], off
	v_lshl_add_u64 v[226:227], s[26:27], 0, v[130:131]
	s_mov_b32 m0, s36
	s_nop 0
	global_load_lds_dwordx4 v[226:227], off
	s_waitcnt vmcnt(8)
	s_waitcnt lgkmcnt(0)
	s_setprio 1
	s_barrier
	v_mfma_f32_16x16x32_bf16 v[124:127], v[144:147], v[186:189], v[124:127]
	v_mfma_f32_16x16x32_bf16 v[120:123], v[162:165], v[186:189], v[120:123]
	v_mfma_f32_16x16x32_bf16 v[108:111], v[144:147], v[196:199], v[108:111]
	v_mfma_f32_16x16x32_bf16 v[104:107], v[162:165], v[196:199], v[104:107]
	v_mfma_f32_16x16x32_bf16 v[92:95], v[144:147], v[204:207], v[92:95]
	v_mfma_f32_16x16x32_bf16 v[88:91], v[162:165], v[204:207], v[88:91]
	v_mfma_f32_16x16x32_bf16 v[76:79], v[144:147], v[212:215], v[76:79]
	v_mfma_f32_16x16x32_bf16 v[72:75], v[162:165], v[212:215], v[72:75]
	v_mfma_f32_16x16x32_bf16 v[124:127], v[158:161], v[192:195], v[124:127]
	v_mfma_f32_16x16x32_bf16 v[120:123], v[166:169], v[192:195], v[120:123]
	v_mfma_f32_16x16x32_bf16 v[108:111], v[158:161], v[200:203], v[108:111]
	v_mfma_f32_16x16x32_bf16 v[104:107], v[166:169], v[200:203], v[104:107]
	v_mfma_f32_16x16x32_bf16 v[92:95], v[158:161], v[208:211], v[92:95]
	v_mfma_f32_16x16x32_bf16 v[88:91], v[166:169], v[208:211], v[88:91]
	v_mfma_f32_16x16x32_bf16 v[76:79], v[158:161], v[216:219], v[76:79]
	v_mfma_f32_16x16x32_bf16 v[72:75], v[166:169], v[216:219], v[72:75]
	s_setprio 0
	s_setprio 1
	v_mfma_f32_16x16x32_bf16 v[116:119], v[170:173], v[186:189], v[116:119]
	v_mfma_f32_16x16x32_bf16 v[112:115], v[178:181], v[186:189], v[112:115]
	v_mfma_f32_16x16x32_bf16 v[100:103], v[170:173], v[196:199], v[100:103]
	v_mfma_f32_16x16x32_bf16 v[96:99], v[178:181], v[196:199], v[96:99]
	v_mfma_f32_16x16x32_bf16 v[84:87], v[170:173], v[204:207], v[84:87]
	v_mfma_f32_16x16x32_bf16 v[80:83], v[178:181], v[204:207], v[80:83]
	v_mfma_f32_16x16x32_bf16 v[68:71], v[170:173], v[212:215], v[68:71]
	v_mfma_f32_16x16x32_bf16 v[64:67], v[178:181], v[212:215], v[64:67]
	v_mfma_f32_16x16x32_bf16 v[116:119], v[174:177], v[192:195], v[116:119]
	v_mfma_f32_16x16x32_bf16 v[112:115], v[182:185], v[192:195], v[112:115]
	v_mfma_f32_16x16x32_bf16 v[100:103], v[174:177], v[200:203], v[100:103]
	v_mfma_f32_16x16x32_bf16 v[96:99], v[182:185], v[200:203], v[96:99]
	v_mfma_f32_16x16x32_bf16 v[84:87], v[174:177], v[208:211], v[84:87]
	v_mfma_f32_16x16x32_bf16 v[80:83], v[182:185], v[208:211], v[80:83]
	v_mfma_f32_16x16x32_bf16 v[68:71], v[174:177], v[216:219], v[68:71]
	v_mfma_f32_16x16x32_bf16 v[64:67], v[182:185], v[216:219], v[64:67]
	s_barrier
	s_setprio 0
	s_add_i32 s26, s65, s28
	v_lshl_add_u64 v[148:149], v[148:149], 0, s[6:7]
	s_mov_b32 m0, s26
	ds_read_b128 v[186:189], v155 offset:49152
	ds_read_b128 v[192:195], v155 offset:50176
	ds_read_b128 v[196:199], v155 offset:51200
	ds_read_b128 v[200:203], v155 offset:52224
	ds_read_b128 v[204:207], v155 offset:53248
	ds_read_b128 v[208:211], v155 offset:54272
	ds_read_b128 v[212:215], v155 offset:55296
	ds_read_b128 v[216:219], v155 offset:56320
	global_load_lds_dwordx4 v[148:149], off
	s_add_i32 m0, s26, 0x2000
	s_add_u32 s24, s24, 0x80080
	v_lshl_add_u64 v[148:149], v[220:221], 0, s[6:7]
	s_addc_u32 s25, s25, 0
	s_add_i32 s26, s69, s28
	global_load_lds_dwordx4 v[148:149], off
	v_lshl_add_u64 v[148:149], s[24:25], 0, v[132:133]
	s_mov_b32 m0, s26
	s_nop 0
	global_load_lds_dwordx4 v[148:149], off
	v_lshl_add_u64 v[148:149], s[24:25], 0, v[128:129]
	s_add_i32 m0, s26, 0x2000
	s_nop 0
	global_load_lds_dwordx4 v[148:149], off
	v_lshl_add_u64 v[148:149], v[222:223], 0, s[6:7]
	s_mov_b32 m0, s38
	s_nop 0
	global_load_lds_dwordx4 v[148:149], off
	v_lshl_add_u64 v[148:149], v[224:225], 0, s[6:7]
	s_mov_b32 m0, s39
	s_nop 0
	global_load_lds_dwordx4 v[148:149], off
	s_waitcnt vmcnt(8)
	s_waitcnt lgkmcnt(0)
	s_setprio 1
	s_barrier
	v_mfma_f32_16x16x32_bf16 v[60:63], v[144:147], v[186:189], v[60:63]
	v_mfma_f32_16x16x32_bf16 v[56:59], v[162:165], v[186:189], v[56:59]
	v_mfma_f32_16x16x32_bf16 v[44:47], v[144:147], v[196:199], v[44:47]
	v_mfma_f32_16x16x32_bf16 v[40:43], v[162:165], v[196:199], v[40:43]
	v_mfma_f32_16x16x32_bf16 v[28:31], v[144:147], v[204:207], v[28:31]
	v_mfma_f32_16x16x32_bf16 v[24:27], v[162:165], v[204:207], v[24:27]
	v_mfma_f32_16x16x32_bf16 v[12:15], v[144:147], v[212:215], v[12:15]
	v_mfma_f32_16x16x32_bf16 v[8:11], v[162:165], v[212:215], v[8:11]
	v_mfma_f32_16x16x32_bf16 v[60:63], v[158:161], v[192:195], v[60:63]
	v_mfma_f32_16x16x32_bf16 v[56:59], v[166:169], v[192:195], v[56:59]
	v_mfma_f32_16x16x32_bf16 v[44:47], v[158:161], v[200:203], v[44:47]
	v_mfma_f32_16x16x32_bf16 v[40:43], v[166:169], v[200:203], v[40:43]
	v_mfma_f32_16x16x32_bf16 v[28:31], v[158:161], v[208:211], v[28:31]
	v_mfma_f32_16x16x32_bf16 v[24:27], v[166:169], v[208:211], v[24:27]
	v_mfma_f32_16x16x32_bf16 v[12:15], v[158:161], v[216:219], v[12:15]
	v_mfma_f32_16x16x32_bf16 v[8:11], v[166:169], v[216:219], v[8:11]
	s_setprio 0
	s_setprio 1
	v_mfma_f32_16x16x32_bf16 v[52:55], v[170:173], v[186:189], v[52:55]
	v_mfma_f32_16x16x32_bf16 v[48:51], v[178:181], v[186:189], v[48:51]
	v_mfma_f32_16x16x32_bf16 v[36:39], v[170:173], v[196:199], v[36:39]
	v_mfma_f32_16x16x32_bf16 v[32:35], v[178:181], v[196:199], v[32:35]
	v_mfma_f32_16x16x32_bf16 v[20:23], v[170:173], v[204:207], v[20:23]
	v_mfma_f32_16x16x32_bf16 v[16:19], v[178:181], v[204:207], v[16:19]
	v_mfma_f32_16x16x32_bf16 v[4:7], v[170:173], v[212:215], v[4:7]
	v_mfma_f32_16x16x32_bf16 v[0:3], v[178:181], v[212:215], v[0:3]
	v_mfma_f32_16x16x32_bf16 v[52:55], v[174:177], v[192:195], v[52:55]
	v_mfma_f32_16x16x32_bf16 v[48:51], v[182:185], v[192:195], v[48:51]
	v_mfma_f32_16x16x32_bf16 v[36:39], v[174:177], v[200:203], v[36:39]
	v_mfma_f32_16x16x32_bf16 v[32:35], v[182:185], v[200:203], v[32:35]
	v_mfma_f32_16x16x32_bf16 v[20:23], v[174:177], v[208:211], v[20:23]
	v_mfma_f32_16x16x32_bf16 v[16:19], v[182:185], v[208:211], v[16:19]
	v_mfma_f32_16x16x32_bf16 v[4:7], v[174:177], v[216:219], v[4:7]
	v_mfma_f32_16x16x32_bf16 v[0:3], v[182:185], v[216:219], v[0:3]
	s_barrier
	s_setprio 0
	s_add_i32 s64, s64, 2
	s_add_u32 s22, s22, 0x100
	s_addc_u32 s23, s23, 0
	s_add_u32 s48, s48, 0x100
	s_addc_u32 s49, s49, 0
	s_cmp_gt_u32 s64, 29
	s_cbranch_scc0 .LBB0_311
	s_and_b64 vcc, exec, s[8:9]
	s_cbranch_vccz .LBB0_314
	s_barrier

.LBB0_705:
	ds_read_b128 v[170:173], v165
	ds_read_b128 v[174:177], v165 offset:1024
	ds_read_b128 v[178:181], v165 offset:2048
	ds_read_b128 v[182:185], v165 offset:3072
	ds_read_b128 v[186:189], v166
	ds_read_b128 v[192:195], v166 offset:1024
	ds_read_b128 v[196:199], v166 offset:2048
	ds_read_b128 v[200:203], v166 offset:3072
	s_add_u32 s36, s34, 0xfff80080
	s_addc_u32 s37, s35, -1
	s_cmp_eq_u32 s55, 28
	s_cselect_b32 s39, s13, s37
	s_cselect_b32 s38, s25, s36
	s_cselect_b32 s37, s23, s54
	s_cselect_b32 s36, s31, s53
	v_lshl_add_u64 v[144:145], s[34:35], 0, v[136:137]
	s_add_i32 m0, s5, 0xc000
	ds_read_b128 v[204:207], v167
	ds_read_b128 v[208:211], v167 offset:1024
	ds_read_b128 v[212:215], v167 offset:2048
	ds_read_b128 v[216:219], v167 offset:3072
	ds_read_b128 v[220:223], v167 offset:4096
	ds_read_b128 v[224:227], v167 offset:5120
	ds_read_b128 v[228:231], v167 offset:6144
	ds_read_b128 v[232:235], v167 offset:7168
	global_load_lds_dwordx4 v[144:145], off
	v_lshl_add_u64 v[144:145], s[34:35], 0, v[138:139]
	s_add_i32 m0, s5, 0xe000
	s_nop 0
	global_load_lds_dwordx4 v[144:145], off
	s_waitcnt vmcnt(8)
	s_waitcnt lgkmcnt(0)
	s_setprio 1
	s_barrier
	v_mfma_f32_16x16x32_bf16 v[124:127], v[170:173], v[204:207], v[124:127]
	v_mfma_f32_16x16x32_bf16 v[120:123], v[178:181], v[204:207], v[120:123]
	v_mfma_f32_16x16x32_bf16 v[108:111], v[170:173], v[212:215], v[108:111]
	v_mfma_f32_16x16x32_bf16 v[104:107], v[178:181], v[212:215], v[104:107]
	v_mfma_f32_16x16x32_bf16 v[92:95], v[170:173], v[220:223], v[92:95]
	v_mfma_f32_16x16x32_bf16 v[88:91], v[178:181], v[220:223], v[88:91]
	v_mfma_f32_16x16x32_bf16 v[76:79], v[170:173], v[228:231], v[76:79]
	v_mfma_f32_16x16x32_bf16 v[72:75], v[178:181], v[228:231], v[72:75]
	v_mfma_f32_16x16x32_bf16 v[124:127], v[174:177], v[208:211], v[124:127]
	v_mfma_f32_16x16x32_bf16 v[120:123], v[182:185], v[208:211], v[120:123]
	v_mfma_f32_16x16x32_bf16 v[108:111], v[174:177], v[216:219], v[108:111]
	v_mfma_f32_16x16x32_bf16 v[104:107], v[182:185], v[216:219], v[104:107]
	v_mfma_f32_16x16x32_bf16 v[92:95], v[174:177], v[224:227], v[92:95]
	v_mfma_f32_16x16x32_bf16 v[88:91], v[182:185], v[224:227], v[88:91]
	v_mfma_f32_16x16x32_bf16 v[76:79], v[174:177], v[232:235], v[76:79]
	v_mfma_f32_16x16x32_bf16 v[72:75], v[182:185], v[232:235], v[72:75]
	s_setprio 0
	s_setprio 1
	v_mfma_f32_16x16x32_bf16 v[116:119], v[186:189], v[204:207], v[116:119]
	v_mfma_f32_16x16x32_bf16 v[112:115], v[196:199], v[204:207], v[112:115]
	v_mfma_f32_16x16x32_bf16 v[100:103], v[186:189], v[212:215], v[100:103]
	v_mfma_f32_16x16x32_bf16 v[96:99], v[196:199], v[212:215], v[96:99]
	v_mfma_f32_16x16x32_bf16 v[84:87], v[186:189], v[220:223], v[84:87]
	v_mfma_f32_16x16x32_bf16 v[80:83], v[196:199], v[220:223], v[80:83]
	v_mfma_f32_16x16x32_bf16 v[68:71], v[186:189], v[228:231], v[68:71]
	v_mfma_f32_16x16x32_bf16 v[64:67], v[196:199], v[228:231], v[64:67]
	v_mfma_f32_16x16x32_bf16 v[116:119], v[192:195], v[208:211], v[116:119]
	v_mfma_f32_16x16x32_bf16 v[112:115], v[200:203], v[208:211], v[112:115]
	v_mfma_f32_16x16x32_bf16 v[100:103], v[192:195], v[216:219], v[100:103]
	v_mfma_f32_16x16x32_bf16 v[96:99], v[200:203], v[216:219], v[96:99]
	v_mfma_f32_16x16x32_bf16 v[84:87], v[192:195], v[224:227], v[84:87]
	v_mfma_f32_16x16x32_bf16 v[80:83], v[200:203], v[224:227], v[80:83]
	v_mfma_f32_16x16x32_bf16 v[68:71], v[192:195], v[232:235], v[68:71]
	v_mfma_f32_16x16x32_bf16 v[64:67], v[200:203], v[232:235], v[64:67]
	s_barrier
	s_setprio 0
	s_add_i32 s56, s49, s4
	v_lshl_add_u64 v[144:145], s[36:37], 0, v[130:131]
	s_mov_b32 m0, s56
	ds_read_b128 v[204:207], v167 offset:16384
	ds_read_b128 v[208:211], v167 offset:17408
	ds_read_b128 v[212:215], v167 offset:18432
	ds_read_b128 v[216:219], v167 offset:19456
	ds_read_b128 v[220:223], v167 offset:20480
	ds_read_b128 v[224:227], v167 offset:21504
	ds_read_b128 v[228:231], v167 offset:22528
	ds_read_b128 v[232:235], v167 offset:23552
	global_load_lds_dwordx4 v[144:145], off
	s_add_i32 m0, s56, 0x2000
	s_add_u32 s56, s36, 0x80000
	v_lshl_add_u64 v[236:237], s[36:37], 0, v[134:135]
	s_addc_u32 s57, s37, 0
	s_add_i32 s58, s52, s4
	global_load_lds_dwordx4 v[236:237], off
	v_lshl_add_u64 v[238:239], s[56:57], 0, v[130:131]
	s_mov_b32 m0, s58
	v_lshl_add_u64 v[240:241], s[38:39], 0, v[132:133]
	global_load_lds_dwordx4 v[238:239], off
	v_lshl_add_u64 v[238:239], s[56:57], 0, v[134:135]
	s_add_i32 m0, s58, 0x2000
	s_nop 0
	global_load_lds_dwordx4 v[238:239], off
	v_lshl_add_u64 v[238:239], s[38:39], 0, v[128:129]
	s_mov_b32 m0, s5
	s_nop 0
	global_load_lds_dwordx4 v[238:239], off
	s_mov_b32 m0, s40
	s_nop 0
	global_load_lds_dwordx4 v[240:241], off
	s_waitcnt vmcnt(8)
	s_waitcnt lgkmcnt(0)
	s_setprio 1
	s_barrier
	v_mfma_f32_16x16x32_bf16 v[60:63], v[170:173], v[204:207], v[60:63]
	v_mfma_f32_16x16x32_bf16 v[56:59], v[178:181], v[204:207], v[56:59]
	v_mfma_f32_16x16x32_bf16 v[44:47], v[170:173], v[212:215], v[44:47]
	v_mfma_f32_16x16x32_bf16 v[40:43], v[178:181], v[212:215], v[40:43]
	v_mfma_f32_16x16x32_bf16 v[28:31], v[170:173], v[220:223], v[28:31]
	v_mfma_f32_16x16x32_bf16 v[24:27], v[178:181], v[220:223], v[24:27]
	v_mfma_f32_16x16x32_bf16 v[12:15], v[170:173], v[228:231], v[12:15]
	v_mfma_f32_16x16x32_bf16 v[8:11], v[178:181], v[228:231], v[8:11]
	v_mfma_f32_16x16x32_bf16 v[60:63], v[174:177], v[208:211], v[60:63]
	v_mfma_f32_16x16x32_bf16 v[56:59], v[182:185], v[208:211], v[56:59]
	v_mfma_f32_16x16x32_bf16 v[44:47], v[174:177], v[216:219], v[44:47]
	v_mfma_f32_16x16x32_bf16 v[40:43], v[182:185], v[216:219], v[40:43]
	v_mfma_f32_16x16x32_bf16 v[28:31], v[174:177], v[224:227], v[28:31]
	v_mfma_f32_16x16x32_bf16 v[24:27], v[182:185], v[224:227], v[24:27]
	v_mfma_f32_16x16x32_bf16 v[12:15], v[174:177], v[232:235], v[12:15]
	v_mfma_f32_16x16x32_bf16 v[8:11], v[182:185], v[232:235], v[8:11]
	s_setprio 0
	s_setprio 1
	v_mfma_f32_16x16x32_bf16 v[52:55], v[186:189], v[204:207], v[52:55]
	v_mfma_f32_16x16x32_bf16 v[48:51], v[196:199], v[204:207], v[48:51]
	v_mfma_f32_16x16x32_bf16 v[36:39], v[186:189], v[212:215], v[36:39]
	v_mfma_f32_16x16x32_bf16 v[32:35], v[196:199], v[212:215], v[32:35]
	v_mfma_f32_16x16x32_bf16 v[20:23], v[186:189], v[220:223], v[20:23]
	v_mfma_f32_16x16x32_bf16 v[16:19], v[196:199], v[220:223], v[16:19]
	v_mfma_f32_16x16x32_bf16 v[4:7], v[186:189], v[228:231], v[4:7]
	v_mfma_f32_16x16x32_bf16 v[0:3], v[196:199], v[228:231], v[0:3]
	v_mfma_f32_16x16x32_bf16 v[52:55], v[192:195], v[208:211], v[52:55]
	v_mfma_f32_16x16x32_bf16 v[48:51], v[200:203], v[208:211], v[48:51]
	v_mfma_f32_16x16x32_bf16 v[36:39], v[192:195], v[216:219], v[36:39]
	v_mfma_f32_16x16x32_bf16 v[32:35], v[200:203], v[216:219], v[32:35]
	v_mfma_f32_16x16x32_bf16 v[20:23], v[192:195], v[224:227], v[20:23]
	v_mfma_f32_16x16x32_bf16 v[16:19], v[200:203], v[224:227], v[16:19]
	v_mfma_f32_16x16x32_bf16 v[4:7], v[192:195], v[232:235], v[4:7]
	v_mfma_f32_16x16x32_bf16 v[0:3], v[200:203], v[232:235], v[0:3]
	s_barrier
	s_setprio 0
	s_add_i32 s56, 0, 0x18000
	s_add_i32 s57, 0, 0x1c000
	v_add_u32_e32 v182, s56, v147
	v_add_u32_e32 v200, s57, v147
	ds_read_b128 v[170:173], v182
	ds_read_b128 v[174:177], v182 offset:1024
	ds_read_b128 v[178:181], v182 offset:2048
	ds_read_b128 v[182:185], v182 offset:3072
	ds_read_b128 v[186:189], v200
	ds_read_b128 v[192:195], v200 offset:1024
	ds_read_b128 v[196:199], v200 offset:2048
	ds_read_b128 v[200:203], v200 offset:3072
	s_add_u32 s38, s38, 0x80000
	s_addc_u32 s39, s39, 0
	s_mov_b32 m0, s41
	v_lshl_add_u64 v[242:243], s[38:39], 0, v[128:129]
	ds_read_b128 v[204:207], v167 offset:32768
	ds_read_b128 v[208:211], v167 offset:33792
	ds_read_b128 v[212:215], v167 offset:34816
	ds_read_b128 v[216:219], v167 offset:35840
	ds_read_b128 v[220:223], v167 offset:36864
	ds_read_b128 v[224:227], v167 offset:37888
	ds_read_b128 v[228:231], v167 offset:38912
	ds_read_b128 v[232:235], v167 offset:39936
	global_load_lds_dwordx4 v[242:243], off
	v_lshl_add_u64 v[242:243], s[38:39], 0, v[132:133]
	s_mov_b32 m0, s42
	s_nop 0
	global_load_lds_dwordx4 v[242:243], off
	s_waitcnt vmcnt(8)
	s_waitcnt lgkmcnt(0)
	s_setprio 1
	s_barrier
	v_mfma_f32_16x16x32_bf16 v[124:127], v[170:173], v[204:207], v[124:127]
	v_mfma_f32_16x16x32_bf16 v[120:123], v[178:181], v[204:207], v[120:123]
	v_mfma_f32_16x16x32_bf16 v[108:111], v[170:173], v[212:215], v[108:111]
	v_mfma_f32_16x16x32_bf16 v[104:107], v[178:181], v[212:215], v[104:107]
	v_mfma_f32_16x16x32_bf16 v[92:95], v[170:173], v[220:223], v[92:95]
	v_mfma_f32_16x16x32_bf16 v[88:91], v[178:181], v[220:223], v[88:91]
	v_mfma_f32_16x16x32_bf16 v[76:79], v[170:173], v[228:231], v[76:79]
	v_mfma_f32_16x16x32_bf16 v[72:75], v[178:181], v[228:231], v[72:75]
	v_mfma_f32_16x16x32_bf16 v[124:127], v[174:177], v[208:211], v[124:127]
	v_mfma_f32_16x16x32_bf16 v[120:123], v[182:185], v[208:211], v[120:123]
	v_mfma_f32_16x16x32_bf16 v[108:111], v[174:177], v[216:219], v[108:111]
	v_mfma_f32_16x16x32_bf16 v[104:107], v[182:185], v[216:219], v[104:107]
	v_mfma_f32_16x16x32_bf16 v[92:95], v[174:177], v[224:227], v[92:95]
	v_mfma_f32_16x16x32_bf16 v[88:91], v[182:185], v[224:227], v[88:91]
	v_mfma_f32_16x16x32_bf16 v[76:79], v[174:177], v[232:235], v[76:79]
	v_mfma_f32_16x16x32_bf16 v[72:75], v[182:185], v[232:235], v[72:75]
	s_setprio 0
	s_setprio 1
	v_mfma_f32_16x16x32_bf16 v[116:119], v[186:189], v[204:207], v[116:119]
	v_mfma_f32_16x16x32_bf16 v[112:115], v[196:199], v[204:207], v[112:115]
	v_mfma_f32_16x16x32_bf16 v[100:103], v[186:189], v[212:215], v[100:103]
	v_mfma_f32_16x16x32_bf16 v[96:99], v[196:199], v[212:215], v[96:99]
	v_mfma_f32_16x16x32_bf16 v[84:87], v[186:189], v[220:223], v[84:87]
	v_mfma_f32_16x16x32_bf16 v[80:83], v[196:199], v[220:223], v[80:83]
	v_mfma_f32_16x16x32_bf16 v[68:71], v[186:189], v[228:231], v[68:71]
	v_mfma_f32_16x16x32_bf16 v[64:67], v[196:199], v[228:231], v[64:67]
	v_mfma_f32_16x16x32_bf16 v[116:119], v[192:195], v[208:211], v[116:119]
	v_mfma_f32_16x16x32_bf16 v[112:115], v[200:203], v[208:211], v[112:115]
	v_mfma_f32_16x16x32_bf16 v[100:103], v[192:195], v[216:219], v[100:103]
	v_mfma_f32_16x16x32_bf16 v[96:99], v[200:203], v[216:219], v[96:99]
	v_mfma_f32_16x16x32_bf16 v[84:87], v[192:195], v[224:227], v[84:87]
	v_mfma_f32_16x16x32_bf16 v[80:83], v[200:203], v[224:227], v[80:83]
	v_mfma_f32_16x16x32_bf16 v[68:71], v[192:195], v[232:235], v[68:71]
	v_mfma_f32_16x16x32_bf16 v[64:67], v[200:203], v[232:235], v[64:67]
	s_barrier
	s_setprio 0
	s_add_i32 s38, s56, s4
	v_lshl_add_u64 v[144:145], v[144:145], 0, s[16:17]
	s_mov_b32 m0, s38
	ds_read_b128 v[204:207], v167 offset:49152
	ds_read_b128 v[208:211], v167 offset:50176
	ds_read_b128 v[212:215], v167 offset:51200
	ds_read_b128 v[216:219], v167 offset:52224
	ds_read_b128 v[220:223], v167 offset:53248
	ds_read_b128 v[224:227], v167 offset:54272
	ds_read_b128 v[228:231], v167 offset:55296
	ds_read_b128 v[232:235], v167 offset:56320
	global_load_lds_dwordx4 v[144:145], off
	s_add_i32 m0, s38, 0x2000
	s_add_u32 s36, s36, 0x80080
	v_lshl_add_u64 v[144:145], v[236:237], 0, s[16:17]
	s_addc_u32 s37, s37, 0
	s_add_i32 s38, s57, s4
	global_load_lds_dwordx4 v[144:145], off
	v_lshl_add_u64 v[144:145], s[36:37], 0, v[130:131]
	s_mov_b32 m0, s38
	s_nop 0
	global_load_lds_dwordx4 v[144:145], off
	v_lshl_add_u64 v[144:145], s[36:37], 0, v[134:135]
	s_add_i32 m0, s38, 0x2000
	s_nop 0
	global_load_lds_dwordx4 v[144:145], off
	v_lshl_add_u64 v[144:145], v[238:239], 0, s[16:17]
	s_mov_b32 m0, s44
	s_nop 0
	global_load_lds_dwordx4 v[144:145], off
	v_lshl_add_u64 v[144:145], v[240:241], 0, s[16:17]
	s_mov_b32 m0, s45
	s_nop 0
	global_load_lds_dwordx4 v[144:145], off
	s_waitcnt vmcnt(8)
	s_waitcnt lgkmcnt(0)
	s_setprio 1
	s_barrier
	v_mfma_f32_16x16x32_bf16 v[60:63], v[170:173], v[204:207], v[60:63]
	v_mfma_f32_16x16x32_bf16 v[56:59], v[178:181], v[204:207], v[56:59]
	v_mfma_f32_16x16x32_bf16 v[44:47], v[170:173], v[212:215], v[44:47]
	v_mfma_f32_16x16x32_bf16 v[40:43], v[178:181], v[212:215], v[40:43]
	v_mfma_f32_16x16x32_bf16 v[28:31], v[170:173], v[220:223], v[28:31]
	v_mfma_f32_16x16x32_bf16 v[24:27], v[178:181], v[220:223], v[24:27]
	v_mfma_f32_16x16x32_bf16 v[12:15], v[170:173], v[228:231], v[12:15]
	v_mfma_f32_16x16x32_bf16 v[8:11], v[178:181], v[228:231], v[8:11]
	v_mfma_f32_16x16x32_bf16 v[60:63], v[174:177], v[208:211], v[60:63]
	v_mfma_f32_16x16x32_bf16 v[56:59], v[182:185], v[208:211], v[56:59]
	v_mfma_f32_16x16x32_bf16 v[44:47], v[174:177], v[216:219], v[44:47]
	v_mfma_f32_16x16x32_bf16 v[40:43], v[182:185], v[216:219], v[40:43]
	v_mfma_f32_16x16x32_bf16 v[28:31], v[174:177], v[224:227], v[28:31]
	v_mfma_f32_16x16x32_bf16 v[24:27], v[182:185], v[224:227], v[24:27]
	v_mfma_f32_16x16x32_bf16 v[12:15], v[174:177], v[232:235], v[12:15]
	v_mfma_f32_16x16x32_bf16 v[8:11], v[182:185], v[232:235], v[8:11]
	s_setprio 0
	s_setprio 1
	v_mfma_f32_16x16x32_bf16 v[52:55], v[186:189], v[204:207], v[52:55]
	v_mfma_f32_16x16x32_bf16 v[48:51], v[196:199], v[204:207], v[48:51]
	v_mfma_f32_16x16x32_bf16 v[36:39], v[186:189], v[212:215], v[36:39]
	v_mfma_f32_16x16x32_bf16 v[32:35], v[196:199], v[212:215], v[32:35]
	v_mfma_f32_16x16x32_bf16 v[20:23], v[186:189], v[220:223], v[20:23]
	v_mfma_f32_16x16x32_bf16 v[16:19], v[196:199], v[220:223], v[16:19]
	v_mfma_f32_16x16x32_bf16 v[4:7], v[186:189], v[228:231], v[4:7]
	v_mfma_f32_16x16x32_bf16 v[0:3], v[196:199], v[228:231], v[0:3]
	v_mfma_f32_16x16x32_bf16 v[52:55], v[192:195], v[208:211], v[52:55]
	v_mfma_f32_16x16x32_bf16 v[48:51], v[200:203], v[208:211], v[48:51]
	v_mfma_f32_16x16x32_bf16 v[36:39], v[192:195], v[216:219], v[36:39]
	v_mfma_f32_16x16x32_bf16 v[32:35], v[200:203], v[216:219], v[32:35]
	v_mfma_f32_16x16x32_bf16 v[20:23], v[192:195], v[224:227], v[20:23]
	v_mfma_f32_16x16x32_bf16 v[16:19], v[200:203], v[224:227], v[16:19]
	v_mfma_f32_16x16x32_bf16 v[4:7], v[192:195], v[232:235], v[4:7]
	v_mfma_f32_16x16x32_bf16 v[0:3], v[200:203], v[232:235], v[0:3]
	s_barrier
	s_setprio 0
	s_add_i32 s55, s55, 2
	s_add_u32 s34, s34, 0x100
	s_addc_u32 s35, s35, 0
	s_add_u32 s53, s53, 0x100
	s_addc_u32 s54, s54, 0
	s_cmp_gt_u32 s55, 29
	s_cbranch_scc0 .LBB0_705
	s_and_b64 vcc, exec, s[20:21]
	s_cbranch_vccz .LBB0_708
	s_barrier

.LBB0_799:
	ds_read_b128 v[144:147], v151
	ds_read_b128 v[156:159], v151 offset:1024
	ds_read_b128 v[160:163], v151 offset:2048
	ds_read_b128 v[164:167], v151 offset:3072
	ds_read_b128 v[168:171], v152
	ds_read_b128 v[172:175], v152 offset:1024
	ds_read_b128 v[176:179], v152 offset:2048
	ds_read_b128 v[180:183], v152 offset:3072
	s_add_u32 s30, s28, 0xfff80080
	s_addc_u32 s31, s29, -1
	s_cmp_eq_u32 s54, 28
	s_cselect_b32 s35, s17, s31
	s_cselect_b32 s34, s48, s30
	s_cselect_b32 s31, s15, s53
	s_cselect_b32 s30, s49, s52
	v_lshl_add_u64 v[188:189], s[28:29], 0, v[136:137]
	s_add_i32 m0, s36, 0xc000
	ds_read_b128 v[184:187], v153
	ds_read_b128 v[192:195], v153 offset:1024
	ds_read_b128 v[196:199], v153 offset:2048
	ds_read_b128 v[200:203], v153 offset:3072
	ds_read_b128 v[204:207], v153 offset:4096
	ds_read_b128 v[208:211], v153 offset:5120
	ds_read_b128 v[212:215], v153 offset:6144
	ds_read_b128 v[216:219], v153 offset:7168
	global_load_lds_dwordx4 v[188:189], off
	v_lshl_add_u64 v[188:189], s[28:29], 0, v[138:139]
	s_add_i32 m0, s36, 0xe000
	s_nop 0
	global_load_lds_dwordx4 v[188:189], off
	s_waitcnt vmcnt(8)
	s_waitcnt lgkmcnt(0)
	s_setprio 1
	s_barrier
	v_mfma_f32_16x16x32_bf16 v[124:127], v[144:147], v[184:187], v[124:127]
	v_mfma_f32_16x16x32_bf16 v[120:123], v[160:163], v[184:187], v[120:123]
	v_mfma_f32_16x16x32_bf16 v[108:111], v[144:147], v[196:199], v[108:111]
	v_mfma_f32_16x16x32_bf16 v[104:107], v[160:163], v[196:199], v[104:107]
	v_mfma_f32_16x16x32_bf16 v[92:95], v[144:147], v[204:207], v[92:95]
	v_mfma_f32_16x16x32_bf16 v[88:91], v[160:163], v[204:207], v[88:91]
	v_mfma_f32_16x16x32_bf16 v[76:79], v[144:147], v[212:215], v[76:79]
	v_mfma_f32_16x16x32_bf16 v[72:75], v[160:163], v[212:215], v[72:75]
	v_mfma_f32_16x16x32_bf16 v[124:127], v[156:159], v[192:195], v[124:127]
	v_mfma_f32_16x16x32_bf16 v[120:123], v[164:167], v[192:195], v[120:123]
	v_mfma_f32_16x16x32_bf16 v[108:111], v[156:159], v[200:203], v[108:111]
	v_mfma_f32_16x16x32_bf16 v[104:107], v[164:167], v[200:203], v[104:107]
	v_mfma_f32_16x16x32_bf16 v[92:95], v[156:159], v[208:211], v[92:95]
	v_mfma_f32_16x16x32_bf16 v[88:91], v[164:167], v[208:211], v[88:91]
	v_mfma_f32_16x16x32_bf16 v[76:79], v[156:159], v[216:219], v[76:79]
	v_mfma_f32_16x16x32_bf16 v[72:75], v[164:167], v[216:219], v[72:75]
	s_setprio 0
	s_setprio 1
	v_mfma_f32_16x16x32_bf16 v[116:119], v[168:171], v[184:187], v[116:119]
	v_mfma_f32_16x16x32_bf16 v[112:115], v[176:179], v[184:187], v[112:115]
	v_mfma_f32_16x16x32_bf16 v[100:103], v[168:171], v[196:199], v[100:103]
	v_mfma_f32_16x16x32_bf16 v[96:99], v[176:179], v[196:199], v[96:99]
	v_mfma_f32_16x16x32_bf16 v[84:87], v[168:171], v[204:207], v[84:87]
	v_mfma_f32_16x16x32_bf16 v[80:83], v[176:179], v[204:207], v[80:83]
	v_mfma_f32_16x16x32_bf16 v[68:71], v[168:171], v[212:215], v[68:71]
	v_mfma_f32_16x16x32_bf16 v[64:67], v[176:179], v[212:215], v[64:67]
	v_mfma_f32_16x16x32_bf16 v[116:119], v[172:175], v[192:195], v[116:119]
	v_mfma_f32_16x16x32_bf16 v[112:115], v[180:183], v[192:195], v[112:115]
	v_mfma_f32_16x16x32_bf16 v[100:103], v[172:175], v[200:203], v[100:103]
	v_mfma_f32_16x16x32_bf16 v[96:99], v[180:183], v[200:203], v[96:99]
	v_mfma_f32_16x16x32_bf16 v[84:87], v[172:175], v[208:211], v[84:87]
	v_mfma_f32_16x16x32_bf16 v[80:83], v[180:183], v[208:211], v[80:83]
	v_mfma_f32_16x16x32_bf16 v[68:71], v[172:175], v[216:219], v[68:71]
	v_mfma_f32_16x16x32_bf16 v[64:67], v[180:183], v[216:219], v[64:67]
	s_barrier
	s_setprio 0
	s_add_i32 s55, s45, s5
	v_lshl_add_u64 v[188:189], s[30:31], 0, v[130:131]
	s_mov_b32 m0, s55
	ds_read_b128 v[184:187], v153 offset:16384
	ds_read_b128 v[192:195], v153 offset:17408
	ds_read_b128 v[196:199], v153 offset:18432
	ds_read_b128 v[200:203], v153 offset:19456
	ds_read_b128 v[204:207], v153 offset:20480
	ds_read_b128 v[208:211], v153 offset:21504
	ds_read_b128 v[212:215], v153 offset:22528
	ds_read_b128 v[216:219], v153 offset:23552
	global_load_lds_dwordx4 v[188:189], off
	s_add_i32 m0, s55, 0x2000
	s_add_u32 s56, s30, 0x80000
	v_lshl_add_u64 v[220:221], s[30:31], 0, v[134:135]
	s_addc_u32 s57, s31, 0
	s_add_i32 s55, s46, s5
	global_load_lds_dwordx4 v[220:221], off
	v_lshl_add_u64 v[222:223], s[56:57], 0, v[130:131]
	s_mov_b32 m0, s55
	v_lshl_add_u64 v[224:225], s[34:35], 0, v[132:133]
	global_load_lds_dwordx4 v[222:223], off
	v_lshl_add_u64 v[222:223], s[56:57], 0, v[134:135]
	s_add_i32 m0, s55, 0x2000
	s_nop 0
	global_load_lds_dwordx4 v[222:223], off
	v_lshl_add_u64 v[222:223], s[34:35], 0, v[128:129]
	s_mov_b32 m0, s36
	s_nop 0
	global_load_lds_dwordx4 v[222:223], off
	s_mov_b32 m0, s37
	s_nop 0
	global_load_lds_dwordx4 v[224:225], off
	s_waitcnt vmcnt(8)
	s_waitcnt lgkmcnt(0)
	s_setprio 1
	s_barrier
	v_mfma_f32_16x16x32_bf16 v[60:63], v[144:147], v[184:187], v[60:63]
	v_mfma_f32_16x16x32_bf16 v[56:59], v[160:163], v[184:187], v[56:59]
	v_mfma_f32_16x16x32_bf16 v[44:47], v[144:147], v[196:199], v[44:47]
	v_mfma_f32_16x16x32_bf16 v[40:43], v[160:163], v[196:199], v[40:43]
	v_mfma_f32_16x16x32_bf16 v[28:31], v[144:147], v[204:207], v[28:31]
	v_mfma_f32_16x16x32_bf16 v[24:27], v[160:163], v[204:207], v[24:27]
	v_mfma_f32_16x16x32_bf16 v[12:15], v[144:147], v[212:215], v[12:15]
	v_mfma_f32_16x16x32_bf16 v[8:11], v[160:163], v[212:215], v[8:11]
	v_mfma_f32_16x16x32_bf16 v[60:63], v[156:159], v[192:195], v[60:63]
	v_mfma_f32_16x16x32_bf16 v[56:59], v[164:167], v[192:195], v[56:59]
	v_mfma_f32_16x16x32_bf16 v[44:47], v[156:159], v[200:203], v[44:47]
	v_mfma_f32_16x16x32_bf16 v[40:43], v[164:167], v[200:203], v[40:43]
	v_mfma_f32_16x16x32_bf16 v[28:31], v[156:159], v[208:211], v[28:31]
	v_mfma_f32_16x16x32_bf16 v[24:27], v[164:167], v[208:211], v[24:27]
	v_mfma_f32_16x16x32_bf16 v[12:15], v[156:159], v[216:219], v[12:15]
	v_mfma_f32_16x16x32_bf16 v[8:11], v[164:167], v[216:219], v[8:11]
	s_setprio 0
	s_setprio 1
	v_mfma_f32_16x16x32_bf16 v[52:55], v[168:171], v[184:187], v[52:55]
	v_mfma_f32_16x16x32_bf16 v[48:51], v[176:179], v[184:187], v[48:51]
	v_mfma_f32_16x16x32_bf16 v[36:39], v[168:171], v[196:199], v[36:39]
	v_mfma_f32_16x16x32_bf16 v[32:35], v[176:179], v[196:199], v[32:35]
	v_mfma_f32_16x16x32_bf16 v[20:23], v[168:171], v[204:207], v[20:23]
	v_mfma_f32_16x16x32_bf16 v[16:19], v[176:179], v[204:207], v[16:19]
	v_mfma_f32_16x16x32_bf16 v[4:7], v[168:171], v[212:215], v[4:7]
	v_mfma_f32_16x16x32_bf16 v[0:3], v[176:179], v[212:215], v[0:3]
	v_mfma_f32_16x16x32_bf16 v[52:55], v[172:175], v[192:195], v[52:55]
	v_mfma_f32_16x16x32_bf16 v[48:51], v[180:183], v[192:195], v[48:51]
	v_mfma_f32_16x16x32_bf16 v[36:39], v[172:175], v[200:203], v[36:39]
	v_mfma_f32_16x16x32_bf16 v[32:35], v[180:183], v[200:203], v[32:35]
	v_mfma_f32_16x16x32_bf16 v[20:23], v[172:175], v[208:211], v[20:23]
	v_mfma_f32_16x16x32_bf16 v[16:19], v[180:183], v[208:211], v[16:19]
	v_mfma_f32_16x16x32_bf16 v[4:7], v[172:175], v[216:219], v[4:7]
	v_mfma_f32_16x16x32_bf16 v[0:3], v[180:183], v[216:219], v[0:3]
	s_barrier
	s_setprio 0
	s_add_i32 s55, 0, 0x18000
	v_add_u32_e32 v155, s55, v149
	s_add_i32 s56, 0, 0x1c000
	ds_read_b128 v[144:147], v155
	ds_read_b128 v[156:159], v155 offset:1024
	ds_read_b128 v[160:163], v155 offset:2048
	ds_read_b128 v[164:167], v155 offset:3072
	v_add_u32_e32 v155, s56, v149
	ds_read_b128 v[168:171], v155
	ds_read_b128 v[172:175], v155 offset:1024
	ds_read_b128 v[176:179], v155 offset:2048
	ds_read_b128 v[180:183], v155 offset:3072
	s_add_u32 s34, s34, 0x80000
	s_addc_u32 s35, s35, 0
	s_mov_b32 m0, s38
	v_lshl_add_u64 v[226:227], s[34:35], 0, v[128:129]
	ds_read_b128 v[184:187], v153 offset:32768
	ds_read_b128 v[192:195], v153 offset:33792
	ds_read_b128 v[196:199], v153 offset:34816
	ds_read_b128 v[200:203], v153 offset:35840
	ds_read_b128 v[204:207], v153 offset:36864
	ds_read_b128 v[208:211], v153 offset:37888
	ds_read_b128 v[212:215], v153 offset:38912
	ds_read_b128 v[216:219], v153 offset:39936
	global_load_lds_dwordx4 v[226:227], off
	v_lshl_add_u64 v[226:227], s[34:35], 0, v[132:133]
	s_mov_b32 m0, s39
	s_nop 0
	global_load_lds_dwordx4 v[226:227], off
	s_waitcnt vmcnt(8)
	s_waitcnt lgkmcnt(0)
	s_setprio 1
	s_barrier
	v_mfma_f32_16x16x32_bf16 v[124:127], v[144:147], v[184:187], v[124:127]
	v_mfma_f32_16x16x32_bf16 v[120:123], v[160:163], v[184:187], v[120:123]
	v_mfma_f32_16x16x32_bf16 v[108:111], v[144:147], v[196:199], v[108:111]
	v_mfma_f32_16x16x32_bf16 v[104:107], v[160:163], v[196:199], v[104:107]
	v_mfma_f32_16x16x32_bf16 v[92:95], v[144:147], v[204:207], v[92:95]
	v_mfma_f32_16x16x32_bf16 v[88:91], v[160:163], v[204:207], v[88:91]
	v_mfma_f32_16x16x32_bf16 v[76:79], v[144:147], v[212:215], v[76:79]
	v_mfma_f32_16x16x32_bf16 v[72:75], v[160:163], v[212:215], v[72:75]
	v_mfma_f32_16x16x32_bf16 v[124:127], v[156:159], v[192:195], v[124:127]
	v_mfma_f32_16x16x32_bf16 v[120:123], v[164:167], v[192:195], v[120:123]
	v_mfma_f32_16x16x32_bf16 v[108:111], v[156:159], v[200:203], v[108:111]
	v_mfma_f32_16x16x32_bf16 v[104:107], v[164:167], v[200:203], v[104:107]
	v_mfma_f32_16x16x32_bf16 v[92:95], v[156:159], v[208:211], v[92:95]
	v_mfma_f32_16x16x32_bf16 v[88:91], v[164:167], v[208:211], v[88:91]
	v_mfma_f32_16x16x32_bf16 v[76:79], v[156:159], v[216:219], v[76:79]
	v_mfma_f32_16x16x32_bf16 v[72:75], v[164:167], v[216:219], v[72:75]
	s_setprio 0
	s_setprio 1
	v_mfma_f32_16x16x32_bf16 v[116:119], v[168:171], v[184:187], v[116:119]
	v_mfma_f32_16x16x32_bf16 v[112:115], v[176:179], v[184:187], v[112:115]
	v_mfma_f32_16x16x32_bf16 v[100:103], v[168:171], v[196:199], v[100:103]
	v_mfma_f32_16x16x32_bf16 v[96:99], v[176:179], v[196:199], v[96:99]
	v_mfma_f32_16x16x32_bf16 v[84:87], v[168:171], v[204:207], v[84:87]
	v_mfma_f32_16x16x32_bf16 v[80:83], v[176:179], v[204:207], v[80:83]
	v_mfma_f32_16x16x32_bf16 v[68:71], v[168:171], v[212:215], v[68:71]
	v_mfma_f32_16x16x32_bf16 v[64:67], v[176:179], v[212:215], v[64:67]
	v_mfma_f32_16x16x32_bf16 v[116:119], v[172:175], v[192:195], v[116:119]
	v_mfma_f32_16x16x32_bf16 v[112:115], v[180:183], v[192:195], v[112:115]
	v_mfma_f32_16x16x32_bf16 v[100:103], v[172:175], v[200:203], v[100:103]
	v_mfma_f32_16x16x32_bf16 v[96:99], v[180:183], v[200:203], v[96:99]
	v_mfma_f32_16x16x32_bf16 v[84:87], v[172:175], v[208:211], v[84:87]
	v_mfma_f32_16x16x32_bf16 v[80:83], v[180:183], v[208:211], v[80:83]
	v_mfma_f32_16x16x32_bf16 v[68:71], v[172:175], v[216:219], v[68:71]
	v_mfma_f32_16x16x32_bf16 v[64:67], v[180:183], v[216:219], v[64:67]
	s_barrier
	s_setprio 0
	s_add_i32 s34, s55, s5
	v_lshl_add_u64 v[188:189], v[188:189], 0, s[10:11]
	s_mov_b32 m0, s34
	ds_read_b128 v[184:187], v153 offset:49152
	ds_read_b128 v[192:195], v153 offset:50176
	ds_read_b128 v[196:199], v153 offset:51200
	ds_read_b128 v[200:203], v153 offset:52224
	ds_read_b128 v[204:207], v153 offset:53248
	ds_read_b128 v[208:211], v153 offset:54272
	ds_read_b128 v[212:215], v153 offset:55296
	ds_read_b128 v[216:219], v153 offset:56320
	global_load_lds_dwordx4 v[188:189], off
	s_add_i32 m0, s34, 0x2000
	s_add_u32 s30, s30, 0x80080
	v_lshl_add_u64 v[188:189], v[220:221], 0, s[10:11]
	s_addc_u32 s31, s31, 0
	s_add_i32 s34, s56, s5
	global_load_lds_dwordx4 v[188:189], off
	v_lshl_add_u64 v[188:189], s[30:31], 0, v[130:131]
	s_mov_b32 m0, s34
	s_nop 0
	global_load_lds_dwordx4 v[188:189], off
	v_lshl_add_u64 v[188:189], s[30:31], 0, v[134:135]
	s_add_i32 m0, s34, 0x2000
	s_nop 0
	global_load_lds_dwordx4 v[188:189], off
	v_lshl_add_u64 v[188:189], v[222:223], 0, s[10:11]
	s_mov_b32 m0, s41
	s_nop 0
	global_load_lds_dwordx4 v[188:189], off
	v_lshl_add_u64 v[188:189], v[224:225], 0, s[10:11]
	s_mov_b32 m0, s42
	s_nop 0
	global_load_lds_dwordx4 v[188:189], off
	s_waitcnt vmcnt(8)
	s_waitcnt lgkmcnt(0)
	s_setprio 1
	s_barrier
	v_mfma_f32_16x16x32_bf16 v[60:63], v[144:147], v[184:187], v[60:63]
	v_mfma_f32_16x16x32_bf16 v[56:59], v[160:163], v[184:187], v[56:59]
	v_mfma_f32_16x16x32_bf16 v[44:47], v[144:147], v[196:199], v[44:47]
	v_mfma_f32_16x16x32_bf16 v[40:43], v[160:163], v[196:199], v[40:43]
	v_mfma_f32_16x16x32_bf16 v[28:31], v[144:147], v[204:207], v[28:31]
	v_mfma_f32_16x16x32_bf16 v[24:27], v[160:163], v[204:207], v[24:27]
	v_mfma_f32_16x16x32_bf16 v[12:15], v[144:147], v[212:215], v[12:15]
	v_mfma_f32_16x16x32_bf16 v[8:11], v[160:163], v[212:215], v[8:11]
	v_mfma_f32_16x16x32_bf16 v[60:63], v[156:159], v[192:195], v[60:63]
	v_mfma_f32_16x16x32_bf16 v[56:59], v[164:167], v[192:195], v[56:59]
	v_mfma_f32_16x16x32_bf16 v[44:47], v[156:159], v[200:203], v[44:47]
	v_mfma_f32_16x16x32_bf16 v[40:43], v[164:167], v[200:203], v[40:43]
	v_mfma_f32_16x16x32_bf16 v[28:31], v[156:159], v[208:211], v[28:31]
	v_mfma_f32_16x16x32_bf16 v[24:27], v[164:167], v[208:211], v[24:27]
	v_mfma_f32_16x16x32_bf16 v[12:15], v[156:159], v[216:219], v[12:15]
	v_mfma_f32_16x16x32_bf16 v[8:11], v[164:167], v[216:219], v[8:11]
	s_setprio 0
	s_setprio 1
	v_mfma_f32_16x16x32_bf16 v[52:55], v[168:171], v[184:187], v[52:55]
	v_mfma_f32_16x16x32_bf16 v[48:51], v[176:179], v[184:187], v[48:51]
	v_mfma_f32_16x16x32_bf16 v[36:39], v[168:171], v[196:199], v[36:39]
	v_mfma_f32_16x16x32_bf16 v[32:35], v[176:179], v[196:199], v[32:35]
	v_mfma_f32_16x16x32_bf16 v[20:23], v[168:171], v[204:207], v[20:23]
	v_mfma_f32_16x16x32_bf16 v[16:19], v[176:179], v[204:207], v[16:19]
	v_mfma_f32_16x16x32_bf16 v[4:7], v[168:171], v[212:215], v[4:7]
	v_mfma_f32_16x16x32_bf16 v[0:3], v[176:179], v[212:215], v[0:3]
	v_mfma_f32_16x16x32_bf16 v[52:55], v[172:175], v[192:195], v[52:55]
	v_mfma_f32_16x16x32_bf16 v[48:51], v[180:183], v[192:195], v[48:51]
	v_mfma_f32_16x16x32_bf16 v[36:39], v[172:175], v[200:203], v[36:39]
	v_mfma_f32_16x16x32_bf16 v[32:35], v[180:183], v[200:203], v[32:35]
	v_mfma_f32_16x16x32_bf16 v[20:23], v[172:175], v[208:211], v[20:23]
	v_mfma_f32_16x16x32_bf16 v[16:19], v[180:183], v[208:211], v[16:19]
	v_mfma_f32_16x16x32_bf16 v[4:7], v[172:175], v[216:219], v[4:7]
	v_mfma_f32_16x16x32_bf16 v[0:3], v[180:183], v[216:219], v[0:3]
	s_barrier
	s_setprio 0
	s_add_i32 s54, s54, 2
	s_add_u32 s28, s28, 0x100
	s_addc_u32 s29, s29, 0
	s_add_u32 s52, s52, 0x100
	s_addc_u32 s53, s53, 0
	s_cmp_gt_u32 s54, 29
	s_cbranch_scc0 .LBB0_799
	s_and_b64 vcc, exec, s[12:13]
	s_cbranch_vccz .LBB0_802
	s_barrier

.LBB0_934:
	ds_read_b128 v[170:173], v165
	ds_read_b128 v[174:177], v165 offset:1024
	ds_read_b128 v[178:181], v165 offset:2048
	ds_read_b128 v[182:185], v165 offset:3072
	ds_read_b128 v[186:189], v166
	ds_read_b128 v[192:195], v166 offset:1024
	ds_read_b128 v[196:199], v166 offset:2048
	ds_read_b128 v[200:203], v166 offset:3072
	s_add_u32 s40, s38, 0xfff80080
	s_addc_u32 s41, s39, -1
	s_cmp_eq_u32 s59, 28
	s_cselect_b32 s43, s13, s41
	s_cselect_b32 s42, s29, s40
	s_cselect_b32 s41, s27, s58
	s_cselect_b32 s40, s37, s57
	v_lshl_add_u64 v[144:145], s[38:39], 0, v[136:137]
	s_add_i32 m0, s5, 0xc000
	ds_read_b128 v[204:207], v167
	ds_read_b128 v[208:211], v167 offset:1024
	ds_read_b128 v[212:215], v167 offset:2048
	ds_read_b128 v[216:219], v167 offset:3072
	ds_read_b128 v[220:223], v167 offset:4096
	ds_read_b128 v[224:227], v167 offset:5120
	ds_read_b128 v[228:231], v167 offset:6144
	ds_read_b128 v[232:235], v167 offset:7168
	global_load_lds_dwordx4 v[144:145], off
	v_lshl_add_u64 v[144:145], s[38:39], 0, v[138:139]
	s_add_i32 m0, s5, 0xe000
	s_nop 0
	global_load_lds_dwordx4 v[144:145], off
	s_waitcnt vmcnt(8)
	s_waitcnt lgkmcnt(0)
	s_setprio 1
	s_barrier
	v_mfma_f32_16x16x32_bf16 v[124:127], v[170:173], v[204:207], v[124:127]
	v_mfma_f32_16x16x32_bf16 v[120:123], v[178:181], v[204:207], v[120:123]
	v_mfma_f32_16x16x32_bf16 v[108:111], v[170:173], v[212:215], v[108:111]
	v_mfma_f32_16x16x32_bf16 v[104:107], v[178:181], v[212:215], v[104:107]
	v_mfma_f32_16x16x32_bf16 v[92:95], v[170:173], v[220:223], v[92:95]
	v_mfma_f32_16x16x32_bf16 v[88:91], v[178:181], v[220:223], v[88:91]
	v_mfma_f32_16x16x32_bf16 v[76:79], v[170:173], v[228:231], v[76:79]
	v_mfma_f32_16x16x32_bf16 v[72:75], v[178:181], v[228:231], v[72:75]
	v_mfma_f32_16x16x32_bf16 v[124:127], v[174:177], v[208:211], v[124:127]
	v_mfma_f32_16x16x32_bf16 v[120:123], v[182:185], v[208:211], v[120:123]
	v_mfma_f32_16x16x32_bf16 v[108:111], v[174:177], v[216:219], v[108:111]
	v_mfma_f32_16x16x32_bf16 v[104:107], v[182:185], v[216:219], v[104:107]
	v_mfma_f32_16x16x32_bf16 v[92:95], v[174:177], v[224:227], v[92:95]
	v_mfma_f32_16x16x32_bf16 v[88:91], v[182:185], v[224:227], v[88:91]
	v_mfma_f32_16x16x32_bf16 v[76:79], v[174:177], v[232:235], v[76:79]
	v_mfma_f32_16x16x32_bf16 v[72:75], v[182:185], v[232:235], v[72:75]
	s_setprio 0
	s_setprio 1
	v_mfma_f32_16x16x32_bf16 v[116:119], v[186:189], v[204:207], v[116:119]
	v_mfma_f32_16x16x32_bf16 v[112:115], v[196:199], v[204:207], v[112:115]
	v_mfma_f32_16x16x32_bf16 v[100:103], v[186:189], v[212:215], v[100:103]
	v_mfma_f32_16x16x32_bf16 v[96:99], v[196:199], v[212:215], v[96:99]
	v_mfma_f32_16x16x32_bf16 v[84:87], v[186:189], v[220:223], v[84:87]
	v_mfma_f32_16x16x32_bf16 v[80:83], v[196:199], v[220:223], v[80:83]
	v_mfma_f32_16x16x32_bf16 v[68:71], v[186:189], v[228:231], v[68:71]
	v_mfma_f32_16x16x32_bf16 v[64:67], v[196:199], v[228:231], v[64:67]
	v_mfma_f32_16x16x32_bf16 v[116:119], v[192:195], v[208:211], v[116:119]
	v_mfma_f32_16x16x32_bf16 v[112:115], v[200:203], v[208:211], v[112:115]
	v_mfma_f32_16x16x32_bf16 v[100:103], v[192:195], v[216:219], v[100:103]
	v_mfma_f32_16x16x32_bf16 v[96:99], v[200:203], v[216:219], v[96:99]
	v_mfma_f32_16x16x32_bf16 v[84:87], v[192:195], v[224:227], v[84:87]
	v_mfma_f32_16x16x32_bf16 v[80:83], v[200:203], v[224:227], v[80:83]
	v_mfma_f32_16x16x32_bf16 v[68:71], v[192:195], v[232:235], v[68:71]
	v_mfma_f32_16x16x32_bf16 v[64:67], v[200:203], v[232:235], v[64:67]
	s_barrier
	s_setprio 0
	s_add_i32 s62, s55, s4
	v_lshl_add_u64 v[144:145], s[40:41], 0, v[130:131]
	s_mov_b32 m0, s62
	ds_read_b128 v[204:207], v167 offset:16384
	ds_read_b128 v[208:211], v167 offset:17408
	ds_read_b128 v[212:215], v167 offset:18432
	ds_read_b128 v[216:219], v167 offset:19456
	ds_read_b128 v[220:223], v167 offset:20480
	ds_read_b128 v[224:227], v167 offset:21504
	ds_read_b128 v[228:231], v167 offset:22528
	ds_read_b128 v[232:235], v167 offset:23552
	global_load_lds_dwordx4 v[144:145], off
	s_add_i32 m0, s62, 0x2000
	s_add_u32 s62, s40, 0x80000
	v_lshl_add_u64 v[236:237], s[40:41], 0, v[134:135]
	s_addc_u32 s63, s41, 0
	s_add_i32 s64, s56, s4
	global_load_lds_dwordx4 v[236:237], off
	v_lshl_add_u64 v[238:239], s[62:63], 0, v[130:131]
	s_mov_b32 m0, s64
	v_lshl_add_u64 v[240:241], s[42:43], 0, v[132:133]
	global_load_lds_dwordx4 v[238:239], off
	v_lshl_add_u64 v[238:239], s[62:63], 0, v[134:135]
	s_add_i32 m0, s64, 0x2000
	s_nop 0
	global_load_lds_dwordx4 v[238:239], off
	v_lshl_add_u64 v[238:239], s[42:43], 0, v[128:129]
	s_mov_b32 m0, s5
	s_nop 0
	global_load_lds_dwordx4 v[238:239], off
	s_mov_b32 m0, s44
	s_nop 0
	global_load_lds_dwordx4 v[240:241], off
	s_waitcnt vmcnt(8)
	s_waitcnt lgkmcnt(0)
	s_setprio 1
	s_barrier
	v_mfma_f32_16x16x32_bf16 v[60:63], v[170:173], v[204:207], v[60:63]
	v_mfma_f32_16x16x32_bf16 v[56:59], v[178:181], v[204:207], v[56:59]
	v_mfma_f32_16x16x32_bf16 v[44:47], v[170:173], v[212:215], v[44:47]
	v_mfma_f32_16x16x32_bf16 v[40:43], v[178:181], v[212:215], v[40:43]
	v_mfma_f32_16x16x32_bf16 v[28:31], v[170:173], v[220:223], v[28:31]
	v_mfma_f32_16x16x32_bf16 v[24:27], v[178:181], v[220:223], v[24:27]
	v_mfma_f32_16x16x32_bf16 v[12:15], v[170:173], v[228:231], v[12:15]
	v_mfma_f32_16x16x32_bf16 v[8:11], v[178:181], v[228:231], v[8:11]
	v_mfma_f32_16x16x32_bf16 v[60:63], v[174:177], v[208:211], v[60:63]
	v_mfma_f32_16x16x32_bf16 v[56:59], v[182:185], v[208:211], v[56:59]
	v_mfma_f32_16x16x32_bf16 v[44:47], v[174:177], v[216:219], v[44:47]
	v_mfma_f32_16x16x32_bf16 v[40:43], v[182:185], v[216:219], v[40:43]
	v_mfma_f32_16x16x32_bf16 v[28:31], v[174:177], v[224:227], v[28:31]
	v_mfma_f32_16x16x32_bf16 v[24:27], v[182:185], v[224:227], v[24:27]
	v_mfma_f32_16x16x32_bf16 v[12:15], v[174:177], v[232:235], v[12:15]
	v_mfma_f32_16x16x32_bf16 v[8:11], v[182:185], v[232:235], v[8:11]
	s_setprio 0
	s_setprio 1
	v_mfma_f32_16x16x32_bf16 v[52:55], v[186:189], v[204:207], v[52:55]
	v_mfma_f32_16x16x32_bf16 v[48:51], v[196:199], v[204:207], v[48:51]
	v_mfma_f32_16x16x32_bf16 v[36:39], v[186:189], v[212:215], v[36:39]
	v_mfma_f32_16x16x32_bf16 v[32:35], v[196:199], v[212:215], v[32:35]
	v_mfma_f32_16x16x32_bf16 v[20:23], v[186:189], v[220:223], v[20:23]
	v_mfma_f32_16x16x32_bf16 v[16:19], v[196:199], v[220:223], v[16:19]
	v_mfma_f32_16x16x32_bf16 v[4:7], v[186:189], v[228:231], v[4:7]
	v_mfma_f32_16x16x32_bf16 v[0:3], v[196:199], v[228:231], v[0:3]
	v_mfma_f32_16x16x32_bf16 v[52:55], v[192:195], v[208:211], v[52:55]
	v_mfma_f32_16x16x32_bf16 v[48:51], v[200:203], v[208:211], v[48:51]
	v_mfma_f32_16x16x32_bf16 v[36:39], v[192:195], v[216:219], v[36:39]
	v_mfma_f32_16x16x32_bf16 v[32:35], v[200:203], v[216:219], v[32:35]
	v_mfma_f32_16x16x32_bf16 v[20:23], v[192:195], v[224:227], v[20:23]
	v_mfma_f32_16x16x32_bf16 v[16:19], v[200:203], v[224:227], v[16:19]
	v_mfma_f32_16x16x32_bf16 v[4:7], v[192:195], v[232:235], v[4:7]
	v_mfma_f32_16x16x32_bf16 v[0:3], v[200:203], v[232:235], v[0:3]
	s_barrier
	s_setprio 0
	s_add_i32 s62, 0, 0x18000
	s_add_i32 s63, 0, 0x1c000
	v_add_u32_e32 v182, s62, v147
	v_add_u32_e32 v200, s63, v147
	ds_read_b128 v[170:173], v182
	ds_read_b128 v[174:177], v182 offset:1024
	ds_read_b128 v[178:181], v182 offset:2048
	ds_read_b128 v[182:185], v182 offset:3072
	ds_read_b128 v[186:189], v200
	ds_read_b128 v[192:195], v200 offset:1024
	ds_read_b128 v[196:199], v200 offset:2048
	ds_read_b128 v[200:203], v200 offset:3072
	s_add_u32 s42, s42, 0x80000
	s_addc_u32 s43, s43, 0
	s_mov_b32 m0, s45
	v_lshl_add_u64 v[242:243], s[42:43], 0, v[128:129]
	ds_read_b128 v[204:207], v167 offset:32768
	ds_read_b128 v[208:211], v167 offset:33792
	ds_read_b128 v[212:215], v167 offset:34816
	ds_read_b128 v[216:219], v167 offset:35840
	ds_read_b128 v[220:223], v167 offset:36864
	ds_read_b128 v[224:227], v167 offset:37888
	ds_read_b128 v[228:231], v167 offset:38912
	ds_read_b128 v[232:235], v167 offset:39936
	global_load_lds_dwordx4 v[242:243], off
	v_lshl_add_u64 v[242:243], s[42:43], 0, v[132:133]
	s_mov_b32 m0, s46
	s_nop 0
	global_load_lds_dwordx4 v[242:243], off
	s_waitcnt vmcnt(8)
	s_waitcnt lgkmcnt(0)
	s_setprio 1
	s_barrier
	v_mfma_f32_16x16x32_bf16 v[124:127], v[170:173], v[204:207], v[124:127]
	v_mfma_f32_16x16x32_bf16 v[120:123], v[178:181], v[204:207], v[120:123]
	v_mfma_f32_16x16x32_bf16 v[108:111], v[170:173], v[212:215], v[108:111]
	v_mfma_f32_16x16x32_bf16 v[104:107], v[178:181], v[212:215], v[104:107]
	v_mfma_f32_16x16x32_bf16 v[92:95], v[170:173], v[220:223], v[92:95]
	v_mfma_f32_16x16x32_bf16 v[88:91], v[178:181], v[220:223], v[88:91]
	v_mfma_f32_16x16x32_bf16 v[76:79], v[170:173], v[228:231], v[76:79]
	v_mfma_f32_16x16x32_bf16 v[72:75], v[178:181], v[228:231], v[72:75]
	v_mfma_f32_16x16x32_bf16 v[124:127], v[174:177], v[208:211], v[124:127]
	v_mfma_f32_16x16x32_bf16 v[120:123], v[182:185], v[208:211], v[120:123]
	v_mfma_f32_16x16x32_bf16 v[108:111], v[174:177], v[216:219], v[108:111]
	v_mfma_f32_16x16x32_bf16 v[104:107], v[182:185], v[216:219], v[104:107]
	v_mfma_f32_16x16x32_bf16 v[92:95], v[174:177], v[224:227], v[92:95]
	v_mfma_f32_16x16x32_bf16 v[88:91], v[182:185], v[224:227], v[88:91]
	v_mfma_f32_16x16x32_bf16 v[76:79], v[174:177], v[232:235], v[76:79]
	v_mfma_f32_16x16x32_bf16 v[72:75], v[182:185], v[232:235], v[72:75]
	s_setprio 0
	s_setprio 1
	v_mfma_f32_16x16x32_bf16 v[116:119], v[186:189], v[204:207], v[116:119]
	v_mfma_f32_16x16x32_bf16 v[112:115], v[196:199], v[204:207], v[112:115]
	v_mfma_f32_16x16x32_bf16 v[100:103], v[186:189], v[212:215], v[100:103]
	v_mfma_f32_16x16x32_bf16 v[96:99], v[196:199], v[212:215], v[96:99]
	v_mfma_f32_16x16x32_bf16 v[84:87], v[186:189], v[220:223], v[84:87]
	v_mfma_f32_16x16x32_bf16 v[80:83], v[196:199], v[220:223], v[80:83]
	v_mfma_f32_16x16x32_bf16 v[68:71], v[186:189], v[228:231], v[68:71]
	v_mfma_f32_16x16x32_bf16 v[64:67], v[196:199], v[228:231], v[64:67]
	v_mfma_f32_16x16x32_bf16 v[116:119], v[192:195], v[208:211], v[116:119]
	v_mfma_f32_16x16x32_bf16 v[112:115], v[200:203], v[208:211], v[112:115]
	v_mfma_f32_16x16x32_bf16 v[100:103], v[192:195], v[216:219], v[100:103]
	v_mfma_f32_16x16x32_bf16 v[96:99], v[200:203], v[216:219], v[96:99]
	v_mfma_f32_16x16x32_bf16 v[84:87], v[192:195], v[224:227], v[84:87]
	v_mfma_f32_16x16x32_bf16 v[80:83], v[200:203], v[224:227], v[80:83]
	v_mfma_f32_16x16x32_bf16 v[68:71], v[192:195], v[232:235], v[68:71]
	v_mfma_f32_16x16x32_bf16 v[64:67], v[200:203], v[232:235], v[64:67]
	s_barrier
	s_setprio 0
	s_add_i32 s42, s62, s4
	v_lshl_add_u64 v[144:145], v[144:145], 0, s[16:17]
	s_mov_b32 m0, s42
	ds_read_b128 v[204:207], v167 offset:49152
	ds_read_b128 v[208:211], v167 offset:50176
	ds_read_b128 v[212:215], v167 offset:51200
	ds_read_b128 v[216:219], v167 offset:52224
	ds_read_b128 v[220:223], v167 offset:53248
	ds_read_b128 v[224:227], v167 offset:54272
	ds_read_b128 v[228:231], v167 offset:55296
	ds_read_b128 v[232:235], v167 offset:56320
	global_load_lds_dwordx4 v[144:145], off
	s_add_i32 m0, s42, 0x2000
	s_add_u32 s40, s40, 0x80080
	v_lshl_add_u64 v[144:145], v[236:237], 0, s[16:17]
	s_addc_u32 s41, s41, 0
	s_add_i32 s42, s63, s4
	global_load_lds_dwordx4 v[144:145], off
	v_lshl_add_u64 v[144:145], s[40:41], 0, v[130:131]
	s_mov_b32 m0, s42
	s_nop 0
	global_load_lds_dwordx4 v[144:145], off
	v_lshl_add_u64 v[144:145], s[40:41], 0, v[134:135]
	s_add_i32 m0, s42, 0x2000
	s_nop 0
	global_load_lds_dwordx4 v[144:145], off
	v_lshl_add_u64 v[144:145], v[238:239], 0, s[16:17]
	s_mov_b32 m0, s48
	s_nop 0
	global_load_lds_dwordx4 v[144:145], off
	v_lshl_add_u64 v[144:145], v[240:241], 0, s[16:17]
	s_mov_b32 m0, s49
	s_nop 0
	global_load_lds_dwordx4 v[144:145], off
	s_waitcnt vmcnt(8)
	s_waitcnt lgkmcnt(0)
	s_setprio 1
	s_barrier
	v_mfma_f32_16x16x32_bf16 v[60:63], v[170:173], v[204:207], v[60:63]
	v_mfma_f32_16x16x32_bf16 v[56:59], v[178:181], v[204:207], v[56:59]
	v_mfma_f32_16x16x32_bf16 v[44:47], v[170:173], v[212:215], v[44:47]
	v_mfma_f32_16x16x32_bf16 v[40:43], v[178:181], v[212:215], v[40:43]
	v_mfma_f32_16x16x32_bf16 v[28:31], v[170:173], v[220:223], v[28:31]
	v_mfma_f32_16x16x32_bf16 v[24:27], v[178:181], v[220:223], v[24:27]
	v_mfma_f32_16x16x32_bf16 v[12:15], v[170:173], v[228:231], v[12:15]
	v_mfma_f32_16x16x32_bf16 v[8:11], v[178:181], v[228:231], v[8:11]
	v_mfma_f32_16x16x32_bf16 v[60:63], v[174:177], v[208:211], v[60:63]
	v_mfma_f32_16x16x32_bf16 v[56:59], v[182:185], v[208:211], v[56:59]
	v_mfma_f32_16x16x32_bf16 v[44:47], v[174:177], v[216:219], v[44:47]
	v_mfma_f32_16x16x32_bf16 v[40:43], v[182:185], v[216:219], v[40:43]
	v_mfma_f32_16x16x32_bf16 v[28:31], v[174:177], v[224:227], v[28:31]
	v_mfma_f32_16x16x32_bf16 v[24:27], v[182:185], v[224:227], v[24:27]
	v_mfma_f32_16x16x32_bf16 v[12:15], v[174:177], v[232:235], v[12:15]
	v_mfma_f32_16x16x32_bf16 v[8:11], v[182:185], v[232:235], v[8:11]
	s_setprio 0
	s_setprio 1
	v_mfma_f32_16x16x32_bf16 v[52:55], v[186:189], v[204:207], v[52:55]
	v_mfma_f32_16x16x32_bf16 v[48:51], v[196:199], v[204:207], v[48:51]
	v_mfma_f32_16x16x32_bf16 v[36:39], v[186:189], v[212:215], v[36:39]
	v_mfma_f32_16x16x32_bf16 v[32:35], v[196:199], v[212:215], v[32:35]
	v_mfma_f32_16x16x32_bf16 v[20:23], v[186:189], v[220:223], v[20:23]
	v_mfma_f32_16x16x32_bf16 v[16:19], v[196:199], v[220:223], v[16:19]
	v_mfma_f32_16x16x32_bf16 v[4:7], v[186:189], v[228:231], v[4:7]
	v_mfma_f32_16x16x32_bf16 v[0:3], v[196:199], v[228:231], v[0:3]
	v_mfma_f32_16x16x32_bf16 v[52:55], v[192:195], v[208:211], v[52:55]
	v_mfma_f32_16x16x32_bf16 v[48:51], v[200:203], v[208:211], v[48:51]
	v_mfma_f32_16x16x32_bf16 v[36:39], v[192:195], v[216:219], v[36:39]
	v_mfma_f32_16x16x32_bf16 v[32:35], v[200:203], v[216:219], v[32:35]
	v_mfma_f32_16x16x32_bf16 v[20:23], v[192:195], v[224:227], v[20:23]
	v_mfma_f32_16x16x32_bf16 v[16:19], v[200:203], v[224:227], v[16:19]
	v_mfma_f32_16x16x32_bf16 v[4:7], v[192:195], v[232:235], v[4:7]
	v_mfma_f32_16x16x32_bf16 v[0:3], v[200:203], v[232:235], v[0:3]
	s_barrier
	s_setprio 0
	s_add_i32 s59, s59, 2
	s_add_u32 s38, s38, 0x100
	s_addc_u32 s39, s39, 0
	s_add_u32 s57, s57, 0x100
	s_addc_u32 s58, s58, 0
	s_cmp_gt_u32 s59, 29
	s_cbranch_scc0 .LBB0_934
	s_and_b64 vcc, exec, s[24:25]
	s_cbranch_vccz .LBB0_937
	s_barrier

.LBB0_1020:
	ds_read_b128 v[144:147], v153
	ds_read_b128 v[158:161], v153 offset:1024
	ds_read_b128 v[162:165], v153 offset:2048
	ds_read_b128 v[166:169], v153 offset:3072
	ds_read_b128 v[170:173], v154
	ds_read_b128 v[174:177], v154 offset:1024
	ds_read_b128 v[178:181], v154 offset:2048
	ds_read_b128 v[182:185], v154 offset:3072
	s_add_u32 s38, s36, 0xfff80080
	s_addc_u32 s39, s37, -1
	s_cmp_eq_u32 s64, 28
	s_cselect_b32 s41, s27, s39
	s_cselect_b32 s40, s58, s38
	s_cselect_b32 s39, s17, s63
	s_cselect_b32 s38, s59, s62
	v_lshl_add_u64 v[148:149], s[36:37], 0, v[136:137]
	s_add_i32 m0, s43, 0xc000
	ds_read_b128 v[186:189], v155
	ds_read_b128 v[192:195], v155 offset:1024
	ds_read_b128 v[196:199], v155 offset:2048
	ds_read_b128 v[200:203], v155 offset:3072
	ds_read_b128 v[204:207], v155 offset:4096
	ds_read_b128 v[208:211], v155 offset:5120
	ds_read_b128 v[212:215], v155 offset:6144
	ds_read_b128 v[216:219], v155 offset:7168
	global_load_lds_dwordx4 v[148:149], off
	v_lshl_add_u64 v[148:149], s[36:37], 0, v[138:139]
	s_add_i32 m0, s43, 0xe000
	s_nop 0
	global_load_lds_dwordx4 v[148:149], off
	s_waitcnt vmcnt(8)
	s_waitcnt lgkmcnt(0)
	s_setprio 1
	s_barrier
	v_mfma_f32_16x16x32_bf16 v[124:127], v[144:147], v[186:189], v[124:127]
	v_mfma_f32_16x16x32_bf16 v[120:123], v[162:165], v[186:189], v[120:123]
	v_mfma_f32_16x16x32_bf16 v[108:111], v[144:147], v[196:199], v[108:111]
	v_mfma_f32_16x16x32_bf16 v[104:107], v[162:165], v[196:199], v[104:107]
	v_mfma_f32_16x16x32_bf16 v[92:95], v[144:147], v[204:207], v[92:95]
	v_mfma_f32_16x16x32_bf16 v[88:91], v[162:165], v[204:207], v[88:91]
	v_mfma_f32_16x16x32_bf16 v[76:79], v[144:147], v[212:215], v[76:79]
	v_mfma_f32_16x16x32_bf16 v[72:75], v[162:165], v[212:215], v[72:75]
	v_mfma_f32_16x16x32_bf16 v[124:127], v[158:161], v[192:195], v[124:127]
	v_mfma_f32_16x16x32_bf16 v[120:123], v[166:169], v[192:195], v[120:123]
	v_mfma_f32_16x16x32_bf16 v[108:111], v[158:161], v[200:203], v[108:111]
	v_mfma_f32_16x16x32_bf16 v[104:107], v[166:169], v[200:203], v[104:107]
	v_mfma_f32_16x16x32_bf16 v[92:95], v[158:161], v[208:211], v[92:95]
	v_mfma_f32_16x16x32_bf16 v[88:91], v[166:169], v[208:211], v[88:91]
	v_mfma_f32_16x16x32_bf16 v[76:79], v[158:161], v[216:219], v[76:79]
	v_mfma_f32_16x16x32_bf16 v[72:75], v[166:169], v[216:219], v[72:75]
	s_setprio 0
	s_setprio 1
	v_mfma_f32_16x16x32_bf16 v[116:119], v[170:173], v[186:189], v[116:119]
	v_mfma_f32_16x16x32_bf16 v[112:115], v[178:181], v[186:189], v[112:115]
	v_mfma_f32_16x16x32_bf16 v[100:103], v[170:173], v[196:199], v[100:103]
	v_mfma_f32_16x16x32_bf16 v[96:99], v[178:181], v[196:199], v[96:99]
	v_mfma_f32_16x16x32_bf16 v[84:87], v[170:173], v[204:207], v[84:87]
	v_mfma_f32_16x16x32_bf16 v[80:83], v[178:181], v[204:207], v[80:83]
	v_mfma_f32_16x16x32_bf16 v[68:71], v[170:173], v[212:215], v[68:71]
	v_mfma_f32_16x16x32_bf16 v[64:67], v[178:181], v[212:215], v[64:67]
	v_mfma_f32_16x16x32_bf16 v[116:119], v[174:177], v[192:195], v[116:119]
	v_mfma_f32_16x16x32_bf16 v[112:115], v[182:185], v[192:195], v[112:115]
	v_mfma_f32_16x16x32_bf16 v[100:103], v[174:177], v[200:203], v[100:103]
	v_mfma_f32_16x16x32_bf16 v[96:99], v[182:185], v[200:203], v[96:99]
	v_mfma_f32_16x16x32_bf16 v[84:87], v[174:177], v[208:211], v[84:87]
	v_mfma_f32_16x16x32_bf16 v[80:83], v[182:185], v[208:211], v[80:83]
	v_mfma_f32_16x16x32_bf16 v[68:71], v[174:177], v[216:219], v[68:71]
	v_mfma_f32_16x16x32_bf16 v[64:67], v[182:185], v[216:219], v[64:67]
	s_barrier
	s_setprio 0
	s_add_i32 s65, s54, s4
	v_lshl_add_u64 v[148:149], s[38:39], 0, v[132:133]
	s_mov_b32 m0, s65
	ds_read_b128 v[186:189], v155 offset:16384
	ds_read_b128 v[192:195], v155 offset:17408
	ds_read_b128 v[196:199], v155 offset:18432
	ds_read_b128 v[200:203], v155 offset:19456
	ds_read_b128 v[204:207], v155 offset:20480
	ds_read_b128 v[208:211], v155 offset:21504
	ds_read_b128 v[212:215], v155 offset:22528
	ds_read_b128 v[216:219], v155 offset:23552
	global_load_lds_dwordx4 v[148:149], off
	s_add_i32 m0, s65, 0x2000
	s_add_u32 s66, s38, 0x80000
	v_lshl_add_u64 v[220:221], s[38:39], 0, v[128:129]
	s_addc_u32 s67, s39, 0
	s_add_i32 s65, s55, s4
	global_load_lds_dwordx4 v[220:221], off
	v_lshl_add_u64 v[222:223], s[66:67], 0, v[132:133]
	s_mov_b32 m0, s65
	v_lshl_add_u64 v[224:225], s[40:41], 0, v[130:131]
	global_load_lds_dwordx4 v[222:223], off
	v_lshl_add_u64 v[222:223], s[66:67], 0, v[128:129]
	s_add_i32 m0, s65, 0x2000
	s_nop 0
	global_load_lds_dwordx4 v[222:223], off
	v_lshl_add_u64 v[222:223], s[40:41], 0, v[134:135]
	s_mov_b32 m0, s43
	s_nop 0
	global_load_lds_dwordx4 v[222:223], off
	s_mov_b32 m0, s44
	s_nop 0
	global_load_lds_dwordx4 v[224:225], off
	s_waitcnt vmcnt(8)
	s_waitcnt lgkmcnt(0)
	s_setprio 1
	s_barrier
	v_mfma_f32_16x16x32_bf16 v[60:63], v[144:147], v[186:189], v[60:63]
	v_mfma_f32_16x16x32_bf16 v[56:59], v[162:165], v[186:189], v[56:59]
	v_mfma_f32_16x16x32_bf16 v[44:47], v[144:147], v[196:199], v[44:47]
	v_mfma_f32_16x16x32_bf16 v[40:43], v[162:165], v[196:199], v[40:43]
	v_mfma_f32_16x16x32_bf16 v[28:31], v[144:147], v[204:207], v[28:31]
	v_mfma_f32_16x16x32_bf16 v[24:27], v[162:165], v[204:207], v[24:27]
	v_mfma_f32_16x16x32_bf16 v[12:15], v[144:147], v[212:215], v[12:15]
	v_mfma_f32_16x16x32_bf16 v[8:11], v[162:165], v[212:215], v[8:11]
	v_mfma_f32_16x16x32_bf16 v[60:63], v[158:161], v[192:195], v[60:63]
	v_mfma_f32_16x16x32_bf16 v[56:59], v[166:169], v[192:195], v[56:59]
	v_mfma_f32_16x16x32_bf16 v[44:47], v[158:161], v[200:203], v[44:47]
	v_mfma_f32_16x16x32_bf16 v[40:43], v[166:169], v[200:203], v[40:43]
	v_mfma_f32_16x16x32_bf16 v[28:31], v[158:161], v[208:211], v[28:31]
	v_mfma_f32_16x16x32_bf16 v[24:27], v[166:169], v[208:211], v[24:27]
	v_mfma_f32_16x16x32_bf16 v[12:15], v[158:161], v[216:219], v[12:15]
	v_mfma_f32_16x16x32_bf16 v[8:11], v[166:169], v[216:219], v[8:11]
	s_setprio 0
	s_setprio 1
	v_mfma_f32_16x16x32_bf16 v[52:55], v[170:173], v[186:189], v[52:55]
	v_mfma_f32_16x16x32_bf16 v[48:51], v[178:181], v[186:189], v[48:51]
	v_mfma_f32_16x16x32_bf16 v[36:39], v[170:173], v[196:199], v[36:39]
	v_mfma_f32_16x16x32_bf16 v[32:35], v[178:181], v[196:199], v[32:35]
	v_mfma_f32_16x16x32_bf16 v[20:23], v[170:173], v[204:207], v[20:23]
	v_mfma_f32_16x16x32_bf16 v[16:19], v[178:181], v[204:207], v[16:19]
	v_mfma_f32_16x16x32_bf16 v[4:7], v[170:173], v[212:215], v[4:7]
	v_mfma_f32_16x16x32_bf16 v[0:3], v[178:181], v[212:215], v[0:3]
	v_mfma_f32_16x16x32_bf16 v[52:55], v[174:177], v[192:195], v[52:55]
	v_mfma_f32_16x16x32_bf16 v[48:51], v[182:185], v[192:195], v[48:51]
	v_mfma_f32_16x16x32_bf16 v[36:39], v[174:177], v[200:203], v[36:39]
	v_mfma_f32_16x16x32_bf16 v[32:35], v[182:185], v[200:203], v[32:35]
	v_mfma_f32_16x16x32_bf16 v[20:23], v[174:177], v[208:211], v[20:23]
	v_mfma_f32_16x16x32_bf16 v[16:19], v[182:185], v[208:211], v[16:19]
	v_mfma_f32_16x16x32_bf16 v[4:7], v[174:177], v[216:219], v[4:7]
	v_mfma_f32_16x16x32_bf16 v[0:3], v[182:185], v[216:219], v[0:3]
	s_barrier
	s_setprio 0
	s_add_i32 s65, 0, 0x18000
	v_add_u32_e32 v157, s65, v151
	s_add_i32 s66, 0, 0x1c000
	ds_read_b128 v[144:147], v157
	ds_read_b128 v[158:161], v157 offset:1024
	ds_read_b128 v[162:165], v157 offset:2048
	ds_read_b128 v[166:169], v157 offset:3072
	v_add_u32_e32 v157, s66, v151
	ds_read_b128 v[170:173], v157
	ds_read_b128 v[174:177], v157 offset:1024
	ds_read_b128 v[178:181], v157 offset:2048
	ds_read_b128 v[182:185], v157 offset:3072
	s_add_u32 s40, s40, 0x80000
	s_addc_u32 s41, s41, 0
	s_mov_b32 m0, s45
	v_lshl_add_u64 v[226:227], s[40:41], 0, v[134:135]
	ds_read_b128 v[186:189], v155 offset:32768
	ds_read_b128 v[192:195], v155 offset:33792
	ds_read_b128 v[196:199], v155 offset:34816
	ds_read_b128 v[200:203], v155 offset:35840
	ds_read_b128 v[204:207], v155 offset:36864
	ds_read_b128 v[208:211], v155 offset:37888
	ds_read_b128 v[212:215], v155 offset:38912
	ds_read_b128 v[216:219], v155 offset:39936
	global_load_lds_dwordx4 v[226:227], off
	v_lshl_add_u64 v[226:227], s[40:41], 0, v[130:131]
	s_mov_b32 m0, s46
	s_nop 0
	global_load_lds_dwordx4 v[226:227], off
	s_waitcnt vmcnt(8)
	s_waitcnt lgkmcnt(0)
	s_setprio 1
	s_barrier
	v_mfma_f32_16x16x32_bf16 v[124:127], v[144:147], v[186:189], v[124:127]
	v_mfma_f32_16x16x32_bf16 v[120:123], v[162:165], v[186:189], v[120:123]
	v_mfma_f32_16x16x32_bf16 v[108:111], v[144:147], v[196:199], v[108:111]
	v_mfma_f32_16x16x32_bf16 v[104:107], v[162:165], v[196:199], v[104:107]
	v_mfma_f32_16x16x32_bf16 v[92:95], v[144:147], v[204:207], v[92:95]
	v_mfma_f32_16x16x32_bf16 v[88:91], v[162:165], v[204:207], v[88:91]
	v_mfma_f32_16x16x32_bf16 v[76:79], v[144:147], v[212:215], v[76:79]
	v_mfma_f32_16x16x32_bf16 v[72:75], v[162:165], v[212:215], v[72:75]
	v_mfma_f32_16x16x32_bf16 v[124:127], v[158:161], v[192:195], v[124:127]
	v_mfma_f32_16x16x32_bf16 v[120:123], v[166:169], v[192:195], v[120:123]
	v_mfma_f32_16x16x32_bf16 v[108:111], v[158:161], v[200:203], v[108:111]
	v_mfma_f32_16x16x32_bf16 v[104:107], v[166:169], v[200:203], v[104:107]
	v_mfma_f32_16x16x32_bf16 v[92:95], v[158:161], v[208:211], v[92:95]
	v_mfma_f32_16x16x32_bf16 v[88:91], v[166:169], v[208:211], v[88:91]
	v_mfma_f32_16x16x32_bf16 v[76:79], v[158:161], v[216:219], v[76:79]
	v_mfma_f32_16x16x32_bf16 v[72:75], v[166:169], v[216:219], v[72:75]
	s_setprio 0
	s_setprio 1
	v_mfma_f32_16x16x32_bf16 v[116:119], v[170:173], v[186:189], v[116:119]
	v_mfma_f32_16x16x32_bf16 v[112:115], v[178:181], v[186:189], v[112:115]
	v_mfma_f32_16x16x32_bf16 v[100:103], v[170:173], v[196:199], v[100:103]
	v_mfma_f32_16x16x32_bf16 v[96:99], v[178:181], v[196:199], v[96:99]
	v_mfma_f32_16x16x32_bf16 v[84:87], v[170:173], v[204:207], v[84:87]
	v_mfma_f32_16x16x32_bf16 v[80:83], v[178:181], v[204:207], v[80:83]
	v_mfma_f32_16x16x32_bf16 v[68:71], v[170:173], v[212:215], v[68:71]
	v_mfma_f32_16x16x32_bf16 v[64:67], v[178:181], v[212:215], v[64:67]
	v_mfma_f32_16x16x32_bf16 v[116:119], v[174:177], v[192:195], v[116:119]
	v_mfma_f32_16x16x32_bf16 v[112:115], v[182:185], v[192:195], v[112:115]
	v_mfma_f32_16x16x32_bf16 v[100:103], v[174:177], v[200:203], v[100:103]
	v_mfma_f32_16x16x32_bf16 v[96:99], v[182:185], v[200:203], v[96:99]
	v_mfma_f32_16x16x32_bf16 v[84:87], v[174:177], v[208:211], v[84:87]
	v_mfma_f32_16x16x32_bf16 v[80:83], v[182:185], v[208:211], v[80:83]
	v_mfma_f32_16x16x32_bf16 v[68:71], v[174:177], v[216:219], v[68:71]
	v_mfma_f32_16x16x32_bf16 v[64:67], v[182:185], v[216:219], v[64:67]
	s_barrier
	s_setprio 0
	s_add_i32 s40, s65, s4
	v_lshl_add_u64 v[148:149], v[148:149], 0, s[12:13]
	s_mov_b32 m0, s40
	ds_read_b128 v[186:189], v155 offset:49152
	ds_read_b128 v[192:195], v155 offset:50176
	ds_read_b128 v[196:199], v155 offset:51200
	ds_read_b128 v[200:203], v155 offset:52224
	ds_read_b128 v[204:207], v155 offset:53248
	ds_read_b128 v[208:211], v155 offset:54272
	ds_read_b128 v[212:215], v155 offset:55296
	ds_read_b128 v[216:219], v155 offset:56320
	global_load_lds_dwordx4 v[148:149], off
	s_add_i32 m0, s40, 0x2000
	s_add_u32 s38, s38, 0x80080
	v_lshl_add_u64 v[148:149], v[220:221], 0, s[12:13]
	s_addc_u32 s39, s39, 0
	s_add_i32 s40, s66, s4
	global_load_lds_dwordx4 v[148:149], off
	v_lshl_add_u64 v[148:149], s[38:39], 0, v[132:133]
	s_mov_b32 m0, s40
	s_nop 0
	global_load_lds_dwordx4 v[148:149], off
	v_lshl_add_u64 v[148:149], s[38:39], 0, v[128:129]
	s_add_i32 m0, s40, 0x2000
	s_nop 0
	global_load_lds_dwordx4 v[148:149], off
	v_lshl_add_u64 v[148:149], v[222:223], 0, s[12:13]
	s_mov_b32 m0, s48
	s_nop 0
	global_load_lds_dwordx4 v[148:149], off
	v_lshl_add_u64 v[148:149], v[224:225], 0, s[12:13]
	s_mov_b32 m0, s49
	s_nop 0
	global_load_lds_dwordx4 v[148:149], off
	s_waitcnt vmcnt(8)
	s_waitcnt lgkmcnt(0)
	s_setprio 1
	s_barrier
	v_mfma_f32_16x16x32_bf16 v[60:63], v[144:147], v[186:189], v[60:63]
	v_mfma_f32_16x16x32_bf16 v[56:59], v[162:165], v[186:189], v[56:59]
	v_mfma_f32_16x16x32_bf16 v[44:47], v[144:147], v[196:199], v[44:47]
	v_mfma_f32_16x16x32_bf16 v[40:43], v[162:165], v[196:199], v[40:43]
	v_mfma_f32_16x16x32_bf16 v[28:31], v[144:147], v[204:207], v[28:31]
	v_mfma_f32_16x16x32_bf16 v[24:27], v[162:165], v[204:207], v[24:27]
	v_mfma_f32_16x16x32_bf16 v[12:15], v[144:147], v[212:215], v[12:15]
	v_mfma_f32_16x16x32_bf16 v[8:11], v[162:165], v[212:215], v[8:11]
	v_mfma_f32_16x16x32_bf16 v[60:63], v[158:161], v[192:195], v[60:63]
	v_mfma_f32_16x16x32_bf16 v[56:59], v[166:169], v[192:195], v[56:59]
	v_mfma_f32_16x16x32_bf16 v[44:47], v[158:161], v[200:203], v[44:47]
	v_mfma_f32_16x16x32_bf16 v[40:43], v[166:169], v[200:203], v[40:43]
	v_mfma_f32_16x16x32_bf16 v[28:31], v[158:161], v[208:211], v[28:31]
	v_mfma_f32_16x16x32_bf16 v[24:27], v[166:169], v[208:211], v[24:27]
	v_mfma_f32_16x16x32_bf16 v[12:15], v[158:161], v[216:219], v[12:15]
	v_mfma_f32_16x16x32_bf16 v[8:11], v[166:169], v[216:219], v[8:11]
	s_setprio 0
	s_setprio 1
	v_mfma_f32_16x16x32_bf16 v[52:55], v[170:173], v[186:189], v[52:55]
	v_mfma_f32_16x16x32_bf16 v[48:51], v[178:181], v[186:189], v[48:51]
	v_mfma_f32_16x16x32_bf16 v[36:39], v[170:173], v[196:199], v[36:39]
	v_mfma_f32_16x16x32_bf16 v[32:35], v[178:181], v[196:199], v[32:35]
	v_mfma_f32_16x16x32_bf16 v[20:23], v[170:173], v[204:207], v[20:23]
	v_mfma_f32_16x16x32_bf16 v[16:19], v[178:181], v[204:207], v[16:19]
	v_mfma_f32_16x16x32_bf16 v[4:7], v[170:173], v[212:215], v[4:7]
	v_mfma_f32_16x16x32_bf16 v[0:3], v[178:181], v[212:215], v[0:3]
	v_mfma_f32_16x16x32_bf16 v[52:55], v[174:177], v[192:195], v[52:55]
	v_mfma_f32_16x16x32_bf16 v[48:51], v[182:185], v[192:195], v[48:51]
	v_mfma_f32_16x16x32_bf16 v[36:39], v[174:177], v[200:203], v[36:39]
	v_mfma_f32_16x16x32_bf16 v[32:35], v[182:185], v[200:203], v[32:35]
	v_mfma_f32_16x16x32_bf16 v[20:23], v[174:177], v[208:211], v[20:23]
	v_mfma_f32_16x16x32_bf16 v[16:19], v[182:185], v[208:211], v[16:19]
	v_mfma_f32_16x16x32_bf16 v[4:7], v[174:177], v[216:219], v[4:7]
	v_mfma_f32_16x16x32_bf16 v[0:3], v[182:185], v[216:219], v[0:3]
	s_barrier
	s_setprio 0
	s_add_i32 s64, s64, 2
	s_add_u32 s36, s36, 0x100
	s_addc_u32 s37, s37, 0
	s_add_u32 s62, s62, 0x100
	s_addc_u32 s63, s63, 0
	s_cmp_gt_u32 s64, 29
	s_cbranch_scc0 .LBB0_1020
	s_and_b64 vcc, exec, s[14:15]
	s_cbranch_vccz .LBB0_1023
	s_barrier

.LBB0_1102:
	ds_read_b128 v[170:173], v165
	ds_read_b128 v[174:177], v165 offset:1024
	ds_read_b128 v[178:181], v165 offset:2048
	ds_read_b128 v[182:185], v165 offset:3072
	ds_read_b128 v[186:189], v166
	ds_read_b128 v[192:195], v166 offset:1024
	ds_read_b128 v[196:199], v166 offset:2048
	ds_read_b128 v[200:203], v166 offset:3072
	s_add_u32 s40, s38, 0x100
	s_addc_u32 s41, s39, 0
	s_cmpk_eq_i32 s65, 0x52
	s_cselect_b32 s45, s1, s41
	s_cselect_b32 s44, s0, s40
	s_cselect_b32 s43, s37, s64
	s_cselect_b32 s42, s36, s63
	v_lshl_add_u64 v[144:145], s[38:39], 0, v[136:137]
	s_add_i32 m0, s5, 0xc000
	ds_read_b128 v[204:207], v167
	ds_read_b128 v[208:211], v167 offset:1024
	ds_read_b128 v[212:215], v167 offset:2048
	ds_read_b128 v[216:219], v167 offset:3072
	ds_read_b128 v[220:223], v167 offset:4096
	ds_read_b128 v[224:227], v167 offset:5120
	ds_read_b128 v[228:231], v167 offset:6144
	ds_read_b128 v[232:235], v167 offset:7168
	global_load_lds_dwordx4 v[144:145], off
	v_lshl_add_u64 v[144:145], s[38:39], 0, v[138:139]
	s_add_i32 m0, s5, 0xe000
	s_nop 0
	global_load_lds_dwordx4 v[144:145], off
	s_waitcnt vmcnt(8)
	s_waitcnt lgkmcnt(0)
	s_setprio 1
	s_barrier
	v_mfma_f32_16x16x32_bf16 v[124:127], v[170:173], v[204:207], v[124:127]
	v_mfma_f32_16x16x32_bf16 v[120:123], v[178:181], v[204:207], v[120:123]
	v_mfma_f32_16x16x32_bf16 v[108:111], v[170:173], v[212:215], v[108:111]
	v_mfma_f32_16x16x32_bf16 v[104:107], v[178:181], v[212:215], v[104:107]
	v_mfma_f32_16x16x32_bf16 v[92:95], v[170:173], v[220:223], v[92:95]
	v_mfma_f32_16x16x32_bf16 v[88:91], v[178:181], v[220:223], v[88:91]
	v_mfma_f32_16x16x32_bf16 v[76:79], v[170:173], v[228:231], v[76:79]
	v_mfma_f32_16x16x32_bf16 v[72:75], v[178:181], v[228:231], v[72:75]
	v_mfma_f32_16x16x32_bf16 v[124:127], v[174:177], v[208:211], v[124:127]
	v_mfma_f32_16x16x32_bf16 v[120:123], v[182:185], v[208:211], v[120:123]
	v_mfma_f32_16x16x32_bf16 v[108:111], v[174:177], v[216:219], v[108:111]
	v_mfma_f32_16x16x32_bf16 v[104:107], v[182:185], v[216:219], v[104:107]
	v_mfma_f32_16x16x32_bf16 v[92:95], v[174:177], v[224:227], v[92:95]
	v_mfma_f32_16x16x32_bf16 v[88:91], v[182:185], v[224:227], v[88:91]
	v_mfma_f32_16x16x32_bf16 v[76:79], v[174:177], v[232:235], v[76:79]
	v_mfma_f32_16x16x32_bf16 v[72:75], v[182:185], v[232:235], v[72:75]
	s_setprio 0
	s_setprio 1
	v_mfma_f32_16x16x32_bf16 v[116:119], v[186:189], v[204:207], v[116:119]
	v_mfma_f32_16x16x32_bf16 v[112:115], v[196:199], v[204:207], v[112:115]
	v_mfma_f32_16x16x32_bf16 v[100:103], v[186:189], v[212:215], v[100:103]
	v_mfma_f32_16x16x32_bf16 v[96:99], v[196:199], v[212:215], v[96:99]
	v_mfma_f32_16x16x32_bf16 v[84:87], v[186:189], v[220:223], v[84:87]
	v_mfma_f32_16x16x32_bf16 v[80:83], v[196:199], v[220:223], v[80:83]
	v_mfma_f32_16x16x32_bf16 v[68:71], v[186:189], v[228:231], v[68:71]
	v_mfma_f32_16x16x32_bf16 v[64:67], v[196:199], v[228:231], v[64:67]
	v_mfma_f32_16x16x32_bf16 v[116:119], v[192:195], v[208:211], v[116:119]
	v_mfma_f32_16x16x32_bf16 v[112:115], v[200:203], v[208:211], v[112:115]
	v_mfma_f32_16x16x32_bf16 v[100:103], v[192:195], v[216:219], v[100:103]
	v_mfma_f32_16x16x32_bf16 v[96:99], v[200:203], v[216:219], v[96:99]
	v_mfma_f32_16x16x32_bf16 v[84:87], v[192:195], v[224:227], v[84:87]
	v_mfma_f32_16x16x32_bf16 v[80:83], v[200:203], v[224:227], v[80:83]
	v_mfma_f32_16x16x32_bf16 v[68:71], v[192:195], v[232:235], v[68:71]
	v_mfma_f32_16x16x32_bf16 v[64:67], v[200:203], v[232:235], v[64:67]
	s_barrier
	s_setprio 0
	s_add_i32 s38, s57, s4
	v_lshl_add_u64 v[144:145], s[42:43], 0, v[130:131]
	s_mov_b32 m0, s38
	ds_read_b128 v[204:207], v167 offset:16384
	ds_read_b128 v[208:211], v167 offset:17408
	ds_read_b128 v[212:215], v167 offset:18432
	ds_read_b128 v[216:219], v167 offset:19456
	ds_read_b128 v[220:223], v167 offset:20480
	ds_read_b128 v[224:227], v167 offset:21504
	ds_read_b128 v[228:231], v167 offset:22528
	ds_read_b128 v[232:235], v167 offset:23552
	global_load_lds_dwordx4 v[144:145], off
	s_add_i32 m0, s38, 0x2000
	s_add_u32 s38, s42, 0x158000
	v_lshl_add_u64 v[236:237], s[42:43], 0, v[134:135]
	s_addc_u32 s39, s43, 0
	s_add_i32 s66, s58, s4
	global_load_lds_dwordx4 v[236:237], off
	v_lshl_add_u64 v[238:239], s[38:39], 0, v[130:131]
	s_mov_b32 m0, s66
	v_lshl_add_u64 v[240:241], s[44:45], 0, v[132:133]
	global_load_lds_dwordx4 v[238:239], off
	v_lshl_add_u64 v[238:239], s[38:39], 0, v[134:135]
	s_add_i32 m0, s66, 0x2000
	s_nop 0
	global_load_lds_dwordx4 v[238:239], off
	v_lshl_add_u64 v[238:239], s[44:45], 0, v[128:129]
	s_mov_b32 m0, s5
	s_nop 0
	global_load_lds_dwordx4 v[238:239], off
	s_mov_b32 m0, s46
	s_nop 0
	global_load_lds_dwordx4 v[240:241], off
	s_waitcnt vmcnt(8)
	s_waitcnt lgkmcnt(0)
	s_setprio 1
	s_barrier
	v_mfma_f32_16x16x32_bf16 v[60:63], v[170:173], v[204:207], v[60:63]
	v_mfma_f32_16x16x32_bf16 v[56:59], v[178:181], v[204:207], v[56:59]
	v_mfma_f32_16x16x32_bf16 v[44:47], v[170:173], v[212:215], v[44:47]
	v_mfma_f32_16x16x32_bf16 v[40:43], v[178:181], v[212:215], v[40:43]
	v_mfma_f32_16x16x32_bf16 v[28:31], v[170:173], v[220:223], v[28:31]
	v_mfma_f32_16x16x32_bf16 v[24:27], v[178:181], v[220:223], v[24:27]
	v_mfma_f32_16x16x32_bf16 v[12:15], v[170:173], v[228:231], v[12:15]
	v_mfma_f32_16x16x32_bf16 v[8:11], v[178:181], v[228:231], v[8:11]
	v_mfma_f32_16x16x32_bf16 v[60:63], v[174:177], v[208:211], v[60:63]
	v_mfma_f32_16x16x32_bf16 v[56:59], v[182:185], v[208:211], v[56:59]
	v_mfma_f32_16x16x32_bf16 v[44:47], v[174:177], v[216:219], v[44:47]
	v_mfma_f32_16x16x32_bf16 v[40:43], v[182:185], v[216:219], v[40:43]
	v_mfma_f32_16x16x32_bf16 v[28:31], v[174:177], v[224:227], v[28:31]
	v_mfma_f32_16x16x32_bf16 v[24:27], v[182:185], v[224:227], v[24:27]
	v_mfma_f32_16x16x32_bf16 v[12:15], v[174:177], v[232:235], v[12:15]
	v_mfma_f32_16x16x32_bf16 v[8:11], v[182:185], v[232:235], v[8:11]
	s_setprio 0
	s_setprio 1
	v_mfma_f32_16x16x32_bf16 v[52:55], v[186:189], v[204:207], v[52:55]
	v_mfma_f32_16x16x32_bf16 v[48:51], v[196:199], v[204:207], v[48:51]
	v_mfma_f32_16x16x32_bf16 v[36:39], v[186:189], v[212:215], v[36:39]
	v_mfma_f32_16x16x32_bf16 v[32:35], v[196:199], v[212:215], v[32:35]
	v_mfma_f32_16x16x32_bf16 v[20:23], v[186:189], v[220:223], v[20:23]
	v_mfma_f32_16x16x32_bf16 v[16:19], v[196:199], v[220:223], v[16:19]
	v_mfma_f32_16x16x32_bf16 v[4:7], v[186:189], v[228:231], v[4:7]
	v_mfma_f32_16x16x32_bf16 v[0:3], v[196:199], v[228:231], v[0:3]
	v_mfma_f32_16x16x32_bf16 v[52:55], v[192:195], v[208:211], v[52:55]
	v_mfma_f32_16x16x32_bf16 v[48:51], v[200:203], v[208:211], v[48:51]
	v_mfma_f32_16x16x32_bf16 v[36:39], v[192:195], v[216:219], v[36:39]
	v_mfma_f32_16x16x32_bf16 v[32:35], v[200:203], v[216:219], v[32:35]
	v_mfma_f32_16x16x32_bf16 v[20:23], v[192:195], v[224:227], v[20:23]
	v_mfma_f32_16x16x32_bf16 v[16:19], v[200:203], v[224:227], v[16:19]
	v_mfma_f32_16x16x32_bf16 v[4:7], v[192:195], v[232:235], v[4:7]
	v_mfma_f32_16x16x32_bf16 v[0:3], v[200:203], v[232:235], v[0:3]
	s_barrier
	s_setprio 0
	s_add_i32 s66, 0, 0x18000
	s_add_i32 s67, 0, 0x1c000
	v_add_u32_e32 v182, s66, v147
	v_add_u32_e32 v200, s67, v147
	ds_read_b128 v[170:173], v182
	ds_read_b128 v[174:177], v182 offset:1024
	ds_read_b128 v[178:181], v182 offset:2048
	ds_read_b128 v[182:185], v182 offset:3072
	ds_read_b128 v[186:189], v200
	ds_read_b128 v[192:195], v200 offset:1024
	ds_read_b128 v[196:199], v200 offset:2048
	ds_read_b128 v[200:203], v200 offset:3072
	s_add_u32 s38, s44, 0x158000
	s_addc_u32 s39, s45, 0
	s_mov_b32 m0, s47
	v_lshl_add_u64 v[242:243], s[38:39], 0, v[128:129]
	ds_read_b128 v[204:207], v167 offset:32768
	ds_read_b128 v[208:211], v167 offset:33792
	ds_read_b128 v[212:215], v167 offset:34816
	ds_read_b128 v[216:219], v167 offset:35840
	ds_read_b128 v[220:223], v167 offset:36864
	ds_read_b128 v[224:227], v167 offset:37888
	ds_read_b128 v[228:231], v167 offset:38912
	ds_read_b128 v[232:235], v167 offset:39936
	global_load_lds_dwordx4 v[242:243], off
	v_lshl_add_u64 v[242:243], s[38:39], 0, v[132:133]
	s_mov_b32 m0, s48
	s_nop 0
	global_load_lds_dwordx4 v[242:243], off
	s_waitcnt vmcnt(8)
	s_waitcnt lgkmcnt(0)
	s_setprio 1
	s_barrier
	v_mfma_f32_16x16x32_bf16 v[124:127], v[170:173], v[204:207], v[124:127]
	v_mfma_f32_16x16x32_bf16 v[120:123], v[178:181], v[204:207], v[120:123]
	v_mfma_f32_16x16x32_bf16 v[108:111], v[170:173], v[212:215], v[108:111]
	v_mfma_f32_16x16x32_bf16 v[104:107], v[178:181], v[212:215], v[104:107]
	v_mfma_f32_16x16x32_bf16 v[92:95], v[170:173], v[220:223], v[92:95]
	v_mfma_f32_16x16x32_bf16 v[88:91], v[178:181], v[220:223], v[88:91]
	v_mfma_f32_16x16x32_bf16 v[76:79], v[170:173], v[228:231], v[76:79]
	v_mfma_f32_16x16x32_bf16 v[72:75], v[178:181], v[228:231], v[72:75]
	v_mfma_f32_16x16x32_bf16 v[124:127], v[174:177], v[208:211], v[124:127]
	v_mfma_f32_16x16x32_bf16 v[120:123], v[182:185], v[208:211], v[120:123]
	v_mfma_f32_16x16x32_bf16 v[108:111], v[174:177], v[216:219], v[108:111]
	v_mfma_f32_16x16x32_bf16 v[104:107], v[182:185], v[216:219], v[104:107]
	v_mfma_f32_16x16x32_bf16 v[92:95], v[174:177], v[224:227], v[92:95]
	v_mfma_f32_16x16x32_bf16 v[88:91], v[182:185], v[224:227], v[88:91]
	v_mfma_f32_16x16x32_bf16 v[76:79], v[174:177], v[232:235], v[76:79]
	v_mfma_f32_16x16x32_bf16 v[72:75], v[182:185], v[232:235], v[72:75]
	s_setprio 0
	s_setprio 1
	v_mfma_f32_16x16x32_bf16 v[116:119], v[186:189], v[204:207], v[116:119]
	v_mfma_f32_16x16x32_bf16 v[112:115], v[196:199], v[204:207], v[112:115]
	v_mfma_f32_16x16x32_bf16 v[100:103], v[186:189], v[212:215], v[100:103]
	v_mfma_f32_16x16x32_bf16 v[96:99], v[196:199], v[212:215], v[96:99]
	v_mfma_f32_16x16x32_bf16 v[84:87], v[186:189], v[220:223], v[84:87]
	v_mfma_f32_16x16x32_bf16 v[80:83], v[196:199], v[220:223], v[80:83]
	v_mfma_f32_16x16x32_bf16 v[68:71], v[186:189], v[228:231], v[68:71]
	v_mfma_f32_16x16x32_bf16 v[64:67], v[196:199], v[228:231], v[64:67]
	v_mfma_f32_16x16x32_bf16 v[116:119], v[192:195], v[208:211], v[116:119]
	v_mfma_f32_16x16x32_bf16 v[112:115], v[200:203], v[208:211], v[112:115]
	v_mfma_f32_16x16x32_bf16 v[100:103], v[192:195], v[216:219], v[100:103]
	v_mfma_f32_16x16x32_bf16 v[96:99], v[200:203], v[216:219], v[96:99]
	v_mfma_f32_16x16x32_bf16 v[84:87], v[192:195], v[224:227], v[84:87]
	v_mfma_f32_16x16x32_bf16 v[80:83], v[200:203], v[224:227], v[80:83]
	v_mfma_f32_16x16x32_bf16 v[68:71], v[192:195], v[232:235], v[68:71]
	v_mfma_f32_16x16x32_bf16 v[64:67], v[200:203], v[232:235], v[64:67]
	s_barrier
	s_setprio 0
	s_add_i32 s38, s66, s4
	v_lshl_add_u64 v[144:145], v[144:145], 0, s[30:31]
	s_mov_b32 m0, s38
	ds_read_b128 v[204:207], v167 offset:49152
	ds_read_b128 v[208:211], v167 offset:50176
	ds_read_b128 v[212:215], v167 offset:51200
	ds_read_b128 v[216:219], v167 offset:52224
	ds_read_b128 v[220:223], v167 offset:53248
	ds_read_b128 v[224:227], v167 offset:54272
	ds_read_b128 v[228:231], v167 offset:55296
	ds_read_b128 v[232:235], v167 offset:56320
	global_load_lds_dwordx4 v[144:145], off
	s_add_i32 m0, s38, 0x2000
	s_add_u32 s38, s42, 0x158080
	v_lshl_add_u64 v[144:145], v[236:237], 0, s[30:31]
	s_addc_u32 s39, s43, 0
	s_add_i32 s42, s67, s4
	global_load_lds_dwordx4 v[144:145], off
	v_lshl_add_u64 v[144:145], s[38:39], 0, v[130:131]
	s_mov_b32 m0, s42
	s_nop 0
	global_load_lds_dwordx4 v[144:145], off
	v_lshl_add_u64 v[144:145], s[38:39], 0, v[134:135]
	s_add_i32 m0, s42, 0x2000
	s_nop 0
	global_load_lds_dwordx4 v[144:145], off
	v_lshl_add_u64 v[144:145], v[238:239], 0, s[30:31]
	s_mov_b32 m0, s52
	s_nop 0
	global_load_lds_dwordx4 v[144:145], off
	v_lshl_add_u64 v[144:145], v[240:241], 0, s[30:31]
	s_mov_b32 m0, s53
	s_nop 0
	global_load_lds_dwordx4 v[144:145], off
	s_waitcnt vmcnt(8)
	s_waitcnt lgkmcnt(0)
	s_setprio 1
	s_barrier
	v_mfma_f32_16x16x32_bf16 v[60:63], v[170:173], v[204:207], v[60:63]
	v_mfma_f32_16x16x32_bf16 v[56:59], v[178:181], v[204:207], v[56:59]
	v_mfma_f32_16x16x32_bf16 v[44:47], v[170:173], v[212:215], v[44:47]
	v_mfma_f32_16x16x32_bf16 v[40:43], v[178:181], v[212:215], v[40:43]
	v_mfma_f32_16x16x32_bf16 v[28:31], v[170:173], v[220:223], v[28:31]
	v_mfma_f32_16x16x32_bf16 v[24:27], v[178:181], v[220:223], v[24:27]
	v_mfma_f32_16x16x32_bf16 v[12:15], v[170:173], v[228:231], v[12:15]
	v_mfma_f32_16x16x32_bf16 v[8:11], v[178:181], v[228:231], v[8:11]
	v_mfma_f32_16x16x32_bf16 v[60:63], v[174:177], v[208:211], v[60:63]
	v_mfma_f32_16x16x32_bf16 v[56:59], v[182:185], v[208:211], v[56:59]
	v_mfma_f32_16x16x32_bf16 v[44:47], v[174:177], v[216:219], v[44:47]
	v_mfma_f32_16x16x32_bf16 v[40:43], v[182:185], v[216:219], v[40:43]
	v_mfma_f32_16x16x32_bf16 v[28:31], v[174:177], v[224:227], v[28:31]
	v_mfma_f32_16x16x32_bf16 v[24:27], v[182:185], v[224:227], v[24:27]
	v_mfma_f32_16x16x32_bf16 v[12:15], v[174:177], v[232:235], v[12:15]
	v_mfma_f32_16x16x32_bf16 v[8:11], v[182:185], v[232:235], v[8:11]
	s_setprio 0
	s_setprio 1
	v_mfma_f32_16x16x32_bf16 v[52:55], v[186:189], v[204:207], v[52:55]
	v_mfma_f32_16x16x32_bf16 v[48:51], v[196:199], v[204:207], v[48:51]
	v_mfma_f32_16x16x32_bf16 v[36:39], v[186:189], v[212:215], v[36:39]
	v_mfma_f32_16x16x32_bf16 v[32:35], v[196:199], v[212:215], v[32:35]
	v_mfma_f32_16x16x32_bf16 v[20:23], v[186:189], v[220:223], v[20:23]
	v_mfma_f32_16x16x32_bf16 v[16:19], v[196:199], v[220:223], v[16:19]
	v_mfma_f32_16x16x32_bf16 v[4:7], v[186:189], v[228:231], v[4:7]
	v_mfma_f32_16x16x32_bf16 v[0:3], v[196:199], v[228:231], v[0:3]
	v_mfma_f32_16x16x32_bf16 v[52:55], v[192:195], v[208:211], v[52:55]
	v_mfma_f32_16x16x32_bf16 v[48:51], v[200:203], v[208:211], v[48:51]
	v_mfma_f32_16x16x32_bf16 v[36:39], v[192:195], v[216:219], v[36:39]
	v_mfma_f32_16x16x32_bf16 v[32:35], v[200:203], v[216:219], v[32:35]
	v_mfma_f32_16x16x32_bf16 v[20:23], v[192:195], v[224:227], v[20:23]
	v_mfma_f32_16x16x32_bf16 v[16:19], v[200:203], v[224:227], v[16:19]
	v_mfma_f32_16x16x32_bf16 v[4:7], v[192:195], v[232:235], v[4:7]
	v_mfma_f32_16x16x32_bf16 v[0:3], v[200:203], v[232:235], v[0:3]
	s_barrier
	s_setprio 0
	s_add_i32 s65, s65, 2
	s_add_u32 s63, s63, 0x100
	s_addc_u32 s64, s64, 0
	s_cmpk_gt_u32 s65, 0x53
	s_mov_b64 s[38:39], s[40:41]
	s_cbranch_scc0 .LBB0_1102
	s_and_b64 vcc, exec, s[34:35]
	s_cbranch_vccz .LBB0_1105
	s_barrier

.LBB0_1313:
	ds_read_b128 v[144:147], v153
	ds_read_b128 v[158:161], v153 offset:1024
	ds_read_b128 v[162:165], v153 offset:2048
	ds_read_b128 v[166:169], v153 offset:3072
	ds_read_b128 v[170:173], v154
	ds_read_b128 v[174:177], v154 offset:1024
	ds_read_b128 v[178:181], v154 offset:2048
	ds_read_b128 v[182:185], v154 offset:3072
	s_add_u32 s44, s42, 0xfff80080
	s_addc_u32 s45, s43, -1
	s_cmp_eq_u32 s77, 28
	s_cselect_b32 s47, s37, s45
	s_cselect_b32 s46, s66, s44
	s_cselect_b32 s45, s35, s71
	s_cselect_b32 s44, s67, s69
	v_lshl_add_u64 v[148:149], s[42:43], 0, v[136:137]
	s_add_i32 m0, s49, 0xc000
	ds_read_b128 v[186:189], v155
	ds_read_b128 v[192:195], v155 offset:1024
	ds_read_b128 v[196:199], v155 offset:2048
	ds_read_b128 v[200:203], v155 offset:3072
	ds_read_b128 v[204:207], v155 offset:4096
	ds_read_b128 v[208:211], v155 offset:5120
	ds_read_b128 v[212:215], v155 offset:6144
	ds_read_b128 v[216:219], v155 offset:7168
	global_load_lds_dwordx4 v[148:149], off
	v_lshl_add_u64 v[148:149], s[42:43], 0, v[138:139]
	s_add_i32 m0, s49, 0xe000
	s_nop 0
	global_load_lds_dwordx4 v[148:149], off
	s_waitcnt vmcnt(8)
	s_waitcnt lgkmcnt(0)
	s_setprio 1
	s_barrier
	v_mfma_f32_16x16x32_bf16 v[124:127], v[144:147], v[186:189], v[124:127]
	v_mfma_f32_16x16x32_bf16 v[120:123], v[162:165], v[186:189], v[120:123]
	v_mfma_f32_16x16x32_bf16 v[108:111], v[144:147], v[196:199], v[108:111]
	v_mfma_f32_16x16x32_bf16 v[104:107], v[162:165], v[196:199], v[104:107]
	v_mfma_f32_16x16x32_bf16 v[92:95], v[144:147], v[204:207], v[92:95]
	v_mfma_f32_16x16x32_bf16 v[88:91], v[162:165], v[204:207], v[88:91]
	v_mfma_f32_16x16x32_bf16 v[76:79], v[144:147], v[212:215], v[76:79]
	v_mfma_f32_16x16x32_bf16 v[72:75], v[162:165], v[212:215], v[72:75]
	v_mfma_f32_16x16x32_bf16 v[124:127], v[158:161], v[192:195], v[124:127]
	v_mfma_f32_16x16x32_bf16 v[120:123], v[166:169], v[192:195], v[120:123]
	v_mfma_f32_16x16x32_bf16 v[108:111], v[158:161], v[200:203], v[108:111]
	v_mfma_f32_16x16x32_bf16 v[104:107], v[166:169], v[200:203], v[104:107]
	v_mfma_f32_16x16x32_bf16 v[92:95], v[158:161], v[208:211], v[92:95]
	v_mfma_f32_16x16x32_bf16 v[88:91], v[166:169], v[208:211], v[88:91]
	v_mfma_f32_16x16x32_bf16 v[76:79], v[158:161], v[216:219], v[76:79]
	v_mfma_f32_16x16x32_bf16 v[72:75], v[166:169], v[216:219], v[72:75]
	s_setprio 0
	s_setprio 1
	v_mfma_f32_16x16x32_bf16 v[116:119], v[170:173], v[186:189], v[116:119]
	v_mfma_f32_16x16x32_bf16 v[112:115], v[178:181], v[186:189], v[112:115]
	v_mfma_f32_16x16x32_bf16 v[100:103], v[170:173], v[196:199], v[100:103]
	v_mfma_f32_16x16x32_bf16 v[96:99], v[178:181], v[196:199], v[96:99]
	v_mfma_f32_16x16x32_bf16 v[84:87], v[170:173], v[204:207], v[84:87]
	v_mfma_f32_16x16x32_bf16 v[80:83], v[178:181], v[204:207], v[80:83]
	v_mfma_f32_16x16x32_bf16 v[68:71], v[170:173], v[212:215], v[68:71]
	v_mfma_f32_16x16x32_bf16 v[64:67], v[178:181], v[212:215], v[64:67]
	v_mfma_f32_16x16x32_bf16 v[116:119], v[174:177], v[192:195], v[116:119]
	v_mfma_f32_16x16x32_bf16 v[112:115], v[182:185], v[192:195], v[112:115]
	v_mfma_f32_16x16x32_bf16 v[100:103], v[174:177], v[200:203], v[100:103]
	v_mfma_f32_16x16x32_bf16 v[96:99], v[182:185], v[200:203], v[96:99]
	v_mfma_f32_16x16x32_bf16 v[84:87], v[174:177], v[208:211], v[84:87]
	v_mfma_f32_16x16x32_bf16 v[80:83], v[182:185], v[208:211], v[80:83]
	v_mfma_f32_16x16x32_bf16 v[68:71], v[174:177], v[216:219], v[68:71]
	v_mfma_f32_16x16x32_bf16 v[64:67], v[182:185], v[216:219], v[64:67]
	s_barrier
	s_setprio 0
	s_add_i32 s84, s62, s4
	v_lshl_add_u64 v[148:149], s[44:45], 0, v[132:133]
	s_mov_b32 m0, s84
	ds_read_b128 v[186:189], v155 offset:16384
	ds_read_b128 v[192:195], v155 offset:17408
	ds_read_b128 v[196:199], v155 offset:18432
	ds_read_b128 v[200:203], v155 offset:19456
	ds_read_b128 v[204:207], v155 offset:20480
	ds_read_b128 v[208:211], v155 offset:21504
	ds_read_b128 v[212:215], v155 offset:22528
	ds_read_b128 v[216:219], v155 offset:23552
	global_load_lds_dwordx4 v[148:149], off
	s_add_i32 m0, s84, 0x2000
	s_add_u32 s84, s44, 0x80000
	v_lshl_add_u64 v[220:221], s[44:45], 0, v[128:129]
	s_addc_u32 s85, s45, 0
	s_add_i32 s86, s63, s4
	global_load_lds_dwordx4 v[220:221], off
	v_lshl_add_u64 v[222:223], s[84:85], 0, v[132:133]
	s_mov_b32 m0, s86
	v_lshl_add_u64 v[224:225], s[46:47], 0, v[130:131]
	global_load_lds_dwordx4 v[222:223], off
	v_lshl_add_u64 v[222:223], s[84:85], 0, v[128:129]
	s_add_i32 m0, s86, 0x2000
	s_nop 0
	global_load_lds_dwordx4 v[222:223], off
	v_lshl_add_u64 v[222:223], s[46:47], 0, v[134:135]
	s_mov_b32 m0, s49
	s_nop 0
	global_load_lds_dwordx4 v[222:223], off
	s_mov_b32 m0, s52
	s_nop 0
	global_load_lds_dwordx4 v[224:225], off
	s_waitcnt vmcnt(8)
	s_waitcnt lgkmcnt(0)
	s_setprio 1
	s_barrier
	v_mfma_f32_16x16x32_bf16 v[60:63], v[144:147], v[186:189], v[60:63]
	v_mfma_f32_16x16x32_bf16 v[56:59], v[162:165], v[186:189], v[56:59]
	v_mfma_f32_16x16x32_bf16 v[44:47], v[144:147], v[196:199], v[44:47]
	v_mfma_f32_16x16x32_bf16 v[40:43], v[162:165], v[196:199], v[40:43]
	v_mfma_f32_16x16x32_bf16 v[28:31], v[144:147], v[204:207], v[28:31]
	v_mfma_f32_16x16x32_bf16 v[24:27], v[162:165], v[204:207], v[24:27]
	v_mfma_f32_16x16x32_bf16 v[12:15], v[144:147], v[212:215], v[12:15]
	v_mfma_f32_16x16x32_bf16 v[8:11], v[162:165], v[212:215], v[8:11]
	v_mfma_f32_16x16x32_bf16 v[60:63], v[158:161], v[192:195], v[60:63]
	v_mfma_f32_16x16x32_bf16 v[56:59], v[166:169], v[192:195], v[56:59]
	v_mfma_f32_16x16x32_bf16 v[44:47], v[158:161], v[200:203], v[44:47]
	v_mfma_f32_16x16x32_bf16 v[40:43], v[166:169], v[200:203], v[40:43]
	v_mfma_f32_16x16x32_bf16 v[28:31], v[158:161], v[208:211], v[28:31]
	v_mfma_f32_16x16x32_bf16 v[24:27], v[166:169], v[208:211], v[24:27]
	v_mfma_f32_16x16x32_bf16 v[12:15], v[158:161], v[216:219], v[12:15]
	v_mfma_f32_16x16x32_bf16 v[8:11], v[166:169], v[216:219], v[8:11]
	s_setprio 0
	s_setprio 1
	v_mfma_f32_16x16x32_bf16 v[52:55], v[170:173], v[186:189], v[52:55]
	v_mfma_f32_16x16x32_bf16 v[48:51], v[178:181], v[186:189], v[48:51]
	v_mfma_f32_16x16x32_bf16 v[36:39], v[170:173], v[196:199], v[36:39]
	v_mfma_f32_16x16x32_bf16 v[32:35], v[178:181], v[196:199], v[32:35]
	v_mfma_f32_16x16x32_bf16 v[20:23], v[170:173], v[204:207], v[20:23]
	v_mfma_f32_16x16x32_bf16 v[16:19], v[178:181], v[204:207], v[16:19]
	v_mfma_f32_16x16x32_bf16 v[4:7], v[170:173], v[212:215], v[4:7]
	v_mfma_f32_16x16x32_bf16 v[0:3], v[178:181], v[212:215], v[0:3]
	v_mfma_f32_16x16x32_bf16 v[52:55], v[174:177], v[192:195], v[52:55]
	v_mfma_f32_16x16x32_bf16 v[48:51], v[182:185], v[192:195], v[48:51]
	v_mfma_f32_16x16x32_bf16 v[36:39], v[174:177], v[200:203], v[36:39]
	v_mfma_f32_16x16x32_bf16 v[32:35], v[182:185], v[200:203], v[32:35]
	v_mfma_f32_16x16x32_bf16 v[20:23], v[174:177], v[208:211], v[20:23]
	v_mfma_f32_16x16x32_bf16 v[16:19], v[182:185], v[208:211], v[16:19]
	v_mfma_f32_16x16x32_bf16 v[4:7], v[174:177], v[216:219], v[4:7]
	v_mfma_f32_16x16x32_bf16 v[0:3], v[182:185], v[216:219], v[0:3]
	s_barrier
	s_setprio 0
	s_add_i32 s84, 0, 0x18000
	v_add_u32_e32 v157, s84, v151
	s_add_i32 s85, 0, 0x1c000
	ds_read_b128 v[144:147], v157
	ds_read_b128 v[158:161], v157 offset:1024
	ds_read_b128 v[162:165], v157 offset:2048
	ds_read_b128 v[166:169], v157 offset:3072
	v_add_u32_e32 v157, s85, v151
	ds_read_b128 v[170:173], v157
	ds_read_b128 v[174:177], v157 offset:1024
	ds_read_b128 v[178:181], v157 offset:2048
	ds_read_b128 v[182:185], v157 offset:3072
	s_add_u32 s46, s46, 0x80000
	s_addc_u32 s47, s47, 0
	s_mov_b32 m0, s53
	v_lshl_add_u64 v[226:227], s[46:47], 0, v[134:135]
	ds_read_b128 v[186:189], v155 offset:32768
	ds_read_b128 v[192:195], v155 offset:33792
	ds_read_b128 v[196:199], v155 offset:34816
	ds_read_b128 v[200:203], v155 offset:35840
	ds_read_b128 v[204:207], v155 offset:36864
	ds_read_b128 v[208:211], v155 offset:37888
	ds_read_b128 v[212:215], v155 offset:38912
	ds_read_b128 v[216:219], v155 offset:39936
	global_load_lds_dwordx4 v[226:227], off
	v_lshl_add_u64 v[226:227], s[46:47], 0, v[130:131]
	s_mov_b32 m0, s54
	s_nop 0
	global_load_lds_dwordx4 v[226:227], off
	s_waitcnt vmcnt(8)
	s_waitcnt lgkmcnt(0)
	s_setprio 1
	s_barrier
	v_mfma_f32_16x16x32_bf16 v[124:127], v[144:147], v[186:189], v[124:127]
	v_mfma_f32_16x16x32_bf16 v[120:123], v[162:165], v[186:189], v[120:123]
	v_mfma_f32_16x16x32_bf16 v[108:111], v[144:147], v[196:199], v[108:111]
	v_mfma_f32_16x16x32_bf16 v[104:107], v[162:165], v[196:199], v[104:107]
	v_mfma_f32_16x16x32_bf16 v[92:95], v[144:147], v[204:207], v[92:95]
	v_mfma_f32_16x16x32_bf16 v[88:91], v[162:165], v[204:207], v[88:91]
	v_mfma_f32_16x16x32_bf16 v[76:79], v[144:147], v[212:215], v[76:79]
	v_mfma_f32_16x16x32_bf16 v[72:75], v[162:165], v[212:215], v[72:75]
	v_mfma_f32_16x16x32_bf16 v[124:127], v[158:161], v[192:195], v[124:127]
	v_mfma_f32_16x16x32_bf16 v[120:123], v[166:169], v[192:195], v[120:123]
	v_mfma_f32_16x16x32_bf16 v[108:111], v[158:161], v[200:203], v[108:111]
	v_mfma_f32_16x16x32_bf16 v[104:107], v[166:169], v[200:203], v[104:107]
	v_mfma_f32_16x16x32_bf16 v[92:95], v[158:161], v[208:211], v[92:95]
	v_mfma_f32_16x16x32_bf16 v[88:91], v[166:169], v[208:211], v[88:91]
	v_mfma_f32_16x16x32_bf16 v[76:79], v[158:161], v[216:219], v[76:79]
	v_mfma_f32_16x16x32_bf16 v[72:75], v[166:169], v[216:219], v[72:75]
	s_setprio 0
	s_setprio 1
	v_mfma_f32_16x16x32_bf16 v[116:119], v[170:173], v[186:189], v[116:119]
	v_mfma_f32_16x16x32_bf16 v[112:115], v[178:181], v[186:189], v[112:115]
	v_mfma_f32_16x16x32_bf16 v[100:103], v[170:173], v[196:199], v[100:103]
	v_mfma_f32_16x16x32_bf16 v[96:99], v[178:181], v[196:199], v[96:99]
	v_mfma_f32_16x16x32_bf16 v[84:87], v[170:173], v[204:207], v[84:87]
	v_mfma_f32_16x16x32_bf16 v[80:83], v[178:181], v[204:207], v[80:83]
	v_mfma_f32_16x16x32_bf16 v[68:71], v[170:173], v[212:215], v[68:71]
	v_mfma_f32_16x16x32_bf16 v[64:67], v[178:181], v[212:215], v[64:67]
	v_mfma_f32_16x16x32_bf16 v[116:119], v[174:177], v[192:195], v[116:119]
	v_mfma_f32_16x16x32_bf16 v[112:115], v[182:185], v[192:195], v[112:115]
	v_mfma_f32_16x16x32_bf16 v[100:103], v[174:177], v[200:203], v[100:103]
	v_mfma_f32_16x16x32_bf16 v[96:99], v[182:185], v[200:203], v[96:99]
	v_mfma_f32_16x16x32_bf16 v[84:87], v[174:177], v[208:211], v[84:87]
	v_mfma_f32_16x16x32_bf16 v[80:83], v[182:185], v[208:211], v[80:83]
	v_mfma_f32_16x16x32_bf16 v[68:71], v[174:177], v[216:219], v[68:71]
	v_mfma_f32_16x16x32_bf16 v[64:67], v[182:185], v[216:219], v[64:67]
	s_barrier
	s_setprio 0
	s_add_i32 s46, s84, s4
	v_lshl_add_u64 v[148:149], v[148:149], 0, s[28:29]
	s_mov_b32 m0, s46
	ds_read_b128 v[186:189], v155 offset:49152
	ds_read_b128 v[192:195], v155 offset:50176
	ds_read_b128 v[196:199], v155 offset:51200
	ds_read_b128 v[200:203], v155 offset:52224
	ds_read_b128 v[204:207], v155 offset:53248
	ds_read_b128 v[208:211], v155 offset:54272
	ds_read_b128 v[212:215], v155 offset:55296
	ds_read_b128 v[216:219], v155 offset:56320
	global_load_lds_dwordx4 v[148:149], off
	s_add_i32 m0, s46, 0x2000
	s_add_u32 s44, s44, 0x80080
	v_lshl_add_u64 v[148:149], v[220:221], 0, s[28:29]
	s_addc_u32 s45, s45, 0
	s_add_i32 s46, s85, s4
	global_load_lds_dwordx4 v[148:149], off
	v_lshl_add_u64 v[148:149], s[44:45], 0, v[132:133]
	s_mov_b32 m0, s46
	s_nop 0
	global_load_lds_dwordx4 v[148:149], off
	v_lshl_add_u64 v[148:149], s[44:45], 0, v[128:129]
	s_add_i32 m0, s46, 0x2000
	s_nop 0
	global_load_lds_dwordx4 v[148:149], off
	v_lshl_add_u64 v[148:149], v[222:223], 0, s[28:29]
	s_mov_b32 m0, s56
	s_nop 0
	global_load_lds_dwordx4 v[148:149], off
	v_lshl_add_u64 v[148:149], v[224:225], 0, s[28:29]
	s_mov_b32 m0, s57
	s_nop 0
	global_load_lds_dwordx4 v[148:149], off
	s_waitcnt vmcnt(8)
	s_waitcnt lgkmcnt(0)
	s_setprio 1
	s_barrier
	v_mfma_f32_16x16x32_bf16 v[60:63], v[144:147], v[186:189], v[60:63]
	v_mfma_f32_16x16x32_bf16 v[56:59], v[162:165], v[186:189], v[56:59]
	v_mfma_f32_16x16x32_bf16 v[44:47], v[144:147], v[196:199], v[44:47]
	v_mfma_f32_16x16x32_bf16 v[40:43], v[162:165], v[196:199], v[40:43]
	v_mfma_f32_16x16x32_bf16 v[28:31], v[144:147], v[204:207], v[28:31]
	v_mfma_f32_16x16x32_bf16 v[24:27], v[162:165], v[204:207], v[24:27]
	v_mfma_f32_16x16x32_bf16 v[12:15], v[144:147], v[212:215], v[12:15]
	v_mfma_f32_16x16x32_bf16 v[8:11], v[162:165], v[212:215], v[8:11]
	v_mfma_f32_16x16x32_bf16 v[60:63], v[158:161], v[192:195], v[60:63]
	v_mfma_f32_16x16x32_bf16 v[56:59], v[166:169], v[192:195], v[56:59]
	v_mfma_f32_16x16x32_bf16 v[44:47], v[158:161], v[200:203], v[44:47]
	v_mfma_f32_16x16x32_bf16 v[40:43], v[166:169], v[200:203], v[40:43]
	v_mfma_f32_16x16x32_bf16 v[28:31], v[158:161], v[208:211], v[28:31]
	v_mfma_f32_16x16x32_bf16 v[24:27], v[166:169], v[208:211], v[24:27]
	v_mfma_f32_16x16x32_bf16 v[12:15], v[158:161], v[216:219], v[12:15]
	v_mfma_f32_16x16x32_bf16 v[8:11], v[166:169], v[216:219], v[8:11]
	s_setprio 0
	s_setprio 1
	v_mfma_f32_16x16x32_bf16 v[52:55], v[170:173], v[186:189], v[52:55]
	v_mfma_f32_16x16x32_bf16 v[48:51], v[178:181], v[186:189], v[48:51]
	v_mfma_f32_16x16x32_bf16 v[36:39], v[170:173], v[196:199], v[36:39]
	v_mfma_f32_16x16x32_bf16 v[32:35], v[178:181], v[196:199], v[32:35]
	v_mfma_f32_16x16x32_bf16 v[20:23], v[170:173], v[204:207], v[20:23]
	v_mfma_f32_16x16x32_bf16 v[16:19], v[178:181], v[204:207], v[16:19]
	v_mfma_f32_16x16x32_bf16 v[4:7], v[170:173], v[212:215], v[4:7]
	v_mfma_f32_16x16x32_bf16 v[0:3], v[178:181], v[212:215], v[0:3]
	v_mfma_f32_16x16x32_bf16 v[52:55], v[174:177], v[192:195], v[52:55]
	v_mfma_f32_16x16x32_bf16 v[48:51], v[182:185], v[192:195], v[48:51]
	v_mfma_f32_16x16x32_bf16 v[36:39], v[174:177], v[200:203], v[36:39]
	v_mfma_f32_16x16x32_bf16 v[32:35], v[182:185], v[200:203], v[32:35]
	v_mfma_f32_16x16x32_bf16 v[20:23], v[174:177], v[208:211], v[20:23]
	v_mfma_f32_16x16x32_bf16 v[16:19], v[182:185], v[208:211], v[16:19]
	v_mfma_f32_16x16x32_bf16 v[4:7], v[174:177], v[216:219], v[4:7]
	v_mfma_f32_16x16x32_bf16 v[0:3], v[182:185], v[216:219], v[0:3]
	s_barrier
	s_setprio 0
	s_add_i32 s77, s77, 2
	s_add_u32 s42, s42, 0x100
	s_addc_u32 s43, s43, 0
	s_add_u32 s69, s69, 0x100
	s_addc_u32 s71, s71, 0
	s_cmp_gt_u32 s77, 29
	s_cbranch_scc0 .LBB0_1313
	s_and_b64 vcc, exec, s[30:31]
	s_cbranch_vccz .LBB0_1316
	s_barrier

.LBB0_1395:
	ds_read_b128 v[170:173], v165
	ds_read_b128 v[174:177], v165 offset:1024
	ds_read_b128 v[178:181], v165 offset:2048
	ds_read_b128 v[182:185], v165 offset:3072
	ds_read_b128 v[186:189], v166
	ds_read_b128 v[192:195], v166 offset:1024
	ds_read_b128 v[196:199], v166 offset:2048
	ds_read_b128 v[200:203], v166 offset:3072
	s_add_u32 s44, s42, 0x100
	s_addc_u32 s45, s43, 0
	s_cmpk_eq_i32 s71, 0x52
	s_cselect_b32 s49, s1, s45
	s_cselect_b32 s48, s0, s44
	s_cselect_b32 s47, s41, s69
	s_cselect_b32 s46, s40, s67
	v_lshl_add_u64 v[144:145], s[42:43], 0, v[136:137]
	s_add_i32 m0, s5, 0xc000
	ds_read_b128 v[204:207], v167
	ds_read_b128 v[208:211], v167 offset:1024
	ds_read_b128 v[212:215], v167 offset:2048
	ds_read_b128 v[216:219], v167 offset:3072
	ds_read_b128 v[220:223], v167 offset:4096
	ds_read_b128 v[224:227], v167 offset:5120
	ds_read_b128 v[228:231], v167 offset:6144
	ds_read_b128 v[232:235], v167 offset:7168
	global_load_lds_dwordx4 v[144:145], off
	v_lshl_add_u64 v[144:145], s[42:43], 0, v[138:139]
	s_add_i32 m0, s5, 0xe000
	s_nop 0
	global_load_lds_dwordx4 v[144:145], off
	s_waitcnt vmcnt(8)
	s_waitcnt lgkmcnt(0)
	s_setprio 1
	s_barrier
	v_mfma_f32_16x16x32_bf16 v[124:127], v[170:173], v[204:207], v[124:127]
	v_mfma_f32_16x16x32_bf16 v[120:123], v[178:181], v[204:207], v[120:123]
	v_mfma_f32_16x16x32_bf16 v[108:111], v[170:173], v[212:215], v[108:111]
	v_mfma_f32_16x16x32_bf16 v[104:107], v[178:181], v[212:215], v[104:107]
	v_mfma_f32_16x16x32_bf16 v[92:95], v[170:173], v[220:223], v[92:95]
	v_mfma_f32_16x16x32_bf16 v[88:91], v[178:181], v[220:223], v[88:91]
	v_mfma_f32_16x16x32_bf16 v[76:79], v[170:173], v[228:231], v[76:79]
	v_mfma_f32_16x16x32_bf16 v[72:75], v[178:181], v[228:231], v[72:75]
	v_mfma_f32_16x16x32_bf16 v[124:127], v[174:177], v[208:211], v[124:127]
	v_mfma_f32_16x16x32_bf16 v[120:123], v[182:185], v[208:211], v[120:123]
	v_mfma_f32_16x16x32_bf16 v[108:111], v[174:177], v[216:219], v[108:111]
	v_mfma_f32_16x16x32_bf16 v[104:107], v[182:185], v[216:219], v[104:107]
	v_mfma_f32_16x16x32_bf16 v[92:95], v[174:177], v[224:227], v[92:95]
	v_mfma_f32_16x16x32_bf16 v[88:91], v[182:185], v[224:227], v[88:91]
	v_mfma_f32_16x16x32_bf16 v[76:79], v[174:177], v[232:235], v[76:79]
	v_mfma_f32_16x16x32_bf16 v[72:75], v[182:185], v[232:235], v[72:75]
	s_setprio 0
	s_setprio 1
	v_mfma_f32_16x16x32_bf16 v[116:119], v[186:189], v[204:207], v[116:119]
	v_mfma_f32_16x16x32_bf16 v[112:115], v[196:199], v[204:207], v[112:115]
	v_mfma_f32_16x16x32_bf16 v[100:103], v[186:189], v[212:215], v[100:103]
	v_mfma_f32_16x16x32_bf16 v[96:99], v[196:199], v[212:215], v[96:99]
	v_mfma_f32_16x16x32_bf16 v[84:87], v[186:189], v[220:223], v[84:87]
	v_mfma_f32_16x16x32_bf16 v[80:83], v[196:199], v[220:223], v[80:83]
	v_mfma_f32_16x16x32_bf16 v[68:71], v[186:189], v[228:231], v[68:71]
	v_mfma_f32_16x16x32_bf16 v[64:67], v[196:199], v[228:231], v[64:67]
	v_mfma_f32_16x16x32_bf16 v[116:119], v[192:195], v[208:211], v[116:119]
	v_mfma_f32_16x16x32_bf16 v[112:115], v[200:203], v[208:211], v[112:115]
	v_mfma_f32_16x16x32_bf16 v[100:103], v[192:195], v[216:219], v[100:103]
	v_mfma_f32_16x16x32_bf16 v[96:99], v[200:203], v[216:219], v[96:99]
	v_mfma_f32_16x16x32_bf16 v[84:87], v[192:195], v[224:227], v[84:87]
	v_mfma_f32_16x16x32_bf16 v[80:83], v[200:203], v[224:227], v[80:83]
	v_mfma_f32_16x16x32_bf16 v[68:71], v[192:195], v[232:235], v[68:71]
	v_mfma_f32_16x16x32_bf16 v[64:67], v[200:203], v[232:235], v[64:67]
	s_barrier
	s_setprio 0
	s_add_i32 s42, s63, s4
	v_lshl_add_u64 v[144:145], s[46:47], 0, v[130:131]
	s_mov_b32 m0, s42
	ds_read_b128 v[204:207], v167 offset:16384
	ds_read_b128 v[208:211], v167 offset:17408
	ds_read_b128 v[212:215], v167 offset:18432
	ds_read_b128 v[216:219], v167 offset:19456
	ds_read_b128 v[220:223], v167 offset:20480
	ds_read_b128 v[224:227], v167 offset:21504
	ds_read_b128 v[228:231], v167 offset:22528
	ds_read_b128 v[232:235], v167 offset:23552
	global_load_lds_dwordx4 v[144:145], off
	s_add_i32 m0, s42, 0x2000
	s_add_u32 s42, s46, 0x158000
	v_lshl_add_u64 v[236:237], s[46:47], 0, v[134:135]
	s_addc_u32 s43, s47, 0
	s_add_i32 s77, s64, s4
	global_load_lds_dwordx4 v[236:237], off
	v_lshl_add_u64 v[238:239], s[42:43], 0, v[130:131]
	s_mov_b32 m0, s77
	v_lshl_add_u64 v[240:241], s[48:49], 0, v[132:133]
	global_load_lds_dwordx4 v[238:239], off
	v_lshl_add_u64 v[238:239], s[42:43], 0, v[134:135]
	s_add_i32 m0, s77, 0x2000
	s_nop 0
	global_load_lds_dwordx4 v[238:239], off
	v_lshl_add_u64 v[238:239], s[48:49], 0, v[128:129]
	s_mov_b32 m0, s5
	s_nop 0
	global_load_lds_dwordx4 v[238:239], off
	s_mov_b32 m0, s52
	s_nop 0
	global_load_lds_dwordx4 v[240:241], off
	s_waitcnt vmcnt(8)
	s_waitcnt lgkmcnt(0)
	s_setprio 1
	s_barrier
	v_mfma_f32_16x16x32_bf16 v[60:63], v[170:173], v[204:207], v[60:63]
	v_mfma_f32_16x16x32_bf16 v[56:59], v[178:181], v[204:207], v[56:59]
	v_mfma_f32_16x16x32_bf16 v[44:47], v[170:173], v[212:215], v[44:47]
	v_mfma_f32_16x16x32_bf16 v[40:43], v[178:181], v[212:215], v[40:43]
	v_mfma_f32_16x16x32_bf16 v[28:31], v[170:173], v[220:223], v[28:31]
	v_mfma_f32_16x16x32_bf16 v[24:27], v[178:181], v[220:223], v[24:27]
	v_mfma_f32_16x16x32_bf16 v[12:15], v[170:173], v[228:231], v[12:15]
	v_mfma_f32_16x16x32_bf16 v[8:11], v[178:181], v[228:231], v[8:11]
	v_mfma_f32_16x16x32_bf16 v[60:63], v[174:177], v[208:211], v[60:63]
	v_mfma_f32_16x16x32_bf16 v[56:59], v[182:185], v[208:211], v[56:59]
	v_mfma_f32_16x16x32_bf16 v[44:47], v[174:177], v[216:219], v[44:47]
	v_mfma_f32_16x16x32_bf16 v[40:43], v[182:185], v[216:219], v[40:43]
	v_mfma_f32_16x16x32_bf16 v[28:31], v[174:177], v[224:227], v[28:31]
	v_mfma_f32_16x16x32_bf16 v[24:27], v[182:185], v[224:227], v[24:27]
	v_mfma_f32_16x16x32_bf16 v[12:15], v[174:177], v[232:235], v[12:15]
	v_mfma_f32_16x16x32_bf16 v[8:11], v[182:185], v[232:235], v[8:11]
	s_setprio 0
	s_setprio 1
	v_mfma_f32_16x16x32_bf16 v[52:55], v[186:189], v[204:207], v[52:55]
	v_mfma_f32_16x16x32_bf16 v[48:51], v[196:199], v[204:207], v[48:51]
	v_mfma_f32_16x16x32_bf16 v[36:39], v[186:189], v[212:215], v[36:39]
	v_mfma_f32_16x16x32_bf16 v[32:35], v[196:199], v[212:215], v[32:35]
	v_mfma_f32_16x16x32_bf16 v[20:23], v[186:189], v[220:223], v[20:23]
	v_mfma_f32_16x16x32_bf16 v[16:19], v[196:199], v[220:223], v[16:19]
	v_mfma_f32_16x16x32_bf16 v[4:7], v[186:189], v[228:231], v[4:7]
	v_mfma_f32_16x16x32_bf16 v[0:3], v[196:199], v[228:231], v[0:3]
	v_mfma_f32_16x16x32_bf16 v[52:55], v[192:195], v[208:211], v[52:55]
	v_mfma_f32_16x16x32_bf16 v[48:51], v[200:203], v[208:211], v[48:51]
	v_mfma_f32_16x16x32_bf16 v[36:39], v[192:195], v[216:219], v[36:39]
	v_mfma_f32_16x16x32_bf16 v[32:35], v[200:203], v[216:219], v[32:35]
	v_mfma_f32_16x16x32_bf16 v[20:23], v[192:195], v[224:227], v[20:23]
	v_mfma_f32_16x16x32_bf16 v[16:19], v[200:203], v[224:227], v[16:19]
	v_mfma_f32_16x16x32_bf16 v[4:7], v[192:195], v[232:235], v[4:7]
	v_mfma_f32_16x16x32_bf16 v[0:3], v[200:203], v[232:235], v[0:3]
	s_barrier
	s_setprio 0
	s_add_i32 s77, 0, 0x18000
	s_add_i32 s84, 0, 0x1c000
	v_add_u32_e32 v182, s77, v147
	v_add_u32_e32 v200, s84, v147
	ds_read_b128 v[170:173], v182
	ds_read_b128 v[174:177], v182 offset:1024
	ds_read_b128 v[178:181], v182 offset:2048
	ds_read_b128 v[182:185], v182 offset:3072
	ds_read_b128 v[186:189], v200
	ds_read_b128 v[192:195], v200 offset:1024
	ds_read_b128 v[196:199], v200 offset:2048
	ds_read_b128 v[200:203], v200 offset:3072
	s_add_u32 s42, s48, 0x158000
	s_addc_u32 s43, s49, 0
	s_mov_b32 m0, s53
	v_lshl_add_u64 v[242:243], s[42:43], 0, v[128:129]
	ds_read_b128 v[204:207], v167 offset:32768
	ds_read_b128 v[208:211], v167 offset:33792
	ds_read_b128 v[212:215], v167 offset:34816
	ds_read_b128 v[216:219], v167 offset:35840
	ds_read_b128 v[220:223], v167 offset:36864
	ds_read_b128 v[224:227], v167 offset:37888
	ds_read_b128 v[228:231], v167 offset:38912
	ds_read_b128 v[232:235], v167 offset:39936
	global_load_lds_dwordx4 v[242:243], off
	v_lshl_add_u64 v[242:243], s[42:43], 0, v[132:133]
	s_mov_b32 m0, s54
	s_nop 0
	global_load_lds_dwordx4 v[242:243], off
	s_waitcnt vmcnt(8)
	s_waitcnt lgkmcnt(0)
	s_setprio 1
	s_barrier
	v_mfma_f32_16x16x32_bf16 v[124:127], v[170:173], v[204:207], v[124:127]
	v_mfma_f32_16x16x32_bf16 v[120:123], v[178:181], v[204:207], v[120:123]
	v_mfma_f32_16x16x32_bf16 v[108:111], v[170:173], v[212:215], v[108:111]
	v_mfma_f32_16x16x32_bf16 v[104:107], v[178:181], v[212:215], v[104:107]
	v_mfma_f32_16x16x32_bf16 v[92:95], v[170:173], v[220:223], v[92:95]
	v_mfma_f32_16x16x32_bf16 v[88:91], v[178:181], v[220:223], v[88:91]
	v_mfma_f32_16x16x32_bf16 v[76:79], v[170:173], v[228:231], v[76:79]
	v_mfma_f32_16x16x32_bf16 v[72:75], v[178:181], v[228:231], v[72:75]
	v_mfma_f32_16x16x32_bf16 v[124:127], v[174:177], v[208:211], v[124:127]
	v_mfma_f32_16x16x32_bf16 v[120:123], v[182:185], v[208:211], v[120:123]
	v_mfma_f32_16x16x32_bf16 v[108:111], v[174:177], v[216:219], v[108:111]
	v_mfma_f32_16x16x32_bf16 v[104:107], v[182:185], v[216:219], v[104:107]
	v_mfma_f32_16x16x32_bf16 v[92:95], v[174:177], v[224:227], v[92:95]
	v_mfma_f32_16x16x32_bf16 v[88:91], v[182:185], v[224:227], v[88:91]
	v_mfma_f32_16x16x32_bf16 v[76:79], v[174:177], v[232:235], v[76:79]
	v_mfma_f32_16x16x32_bf16 v[72:75], v[182:185], v[232:235], v[72:75]
	s_setprio 0
	s_setprio 1
	v_mfma_f32_16x16x32_bf16 v[116:119], v[186:189], v[204:207], v[116:119]
	v_mfma_f32_16x16x32_bf16 v[112:115], v[196:199], v[204:207], v[112:115]
	v_mfma_f32_16x16x32_bf16 v[100:103], v[186:189], v[212:215], v[100:103]
	v_mfma_f32_16x16x32_bf16 v[96:99], v[196:199], v[212:215], v[96:99]
	v_mfma_f32_16x16x32_bf16 v[84:87], v[186:189], v[220:223], v[84:87]
	v_mfma_f32_16x16x32_bf16 v[80:83], v[196:199], v[220:223], v[80:83]
	v_mfma_f32_16x16x32_bf16 v[68:71], v[186:189], v[228:231], v[68:71]
	v_mfma_f32_16x16x32_bf16 v[64:67], v[196:199], v[228:231], v[64:67]
	v_mfma_f32_16x16x32_bf16 v[116:119], v[192:195], v[208:211], v[116:119]
	v_mfma_f32_16x16x32_bf16 v[112:115], v[200:203], v[208:211], v[112:115]
	v_mfma_f32_16x16x32_bf16 v[100:103], v[192:195], v[216:219], v[100:103]
	v_mfma_f32_16x16x32_bf16 v[96:99], v[200:203], v[216:219], v[96:99]
	v_mfma_f32_16x16x32_bf16 v[84:87], v[192:195], v[224:227], v[84:87]
	v_mfma_f32_16x16x32_bf16 v[80:83], v[200:203], v[224:227], v[80:83]
	v_mfma_f32_16x16x32_bf16 v[68:71], v[192:195], v[232:235], v[68:71]
	v_mfma_f32_16x16x32_bf16 v[64:67], v[200:203], v[232:235], v[64:67]
	s_barrier
	s_setprio 0
	s_add_i32 s42, s77, s4
	v_lshl_add_u64 v[144:145], v[144:145], 0, s[36:37]
	s_mov_b32 m0, s42
	ds_read_b128 v[204:207], v167 offset:49152
	ds_read_b128 v[208:211], v167 offset:50176
	ds_read_b128 v[212:215], v167 offset:51200
	ds_read_b128 v[216:219], v167 offset:52224
	ds_read_b128 v[220:223], v167 offset:53248
	ds_read_b128 v[224:227], v167 offset:54272
	ds_read_b128 v[228:231], v167 offset:55296
	ds_read_b128 v[232:235], v167 offset:56320
	global_load_lds_dwordx4 v[144:145], off
	s_add_i32 m0, s42, 0x2000
	s_add_u32 s42, s46, 0x158080
	v_lshl_add_u64 v[144:145], v[236:237], 0, s[36:37]
	s_addc_u32 s43, s47, 0
	s_add_i32 s46, s84, s4
	global_load_lds_dwordx4 v[144:145], off
	v_lshl_add_u64 v[144:145], s[42:43], 0, v[130:131]
	s_mov_b32 m0, s46
	s_nop 0
	global_load_lds_dwordx4 v[144:145], off
	v_lshl_add_u64 v[144:145], s[42:43], 0, v[134:135]
	s_add_i32 m0, s46, 0x2000
	s_nop 0
	global_load_lds_dwordx4 v[144:145], off
	v_lshl_add_u64 v[144:145], v[238:239], 0, s[36:37]
	s_mov_b32 m0, s56
	s_nop 0
	global_load_lds_dwordx4 v[144:145], off
	v_lshl_add_u64 v[144:145], v[240:241], 0, s[36:37]
	s_mov_b32 m0, s57
	s_nop 0
	global_load_lds_dwordx4 v[144:145], off
	s_waitcnt vmcnt(8)
	s_waitcnt lgkmcnt(0)
	s_setprio 1
	s_barrier
	v_mfma_f32_16x16x32_bf16 v[60:63], v[170:173], v[204:207], v[60:63]
	v_mfma_f32_16x16x32_bf16 v[56:59], v[178:181], v[204:207], v[56:59]
	v_mfma_f32_16x16x32_bf16 v[44:47], v[170:173], v[212:215], v[44:47]
	v_mfma_f32_16x16x32_bf16 v[40:43], v[178:181], v[212:215], v[40:43]
	v_mfma_f32_16x16x32_bf16 v[28:31], v[170:173], v[220:223], v[28:31]
	v_mfma_f32_16x16x32_bf16 v[24:27], v[178:181], v[220:223], v[24:27]
	v_mfma_f32_16x16x32_bf16 v[12:15], v[170:173], v[228:231], v[12:15]
	v_mfma_f32_16x16x32_bf16 v[8:11], v[178:181], v[228:231], v[8:11]
	v_mfma_f32_16x16x32_bf16 v[60:63], v[174:177], v[208:211], v[60:63]
	v_mfma_f32_16x16x32_bf16 v[56:59], v[182:185], v[208:211], v[56:59]
	v_mfma_f32_16x16x32_bf16 v[44:47], v[174:177], v[216:219], v[44:47]
	v_mfma_f32_16x16x32_bf16 v[40:43], v[182:185], v[216:219], v[40:43]
	v_mfma_f32_16x16x32_bf16 v[28:31], v[174:177], v[224:227], v[28:31]
	v_mfma_f32_16x16x32_bf16 v[24:27], v[182:185], v[224:227], v[24:27]
	v_mfma_f32_16x16x32_bf16 v[12:15], v[174:177], v[232:235], v[12:15]
	v_mfma_f32_16x16x32_bf16 v[8:11], v[182:185], v[232:235], v[8:11]
	s_setprio 0
	s_setprio 1
	v_mfma_f32_16x16x32_bf16 v[52:55], v[186:189], v[204:207], v[52:55]
	v_mfma_f32_16x16x32_bf16 v[48:51], v[196:199], v[204:207], v[48:51]
	v_mfma_f32_16x16x32_bf16 v[36:39], v[186:189], v[212:215], v[36:39]
	v_mfma_f32_16x16x32_bf16 v[32:35], v[196:199], v[212:215], v[32:35]
	v_mfma_f32_16x16x32_bf16 v[20:23], v[186:189], v[220:223], v[20:23]
	v_mfma_f32_16x16x32_bf16 v[16:19], v[196:199], v[220:223], v[16:19]
	v_mfma_f32_16x16x32_bf16 v[4:7], v[186:189], v[228:231], v[4:7]
	v_mfma_f32_16x16x32_bf16 v[0:3], v[196:199], v[228:231], v[0:3]
	v_mfma_f32_16x16x32_bf16 v[52:55], v[192:195], v[208:211], v[52:55]
	v_mfma_f32_16x16x32_bf16 v[48:51], v[200:203], v[208:211], v[48:51]
	v_mfma_f32_16x16x32_bf16 v[36:39], v[192:195], v[216:219], v[36:39]
	v_mfma_f32_16x16x32_bf16 v[32:35], v[200:203], v[216:219], v[32:35]
	v_mfma_f32_16x16x32_bf16 v[20:23], v[192:195], v[224:227], v[20:23]
	v_mfma_f32_16x16x32_bf16 v[16:19], v[200:203], v[224:227], v[16:19]
	v_mfma_f32_16x16x32_bf16 v[4:7], v[192:195], v[232:235], v[4:7]
	v_mfma_f32_16x16x32_bf16 v[0:3], v[200:203], v[232:235], v[0:3]
	s_barrier
	s_setprio 0
	s_add_i32 s71, s71, 2
	s_add_u32 s67, s67, 0x100
	s_addc_u32 s69, s69, 0
	s_cmpk_gt_u32 s71, 0x53
	s_mov_b64 s[42:43], s[44:45]
	s_cbranch_scc0 .LBB0_1395
	s_and_b64 vcc, exec, s[38:39]
	s_cbranch_vccz .LBB0_1398
	s_barrier

.LBB0_1481:
	ds_read_b128 v[144:147], v153
	ds_read_b128 v[158:161], v153 offset:1024
	ds_read_b128 v[162:165], v153 offset:2048
	ds_read_b128 v[166:169], v153 offset:3072
	ds_read_b128 v[170:173], v154
	ds_read_b128 v[174:177], v154 offset:1024
	ds_read_b128 v[178:181], v154 offset:2048
	ds_read_b128 v[182:185], v154 offset:3072
	s_add_u32 s44, s42, 0xfff80080
	s_addc_u32 s45, s43, -1
	s_cmp_eq_u32 s77, 28
	s_cselect_b32 s47, s37, s45
	s_cselect_b32 s46, s66, s44
	s_cselect_b32 s45, s35, s71
	s_cselect_b32 s44, s67, s69
	v_lshl_add_u64 v[148:149], s[42:43], 0, v[136:137]
	s_add_i32 m0, s49, 0xc000
	ds_read_b128 v[186:189], v155
	ds_read_b128 v[192:195], v155 offset:1024
	ds_read_b128 v[196:199], v155 offset:2048
	ds_read_b128 v[200:203], v155 offset:3072
	ds_read_b128 v[204:207], v155 offset:4096
	ds_read_b128 v[208:211], v155 offset:5120
	ds_read_b128 v[212:215], v155 offset:6144
	ds_read_b128 v[216:219], v155 offset:7168
	global_load_lds_dwordx4 v[148:149], off
	v_lshl_add_u64 v[148:149], s[42:43], 0, v[138:139]
	s_add_i32 m0, s49, 0xe000
	s_nop 0
	global_load_lds_dwordx4 v[148:149], off
	s_waitcnt vmcnt(8)
	s_waitcnt lgkmcnt(0)
	s_setprio 1
	s_barrier
	v_mfma_f32_16x16x32_bf16 v[124:127], v[144:147], v[186:189], v[124:127]
	v_mfma_f32_16x16x32_bf16 v[120:123], v[162:165], v[186:189], v[120:123]
	v_mfma_f32_16x16x32_bf16 v[108:111], v[144:147], v[196:199], v[108:111]
	v_mfma_f32_16x16x32_bf16 v[104:107], v[162:165], v[196:199], v[104:107]
	v_mfma_f32_16x16x32_bf16 v[92:95], v[144:147], v[204:207], v[92:95]
	v_mfma_f32_16x16x32_bf16 v[88:91], v[162:165], v[204:207], v[88:91]
	v_mfma_f32_16x16x32_bf16 v[76:79], v[144:147], v[212:215], v[76:79]
	v_mfma_f32_16x16x32_bf16 v[72:75], v[162:165], v[212:215], v[72:75]
	v_mfma_f32_16x16x32_bf16 v[124:127], v[158:161], v[192:195], v[124:127]
	v_mfma_f32_16x16x32_bf16 v[120:123], v[166:169], v[192:195], v[120:123]
	v_mfma_f32_16x16x32_bf16 v[108:111], v[158:161], v[200:203], v[108:111]
	v_mfma_f32_16x16x32_bf16 v[104:107], v[166:169], v[200:203], v[104:107]
	v_mfma_f32_16x16x32_bf16 v[92:95], v[158:161], v[208:211], v[92:95]
	v_mfma_f32_16x16x32_bf16 v[88:91], v[166:169], v[208:211], v[88:91]
	v_mfma_f32_16x16x32_bf16 v[76:79], v[158:161], v[216:219], v[76:79]
	v_mfma_f32_16x16x32_bf16 v[72:75], v[166:169], v[216:219], v[72:75]
	s_setprio 0
	s_setprio 1
	v_mfma_f32_16x16x32_bf16 v[116:119], v[170:173], v[186:189], v[116:119]
	v_mfma_f32_16x16x32_bf16 v[112:115], v[178:181], v[186:189], v[112:115]
	v_mfma_f32_16x16x32_bf16 v[100:103], v[170:173], v[196:199], v[100:103]
	v_mfma_f32_16x16x32_bf16 v[96:99], v[178:181], v[196:199], v[96:99]
	v_mfma_f32_16x16x32_bf16 v[84:87], v[170:173], v[204:207], v[84:87]
	v_mfma_f32_16x16x32_bf16 v[80:83], v[178:181], v[204:207], v[80:83]
	v_mfma_f32_16x16x32_bf16 v[68:71], v[170:173], v[212:215], v[68:71]
	v_mfma_f32_16x16x32_bf16 v[64:67], v[178:181], v[212:215], v[64:67]
	v_mfma_f32_16x16x32_bf16 v[116:119], v[174:177], v[192:195], v[116:119]
	v_mfma_f32_16x16x32_bf16 v[112:115], v[182:185], v[192:195], v[112:115]
	v_mfma_f32_16x16x32_bf16 v[100:103], v[174:177], v[200:203], v[100:103]
	v_mfma_f32_16x16x32_bf16 v[96:99], v[182:185], v[200:203], v[96:99]
	v_mfma_f32_16x16x32_bf16 v[84:87], v[174:177], v[208:211], v[84:87]
	v_mfma_f32_16x16x32_bf16 v[80:83], v[182:185], v[208:211], v[80:83]
	v_mfma_f32_16x16x32_bf16 v[68:71], v[174:177], v[216:219], v[68:71]
	v_mfma_f32_16x16x32_bf16 v[64:67], v[182:185], v[216:219], v[64:67]
	s_barrier
	s_setprio 0
	s_add_i32 s80, s62, s4
	v_lshl_add_u64 v[148:149], s[44:45], 0, v[132:133]
	s_mov_b32 m0, s80
	ds_read_b128 v[186:189], v155 offset:16384
	ds_read_b128 v[192:195], v155 offset:17408
	ds_read_b128 v[196:199], v155 offset:18432
	ds_read_b128 v[200:203], v155 offset:19456
	ds_read_b128 v[204:207], v155 offset:20480
	ds_read_b128 v[208:211], v155 offset:21504
	ds_read_b128 v[212:215], v155 offset:22528
	ds_read_b128 v[216:219], v155 offset:23552
	global_load_lds_dwordx4 v[148:149], off
	s_add_i32 m0, s80, 0x2000
	s_add_u32 s80, s44, 0x80000
	v_lshl_add_u64 v[220:221], s[44:45], 0, v[128:129]
	s_addc_u32 s81, s45, 0
	s_add_i32 s84, s63, s4
	global_load_lds_dwordx4 v[220:221], off
	v_lshl_add_u64 v[222:223], s[80:81], 0, v[132:133]
	s_mov_b32 m0, s84
	v_lshl_add_u64 v[224:225], s[46:47], 0, v[130:131]
	global_load_lds_dwordx4 v[222:223], off
	v_lshl_add_u64 v[222:223], s[80:81], 0, v[128:129]
	s_add_i32 m0, s84, 0x2000
	s_nop 0
	global_load_lds_dwordx4 v[222:223], off
	v_lshl_add_u64 v[222:223], s[46:47], 0, v[134:135]
	s_mov_b32 m0, s49
	s_nop 0
	global_load_lds_dwordx4 v[222:223], off
	s_mov_b32 m0, s52
	s_nop 0
	global_load_lds_dwordx4 v[224:225], off
	s_waitcnt vmcnt(8)
	s_waitcnt lgkmcnt(0)
	s_setprio 1
	s_barrier
	v_mfma_f32_16x16x32_bf16 v[60:63], v[144:147], v[186:189], v[60:63]
	v_mfma_f32_16x16x32_bf16 v[56:59], v[162:165], v[186:189], v[56:59]
	v_mfma_f32_16x16x32_bf16 v[44:47], v[144:147], v[196:199], v[44:47]
	v_mfma_f32_16x16x32_bf16 v[40:43], v[162:165], v[196:199], v[40:43]
	v_mfma_f32_16x16x32_bf16 v[28:31], v[144:147], v[204:207], v[28:31]
	v_mfma_f32_16x16x32_bf16 v[24:27], v[162:165], v[204:207], v[24:27]
	v_mfma_f32_16x16x32_bf16 v[12:15], v[144:147], v[212:215], v[12:15]
	v_mfma_f32_16x16x32_bf16 v[8:11], v[162:165], v[212:215], v[8:11]
	v_mfma_f32_16x16x32_bf16 v[60:63], v[158:161], v[192:195], v[60:63]
	v_mfma_f32_16x16x32_bf16 v[56:59], v[166:169], v[192:195], v[56:59]
	v_mfma_f32_16x16x32_bf16 v[44:47], v[158:161], v[200:203], v[44:47]
	v_mfma_f32_16x16x32_bf16 v[40:43], v[166:169], v[200:203], v[40:43]
	v_mfma_f32_16x16x32_bf16 v[28:31], v[158:161], v[208:211], v[28:31]
	v_mfma_f32_16x16x32_bf16 v[24:27], v[166:169], v[208:211], v[24:27]
	v_mfma_f32_16x16x32_bf16 v[12:15], v[158:161], v[216:219], v[12:15]
	v_mfma_f32_16x16x32_bf16 v[8:11], v[166:169], v[216:219], v[8:11]
	s_setprio 0
	s_setprio 1
	v_mfma_f32_16x16x32_bf16 v[52:55], v[170:173], v[186:189], v[52:55]
	v_mfma_f32_16x16x32_bf16 v[48:51], v[178:181], v[186:189], v[48:51]
	v_mfma_f32_16x16x32_bf16 v[36:39], v[170:173], v[196:199], v[36:39]
	v_mfma_f32_16x16x32_bf16 v[32:35], v[178:181], v[196:199], v[32:35]
	v_mfma_f32_16x16x32_bf16 v[20:23], v[170:173], v[204:207], v[20:23]
	v_mfma_f32_16x16x32_bf16 v[16:19], v[178:181], v[204:207], v[16:19]
	v_mfma_f32_16x16x32_bf16 v[4:7], v[170:173], v[212:215], v[4:7]
	v_mfma_f32_16x16x32_bf16 v[0:3], v[178:181], v[212:215], v[0:3]
	v_mfma_f32_16x16x32_bf16 v[52:55], v[174:177], v[192:195], v[52:55]
	v_mfma_f32_16x16x32_bf16 v[48:51], v[182:185], v[192:195], v[48:51]
	v_mfma_f32_16x16x32_bf16 v[36:39], v[174:177], v[200:203], v[36:39]
	v_mfma_f32_16x16x32_bf16 v[32:35], v[182:185], v[200:203], v[32:35]
	v_mfma_f32_16x16x32_bf16 v[20:23], v[174:177], v[208:211], v[20:23]
	v_mfma_f32_16x16x32_bf16 v[16:19], v[182:185], v[208:211], v[16:19]
	v_mfma_f32_16x16x32_bf16 v[4:7], v[174:177], v[216:219], v[4:7]
	v_mfma_f32_16x16x32_bf16 v[0:3], v[182:185], v[216:219], v[0:3]
	s_barrier
	s_setprio 0
	s_add_i32 s80, 0, 0x18000
	v_add_u32_e32 v157, s80, v151
	s_add_i32 s81, 0, 0x1c000
	ds_read_b128 v[144:147], v157
	ds_read_b128 v[158:161], v157 offset:1024
	ds_read_b128 v[162:165], v157 offset:2048
	ds_read_b128 v[166:169], v157 offset:3072
	v_add_u32_e32 v157, s81, v151
	ds_read_b128 v[170:173], v157
	ds_read_b128 v[174:177], v157 offset:1024
	ds_read_b128 v[178:181], v157 offset:2048
	ds_read_b128 v[182:185], v157 offset:3072
	s_add_u32 s46, s46, 0x80000
	s_addc_u32 s47, s47, 0
	s_mov_b32 m0, s53
	v_lshl_add_u64 v[226:227], s[46:47], 0, v[134:135]
	ds_read_b128 v[186:189], v155 offset:32768
	ds_read_b128 v[192:195], v155 offset:33792
	ds_read_b128 v[196:199], v155 offset:34816
	ds_read_b128 v[200:203], v155 offset:35840
	ds_read_b128 v[204:207], v155 offset:36864
	ds_read_b128 v[208:211], v155 offset:37888
	ds_read_b128 v[212:215], v155 offset:38912
	ds_read_b128 v[216:219], v155 offset:39936
	global_load_lds_dwordx4 v[226:227], off
	v_lshl_add_u64 v[226:227], s[46:47], 0, v[130:131]
	s_mov_b32 m0, s54
	s_nop 0
	global_load_lds_dwordx4 v[226:227], off
	s_waitcnt vmcnt(8)
	s_waitcnt lgkmcnt(0)
	s_setprio 1
	s_barrier
	v_mfma_f32_16x16x32_bf16 v[124:127], v[144:147], v[186:189], v[124:127]
	v_mfma_f32_16x16x32_bf16 v[120:123], v[162:165], v[186:189], v[120:123]
	v_mfma_f32_16x16x32_bf16 v[108:111], v[144:147], v[196:199], v[108:111]
	v_mfma_f32_16x16x32_bf16 v[104:107], v[162:165], v[196:199], v[104:107]
	v_mfma_f32_16x16x32_bf16 v[92:95], v[144:147], v[204:207], v[92:95]
	v_mfma_f32_16x16x32_bf16 v[88:91], v[162:165], v[204:207], v[88:91]
	v_mfma_f32_16x16x32_bf16 v[76:79], v[144:147], v[212:215], v[76:79]
	v_mfma_f32_16x16x32_bf16 v[72:75], v[162:165], v[212:215], v[72:75]
	v_mfma_f32_16x16x32_bf16 v[124:127], v[158:161], v[192:195], v[124:127]
	v_mfma_f32_16x16x32_bf16 v[120:123], v[166:169], v[192:195], v[120:123]
	v_mfma_f32_16x16x32_bf16 v[108:111], v[158:161], v[200:203], v[108:111]
	v_mfma_f32_16x16x32_bf16 v[104:107], v[166:169], v[200:203], v[104:107]
	v_mfma_f32_16x16x32_bf16 v[92:95], v[158:161], v[208:211], v[92:95]
	v_mfma_f32_16x16x32_bf16 v[88:91], v[166:169], v[208:211], v[88:91]
	v_mfma_f32_16x16x32_bf16 v[76:79], v[158:161], v[216:219], v[76:79]
	v_mfma_f32_16x16x32_bf16 v[72:75], v[166:169], v[216:219], v[72:75]
	s_setprio 0
	s_setprio 1
	v_mfma_f32_16x16x32_bf16 v[116:119], v[170:173], v[186:189], v[116:119]
	v_mfma_f32_16x16x32_bf16 v[112:115], v[178:181], v[186:189], v[112:115]
	v_mfma_f32_16x16x32_bf16 v[100:103], v[170:173], v[196:199], v[100:103]
	v_mfma_f32_16x16x32_bf16 v[96:99], v[178:181], v[196:199], v[96:99]
	v_mfma_f32_16x16x32_bf16 v[84:87], v[170:173], v[204:207], v[84:87]
	v_mfma_f32_16x16x32_bf16 v[80:83], v[178:181], v[204:207], v[80:83]
	v_mfma_f32_16x16x32_bf16 v[68:71], v[170:173], v[212:215], v[68:71]
	v_mfma_f32_16x16x32_bf16 v[64:67], v[178:181], v[212:215], v[64:67]
	v_mfma_f32_16x16x32_bf16 v[116:119], v[174:177], v[192:195], v[116:119]
	v_mfma_f32_16x16x32_bf16 v[112:115], v[182:185], v[192:195], v[112:115]
	v_mfma_f32_16x16x32_bf16 v[100:103], v[174:177], v[200:203], v[100:103]
	v_mfma_f32_16x16x32_bf16 v[96:99], v[182:185], v[200:203], v[96:99]
	v_mfma_f32_16x16x32_bf16 v[84:87], v[174:177], v[208:211], v[84:87]
	v_mfma_f32_16x16x32_bf16 v[80:83], v[182:185], v[208:211], v[80:83]
	v_mfma_f32_16x16x32_bf16 v[68:71], v[174:177], v[216:219], v[68:71]
	v_mfma_f32_16x16x32_bf16 v[64:67], v[182:185], v[216:219], v[64:67]
	s_barrier
	s_setprio 0
	s_add_i32 s46, s80, s4
	v_lshl_add_u64 v[148:149], v[148:149], 0, s[16:17]
	s_mov_b32 m0, s46
	ds_read_b128 v[186:189], v155 offset:49152
	ds_read_b128 v[192:195], v155 offset:50176
	ds_read_b128 v[196:199], v155 offset:51200
	ds_read_b128 v[200:203], v155 offset:52224
	ds_read_b128 v[204:207], v155 offset:53248
	ds_read_b128 v[208:211], v155 offset:54272
	ds_read_b128 v[212:215], v155 offset:55296
	ds_read_b128 v[216:219], v155 offset:56320
	global_load_lds_dwordx4 v[148:149], off
	s_add_i32 m0, s46, 0x2000
	s_add_u32 s44, s44, 0x80080
	v_lshl_add_u64 v[148:149], v[220:221], 0, s[16:17]
	s_addc_u32 s45, s45, 0
	s_add_i32 s46, s81, s4
	global_load_lds_dwordx4 v[148:149], off
	v_lshl_add_u64 v[148:149], s[44:45], 0, v[132:133]
	s_mov_b32 m0, s46
	s_nop 0
	global_load_lds_dwordx4 v[148:149], off
	v_lshl_add_u64 v[148:149], s[44:45], 0, v[128:129]
	s_add_i32 m0, s46, 0x2000
	s_nop 0
	global_load_lds_dwordx4 v[148:149], off
	v_lshl_add_u64 v[148:149], v[222:223], 0, s[16:17]
	s_mov_b32 m0, s56
	s_nop 0
	global_load_lds_dwordx4 v[148:149], off
	v_lshl_add_u64 v[148:149], v[224:225], 0, s[16:17]
	s_mov_b32 m0, s57
	s_nop 0
	global_load_lds_dwordx4 v[148:149], off
	s_waitcnt vmcnt(8)
	s_waitcnt lgkmcnt(0)
	s_setprio 1
	s_barrier
	v_mfma_f32_16x16x32_bf16 v[60:63], v[144:147], v[186:189], v[60:63]
	v_mfma_f32_16x16x32_bf16 v[56:59], v[162:165], v[186:189], v[56:59]
	v_mfma_f32_16x16x32_bf16 v[44:47], v[144:147], v[196:199], v[44:47]
	v_mfma_f32_16x16x32_bf16 v[40:43], v[162:165], v[196:199], v[40:43]
	v_mfma_f32_16x16x32_bf16 v[28:31], v[144:147], v[204:207], v[28:31]
	v_mfma_f32_16x16x32_bf16 v[24:27], v[162:165], v[204:207], v[24:27]
	v_mfma_f32_16x16x32_bf16 v[12:15], v[144:147], v[212:215], v[12:15]
	v_mfma_f32_16x16x32_bf16 v[8:11], v[162:165], v[212:215], v[8:11]
	v_mfma_f32_16x16x32_bf16 v[60:63], v[158:161], v[192:195], v[60:63]
	v_mfma_f32_16x16x32_bf16 v[56:59], v[166:169], v[192:195], v[56:59]
	v_mfma_f32_16x16x32_bf16 v[44:47], v[158:161], v[200:203], v[44:47]
	v_mfma_f32_16x16x32_bf16 v[40:43], v[166:169], v[200:203], v[40:43]
	v_mfma_f32_16x16x32_bf16 v[28:31], v[158:161], v[208:211], v[28:31]
	v_mfma_f32_16x16x32_bf16 v[24:27], v[166:169], v[208:211], v[24:27]
	v_mfma_f32_16x16x32_bf16 v[12:15], v[158:161], v[216:219], v[12:15]
	v_mfma_f32_16x16x32_bf16 v[8:11], v[166:169], v[216:219], v[8:11]
	s_setprio 0
	s_setprio 1
	v_mfma_f32_16x16x32_bf16 v[52:55], v[170:173], v[186:189], v[52:55]
	v_mfma_f32_16x16x32_bf16 v[48:51], v[178:181], v[186:189], v[48:51]
	v_mfma_f32_16x16x32_bf16 v[36:39], v[170:173], v[196:199], v[36:39]
	v_mfma_f32_16x16x32_bf16 v[32:35], v[178:181], v[196:199], v[32:35]
	v_mfma_f32_16x16x32_bf16 v[20:23], v[170:173], v[204:207], v[20:23]
	v_mfma_f32_16x16x32_bf16 v[16:19], v[178:181], v[204:207], v[16:19]
	v_mfma_f32_16x16x32_bf16 v[4:7], v[170:173], v[212:215], v[4:7]
	v_mfma_f32_16x16x32_bf16 v[0:3], v[178:181], v[212:215], v[0:3]
	v_mfma_f32_16x16x32_bf16 v[52:55], v[174:177], v[192:195], v[52:55]
	v_mfma_f32_16x16x32_bf16 v[48:51], v[182:185], v[192:195], v[48:51]
	v_mfma_f32_16x16x32_bf16 v[36:39], v[174:177], v[200:203], v[36:39]
	v_mfma_f32_16x16x32_bf16 v[32:35], v[182:185], v[200:203], v[32:35]
	v_mfma_f32_16x16x32_bf16 v[20:23], v[174:177], v[208:211], v[20:23]
	v_mfma_f32_16x16x32_bf16 v[16:19], v[182:185], v[208:211], v[16:19]
	v_mfma_f32_16x16x32_bf16 v[4:7], v[174:177], v[216:219], v[4:7]
	v_mfma_f32_16x16x32_bf16 v[0:3], v[182:185], v[216:219], v[0:3]
	s_barrier
	s_setprio 0
	s_add_i32 s77, s77, 2
	s_add_u32 s42, s42, 0x100
	s_addc_u32 s43, s43, 0
	s_add_u32 s69, s69, 0x100
	s_addc_u32 s71, s71, 0
	s_cmp_gt_u32 s77, 29
	s_cbranch_scc0 .LBB0_1481
	s_and_b64 vcc, exec, s[30:31]
	s_cbranch_vccz .LBB0_1484
	s_barrier

.LBB0_1683:
	ds_read_b128 v[170:173], v165
	ds_read_b128 v[174:177], v165 offset:1024
	ds_read_b128 v[178:181], v165 offset:2048
	ds_read_b128 v[182:185], v165 offset:3072
	ds_read_b128 v[186:189], v166
	ds_read_b128 v[192:195], v166 offset:1024
	ds_read_b128 v[196:199], v166 offset:2048
	ds_read_b128 v[200:203], v166 offset:3072
	s_add_u32 s44, s42, 0xfff80080
	s_addc_u32 s45, s43, -1
	s_cmp_eq_u32 s67, 28
	s_cselect_b32 s47, s1, s45
	s_cselect_b32 s46, s35, s44
	s_cselect_b32 s45, s31, s66
	s_cselect_b32 s44, s41, s65
	v_lshl_add_u64 v[144:145], s[42:43], 0, v[136:137]
	s_add_i32 m0, s49, 0xc000
	ds_read_b128 v[204:207], v167
	ds_read_b128 v[208:211], v167 offset:1024
	ds_read_b128 v[212:215], v167 offset:2048
	ds_read_b128 v[216:219], v167 offset:3072
	ds_read_b128 v[220:223], v167 offset:4096
	ds_read_b128 v[224:227], v167 offset:5120
	ds_read_b128 v[228:231], v167 offset:6144
	ds_read_b128 v[232:235], v167 offset:7168
	global_load_lds_dwordx4 v[144:145], off
	v_lshl_add_u64 v[144:145], s[42:43], 0, v[138:139]
	s_add_i32 m0, s49, 0xe000
	s_nop 0
	global_load_lds_dwordx4 v[144:145], off
	s_waitcnt vmcnt(8)
	s_waitcnt lgkmcnt(0)
	s_setprio 1
	s_barrier
	v_mfma_f32_16x16x32_bf16 v[124:127], v[170:173], v[204:207], v[124:127]
	v_mfma_f32_16x16x32_bf16 v[120:123], v[178:181], v[204:207], v[120:123]
	v_mfma_f32_16x16x32_bf16 v[108:111], v[170:173], v[212:215], v[108:111]
	v_mfma_f32_16x16x32_bf16 v[104:107], v[178:181], v[212:215], v[104:107]
	v_mfma_f32_16x16x32_bf16 v[92:95], v[170:173], v[220:223], v[92:95]
	v_mfma_f32_16x16x32_bf16 v[88:91], v[178:181], v[220:223], v[88:91]
	v_mfma_f32_16x16x32_bf16 v[76:79], v[170:173], v[228:231], v[76:79]
	v_mfma_f32_16x16x32_bf16 v[72:75], v[178:181], v[228:231], v[72:75]
	v_mfma_f32_16x16x32_bf16 v[124:127], v[174:177], v[208:211], v[124:127]
	v_mfma_f32_16x16x32_bf16 v[120:123], v[182:185], v[208:211], v[120:123]
	v_mfma_f32_16x16x32_bf16 v[108:111], v[174:177], v[216:219], v[108:111]
	v_mfma_f32_16x16x32_bf16 v[104:107], v[182:185], v[216:219], v[104:107]
	v_mfma_f32_16x16x32_bf16 v[92:95], v[174:177], v[224:227], v[92:95]
	v_mfma_f32_16x16x32_bf16 v[88:91], v[182:185], v[224:227], v[88:91]
	v_mfma_f32_16x16x32_bf16 v[76:79], v[174:177], v[232:235], v[76:79]
	v_mfma_f32_16x16x32_bf16 v[72:75], v[182:185], v[232:235], v[72:75]
	s_setprio 0
	s_setprio 1
	v_mfma_f32_16x16x32_bf16 v[116:119], v[186:189], v[204:207], v[116:119]
	v_mfma_f32_16x16x32_bf16 v[112:115], v[196:199], v[204:207], v[112:115]
	v_mfma_f32_16x16x32_bf16 v[100:103], v[186:189], v[212:215], v[100:103]
	v_mfma_f32_16x16x32_bf16 v[96:99], v[196:199], v[212:215], v[96:99]
	v_mfma_f32_16x16x32_bf16 v[84:87], v[186:189], v[220:223], v[84:87]
	v_mfma_f32_16x16x32_bf16 v[80:83], v[196:199], v[220:223], v[80:83]
	v_mfma_f32_16x16x32_bf16 v[68:71], v[186:189], v[228:231], v[68:71]
	v_mfma_f32_16x16x32_bf16 v[64:67], v[196:199], v[228:231], v[64:67]
	v_mfma_f32_16x16x32_bf16 v[116:119], v[192:195], v[208:211], v[116:119]
	v_mfma_f32_16x16x32_bf16 v[112:115], v[200:203], v[208:211], v[112:115]
	v_mfma_f32_16x16x32_bf16 v[100:103], v[192:195], v[216:219], v[100:103]
	v_mfma_f32_16x16x32_bf16 v[96:99], v[200:203], v[216:219], v[96:99]
	v_mfma_f32_16x16x32_bf16 v[84:87], v[192:195], v[224:227], v[84:87]
	v_mfma_f32_16x16x32_bf16 v[80:83], v[200:203], v[224:227], v[80:83]
	v_mfma_f32_16x16x32_bf16 v[68:71], v[192:195], v[232:235], v[68:71]
	v_mfma_f32_16x16x32_bf16 v[64:67], v[200:203], v[232:235], v[64:67]
	s_barrier
	s_setprio 0
	s_add_i32 s69, s63, s48
	v_lshl_add_u64 v[144:145], s[44:45], 0, v[130:131]
	s_mov_b32 m0, s69
	ds_read_b128 v[204:207], v167 offset:16384
	ds_read_b128 v[208:211], v167 offset:17408
	ds_read_b128 v[212:215], v167 offset:18432
	ds_read_b128 v[216:219], v167 offset:19456
	ds_read_b128 v[220:223], v167 offset:20480
	ds_read_b128 v[224:227], v167 offset:21504
	ds_read_b128 v[228:231], v167 offset:22528
	ds_read_b128 v[232:235], v167 offset:23552
	global_load_lds_dwordx4 v[144:145], off
	s_add_i32 m0, s69, 0x2000
	s_add_u32 s80, s44, 0x80000
	v_lshl_add_u64 v[236:237], s[44:45], 0, v[134:135]
	s_addc_u32 s81, s45, 0
	s_add_i32 s69, s64, s48
	global_load_lds_dwordx4 v[236:237], off
	v_lshl_add_u64 v[238:239], s[80:81], 0, v[130:131]
	s_mov_b32 m0, s69
	v_lshl_add_u64 v[240:241], s[46:47], 0, v[132:133]
	global_load_lds_dwordx4 v[238:239], off
	v_lshl_add_u64 v[238:239], s[80:81], 0, v[134:135]
	s_add_i32 m0, s69, 0x2000
	s_nop 0
	global_load_lds_dwordx4 v[238:239], off
	v_lshl_add_u64 v[238:239], s[46:47], 0, v[128:129]
	s_mov_b32 m0, s49
	s_nop 0
	global_load_lds_dwordx4 v[238:239], off
	s_mov_b32 m0, s52
	s_nop 0
	global_load_lds_dwordx4 v[240:241], off
	s_waitcnt vmcnt(8)
	s_waitcnt lgkmcnt(0)
	s_setprio 1
	s_barrier
	v_mfma_f32_16x16x32_bf16 v[60:63], v[170:173], v[204:207], v[60:63]
	v_mfma_f32_16x16x32_bf16 v[56:59], v[178:181], v[204:207], v[56:59]
	v_mfma_f32_16x16x32_bf16 v[44:47], v[170:173], v[212:215], v[44:47]
	v_mfma_f32_16x16x32_bf16 v[40:43], v[178:181], v[212:215], v[40:43]
	v_mfma_f32_16x16x32_bf16 v[28:31], v[170:173], v[220:223], v[28:31]
	v_mfma_f32_16x16x32_bf16 v[24:27], v[178:181], v[220:223], v[24:27]
	v_mfma_f32_16x16x32_bf16 v[12:15], v[170:173], v[228:231], v[12:15]
	v_mfma_f32_16x16x32_bf16 v[8:11], v[178:181], v[228:231], v[8:11]
	v_mfma_f32_16x16x32_bf16 v[60:63], v[174:177], v[208:211], v[60:63]
	v_mfma_f32_16x16x32_bf16 v[56:59], v[182:185], v[208:211], v[56:59]
	v_mfma_f32_16x16x32_bf16 v[44:47], v[174:177], v[216:219], v[44:47]
	v_mfma_f32_16x16x32_bf16 v[40:43], v[182:185], v[216:219], v[40:43]
	v_mfma_f32_16x16x32_bf16 v[28:31], v[174:177], v[224:227], v[28:31]
	v_mfma_f32_16x16x32_bf16 v[24:27], v[182:185], v[224:227], v[24:27]
	v_mfma_f32_16x16x32_bf16 v[12:15], v[174:177], v[232:235], v[12:15]
	v_mfma_f32_16x16x32_bf16 v[8:11], v[182:185], v[232:235], v[8:11]
	s_setprio 0
	s_setprio 1
	v_mfma_f32_16x16x32_bf16 v[52:55], v[186:189], v[204:207], v[52:55]
	v_mfma_f32_16x16x32_bf16 v[48:51], v[196:199], v[204:207], v[48:51]
	v_mfma_f32_16x16x32_bf16 v[36:39], v[186:189], v[212:215], v[36:39]
	v_mfma_f32_16x16x32_bf16 v[32:35], v[196:199], v[212:215], v[32:35]
	v_mfma_f32_16x16x32_bf16 v[20:23], v[186:189], v[220:223], v[20:23]
	v_mfma_f32_16x16x32_bf16 v[16:19], v[196:199], v[220:223], v[16:19]
	v_mfma_f32_16x16x32_bf16 v[4:7], v[186:189], v[228:231], v[4:7]
	v_mfma_f32_16x16x32_bf16 v[0:3], v[196:199], v[228:231], v[0:3]
	v_mfma_f32_16x16x32_bf16 v[52:55], v[192:195], v[208:211], v[52:55]
	v_mfma_f32_16x16x32_bf16 v[48:51], v[200:203], v[208:211], v[48:51]
	v_mfma_f32_16x16x32_bf16 v[36:39], v[192:195], v[216:219], v[36:39]
	v_mfma_f32_16x16x32_bf16 v[32:35], v[200:203], v[216:219], v[32:35]
	v_mfma_f32_16x16x32_bf16 v[20:23], v[192:195], v[224:227], v[20:23]
	v_mfma_f32_16x16x32_bf16 v[16:19], v[200:203], v[224:227], v[16:19]
	v_mfma_f32_16x16x32_bf16 v[4:7], v[192:195], v[232:235], v[4:7]
	v_mfma_f32_16x16x32_bf16 v[0:3], v[200:203], v[232:235], v[0:3]
	s_barrier
	s_setprio 0
	s_add_i32 s69, 0, 0x18000
	s_add_i32 s71, 0, 0x1c000
	v_add_u32_e32 v182, s69, v147
	v_add_u32_e32 v200, s71, v147
	ds_read_b128 v[170:173], v182
	ds_read_b128 v[174:177], v182 offset:1024
	ds_read_b128 v[178:181], v182 offset:2048
	ds_read_b128 v[182:185], v182 offset:3072
	ds_read_b128 v[186:189], v200
	ds_read_b128 v[192:195], v200 offset:1024
	ds_read_b128 v[196:199], v200 offset:2048
	ds_read_b128 v[200:203], v200 offset:3072
	s_add_u32 s46, s46, 0x80000
	s_addc_u32 s47, s47, 0
	s_mov_b32 m0, s53
	v_lshl_add_u64 v[242:243], s[46:47], 0, v[128:129]
	ds_read_b128 v[204:207], v167 offset:32768
	ds_read_b128 v[208:211], v167 offset:33792
	ds_read_b128 v[212:215], v167 offset:34816
	ds_read_b128 v[216:219], v167 offset:35840
	ds_read_b128 v[220:223], v167 offset:36864
	ds_read_b128 v[224:227], v167 offset:37888
	ds_read_b128 v[228:231], v167 offset:38912
	ds_read_b128 v[232:235], v167 offset:39936
	global_load_lds_dwordx4 v[242:243], off
	v_lshl_add_u64 v[242:243], s[46:47], 0, v[132:133]
	s_mov_b32 m0, s54
	s_nop 0
	global_load_lds_dwordx4 v[242:243], off
	s_waitcnt vmcnt(8)
	s_waitcnt lgkmcnt(0)
	s_setprio 1
	s_barrier
	v_mfma_f32_16x16x32_bf16 v[124:127], v[170:173], v[204:207], v[124:127]
	v_mfma_f32_16x16x32_bf16 v[120:123], v[178:181], v[204:207], v[120:123]
	v_mfma_f32_16x16x32_bf16 v[108:111], v[170:173], v[212:215], v[108:111]
	v_mfma_f32_16x16x32_bf16 v[104:107], v[178:181], v[212:215], v[104:107]
	v_mfma_f32_16x16x32_bf16 v[92:95], v[170:173], v[220:223], v[92:95]
	v_mfma_f32_16x16x32_bf16 v[88:91], v[178:181], v[220:223], v[88:91]
	v_mfma_f32_16x16x32_bf16 v[76:79], v[170:173], v[228:231], v[76:79]
	v_mfma_f32_16x16x32_bf16 v[72:75], v[178:181], v[228:231], v[72:75]
	v_mfma_f32_16x16x32_bf16 v[124:127], v[174:177], v[208:211], v[124:127]
	v_mfma_f32_16x16x32_bf16 v[120:123], v[182:185], v[208:211], v[120:123]
	v_mfma_f32_16x16x32_bf16 v[108:111], v[174:177], v[216:219], v[108:111]
	v_mfma_f32_16x16x32_bf16 v[104:107], v[182:185], v[216:219], v[104:107]
	v_mfma_f32_16x16x32_bf16 v[92:95], v[174:177], v[224:227], v[92:95]
	v_mfma_f32_16x16x32_bf16 v[88:91], v[182:185], v[224:227], v[88:91]
	v_mfma_f32_16x16x32_bf16 v[76:79], v[174:177], v[232:235], v[76:79]
	v_mfma_f32_16x16x32_bf16 v[72:75], v[182:185], v[232:235], v[72:75]
	s_setprio 0
	s_setprio 1
	v_mfma_f32_16x16x32_bf16 v[116:119], v[186:189], v[204:207], v[116:119]
	v_mfma_f32_16x16x32_bf16 v[112:115], v[196:199], v[204:207], v[112:115]
	v_mfma_f32_16x16x32_bf16 v[100:103], v[186:189], v[212:215], v[100:103]
	v_mfma_f32_16x16x32_bf16 v[96:99], v[196:199], v[212:215], v[96:99]
	v_mfma_f32_16x16x32_bf16 v[84:87], v[186:189], v[220:223], v[84:87]
	v_mfma_f32_16x16x32_bf16 v[80:83], v[196:199], v[220:223], v[80:83]
	v_mfma_f32_16x16x32_bf16 v[68:71], v[186:189], v[228:231], v[68:71]
	v_mfma_f32_16x16x32_bf16 v[64:67], v[196:199], v[228:231], v[64:67]
	v_mfma_f32_16x16x32_bf16 v[116:119], v[192:195], v[208:211], v[116:119]
	v_mfma_f32_16x16x32_bf16 v[112:115], v[200:203], v[208:211], v[112:115]
	v_mfma_f32_16x16x32_bf16 v[100:103], v[192:195], v[216:219], v[100:103]
	v_mfma_f32_16x16x32_bf16 v[96:99], v[200:203], v[216:219], v[96:99]
	v_mfma_f32_16x16x32_bf16 v[84:87], v[192:195], v[224:227], v[84:87]
	v_mfma_f32_16x16x32_bf16 v[80:83], v[200:203], v[224:227], v[80:83]
	v_mfma_f32_16x16x32_bf16 v[68:71], v[192:195], v[232:235], v[68:71]
	v_mfma_f32_16x16x32_bf16 v[64:67], v[200:203], v[232:235], v[64:67]
	s_barrier
	s_setprio 0
	s_add_i32 s46, s69, s48
	v_lshl_add_u64 v[144:145], v[144:145], 0, s[16:17]
	s_mov_b32 m0, s46
	ds_read_b128 v[204:207], v167 offset:49152
	ds_read_b128 v[208:211], v167 offset:50176
	ds_read_b128 v[212:215], v167 offset:51200
	ds_read_b128 v[216:219], v167 offset:52224
	ds_read_b128 v[220:223], v167 offset:53248
	ds_read_b128 v[224:227], v167 offset:54272
	ds_read_b128 v[228:231], v167 offset:55296
	ds_read_b128 v[232:235], v167 offset:56320
	global_load_lds_dwordx4 v[144:145], off
	s_add_i32 m0, s46, 0x2000
	s_add_u32 s44, s44, 0x80080
	v_lshl_add_u64 v[144:145], v[236:237], 0, s[16:17]
	s_addc_u32 s45, s45, 0
	s_add_i32 s46, s71, s48
	global_load_lds_dwordx4 v[144:145], off
	v_lshl_add_u64 v[144:145], s[44:45], 0, v[130:131]
	s_mov_b32 m0, s46
	s_nop 0
	global_load_lds_dwordx4 v[144:145], off
	v_lshl_add_u64 v[144:145], s[44:45], 0, v[134:135]
	s_add_i32 m0, s46, 0x2000
	s_nop 0
	global_load_lds_dwordx4 v[144:145], off
	v_lshl_add_u64 v[144:145], v[238:239], 0, s[16:17]
	s_mov_b32 m0, s56
	s_nop 0
	global_load_lds_dwordx4 v[144:145], off
	v_lshl_add_u64 v[144:145], v[240:241], 0, s[16:17]
	s_mov_b32 m0, s57
	s_nop 0
	global_load_lds_dwordx4 v[144:145], off
	s_waitcnt vmcnt(8)
	s_waitcnt lgkmcnt(0)
	s_setprio 1
	s_barrier
	v_mfma_f32_16x16x32_bf16 v[60:63], v[170:173], v[204:207], v[60:63]
	v_mfma_f32_16x16x32_bf16 v[56:59], v[178:181], v[204:207], v[56:59]
	v_mfma_f32_16x16x32_bf16 v[44:47], v[170:173], v[212:215], v[44:47]
	v_mfma_f32_16x16x32_bf16 v[40:43], v[178:181], v[212:215], v[40:43]
	v_mfma_f32_16x16x32_bf16 v[28:31], v[170:173], v[220:223], v[28:31]
	v_mfma_f32_16x16x32_bf16 v[24:27], v[178:181], v[220:223], v[24:27]
	v_mfma_f32_16x16x32_bf16 v[12:15], v[170:173], v[228:231], v[12:15]
	v_mfma_f32_16x16x32_bf16 v[8:11], v[178:181], v[228:231], v[8:11]
	v_mfma_f32_16x16x32_bf16 v[60:63], v[174:177], v[208:211], v[60:63]
	v_mfma_f32_16x16x32_bf16 v[56:59], v[182:185], v[208:211], v[56:59]
	v_mfma_f32_16x16x32_bf16 v[44:47], v[174:177], v[216:219], v[44:47]
	v_mfma_f32_16x16x32_bf16 v[40:43], v[182:185], v[216:219], v[40:43]
	v_mfma_f32_16x16x32_bf16 v[28:31], v[174:177], v[224:227], v[28:31]
	v_mfma_f32_16x16x32_bf16 v[24:27], v[182:185], v[224:227], v[24:27]
	v_mfma_f32_16x16x32_bf16 v[12:15], v[174:177], v[232:235], v[12:15]
	v_mfma_f32_16x16x32_bf16 v[8:11], v[182:185], v[232:235], v[8:11]
	s_setprio 0
	s_setprio 1
	v_mfma_f32_16x16x32_bf16 v[52:55], v[186:189], v[204:207], v[52:55]
	v_mfma_f32_16x16x32_bf16 v[48:51], v[196:199], v[204:207], v[48:51]
	v_mfma_f32_16x16x32_bf16 v[36:39], v[186:189], v[212:215], v[36:39]
	v_mfma_f32_16x16x32_bf16 v[32:35], v[196:199], v[212:215], v[32:35]
	v_mfma_f32_16x16x32_bf16 v[20:23], v[186:189], v[220:223], v[20:23]
	v_mfma_f32_16x16x32_bf16 v[16:19], v[196:199], v[220:223], v[16:19]
	v_mfma_f32_16x16x32_bf16 v[4:7], v[186:189], v[228:231], v[4:7]
	v_mfma_f32_16x16x32_bf16 v[0:3], v[196:199], v[228:231], v[0:3]
	v_mfma_f32_16x16x32_bf16 v[52:55], v[192:195], v[208:211], v[52:55]
	v_mfma_f32_16x16x32_bf16 v[48:51], v[200:203], v[208:211], v[48:51]
	v_mfma_f32_16x16x32_bf16 v[36:39], v[192:195], v[216:219], v[36:39]
	v_mfma_f32_16x16x32_bf16 v[32:35], v[200:203], v[216:219], v[32:35]
	v_mfma_f32_16x16x32_bf16 v[20:23], v[192:195], v[224:227], v[20:23]
	v_mfma_f32_16x16x32_bf16 v[16:19], v[200:203], v[224:227], v[16:19]
	v_mfma_f32_16x16x32_bf16 v[4:7], v[192:195], v[232:235], v[4:7]
	v_mfma_f32_16x16x32_bf16 v[0:3], v[200:203], v[232:235], v[0:3]
	s_barrier
	s_setprio 0
	s_add_i32 s67, s67, 2
	s_add_u32 s42, s42, 0x100
	s_addc_u32 s43, s43, 0
	s_add_u32 s65, s65, 0x100
	s_addc_u32 s66, s66, 0
	s_cmp_gt_u32 s67, 29
	s_cbranch_scc0 .LBB0_1683
	s_and_b64 vcc, exec, s[28:29]
	s_cbranch_vccz .LBB0_1686
	s_barrier

.LBB0_1777:
	ds_read_b128 v[144:147], v151
	ds_read_b128 v[156:159], v151 offset:1024
	ds_read_b128 v[160:163], v151 offset:2048
	ds_read_b128 v[164:167], v151 offset:3072
	ds_read_b128 v[168:171], v152
	ds_read_b128 v[172:175], v152 offset:1024
	ds_read_b128 v[176:179], v152 offset:2048
	ds_read_b128 v[180:183], v152 offset:3072
	s_add_u32 s36, s34, 0xfff80080
	s_addc_u32 s37, s35, -1
	s_cmp_eq_u32 s62, 28
	s_cselect_b32 s39, s19, s37
	s_cselect_b32 s38, s56, s36
	s_cselect_b32 s37, s17, s59
	s_cselect_b32 s36, s57, s58
	v_lshl_add_u64 v[188:189], s[34:35], 0, v[136:137]
	s_add_i32 m0, s42, 0xc000
	ds_read_b128 v[184:187], v153
	ds_read_b128 v[192:195], v153 offset:1024
	ds_read_b128 v[196:199], v153 offset:2048
	ds_read_b128 v[200:203], v153 offset:3072
	ds_read_b128 v[204:207], v153 offset:4096
	ds_read_b128 v[208:211], v153 offset:5120
	ds_read_b128 v[212:215], v153 offset:6144
	ds_read_b128 v[216:219], v153 offset:7168
	global_load_lds_dwordx4 v[188:189], off
	v_lshl_add_u64 v[188:189], s[34:35], 0, v[138:139]
	s_add_i32 m0, s42, 0xe000
	s_nop 0
	global_load_lds_dwordx4 v[188:189], off
	s_waitcnt vmcnt(8)
	s_waitcnt lgkmcnt(0)
	s_setprio 1
	s_barrier
	v_mfma_f32_16x16x32_bf16 v[124:127], v[144:147], v[184:187], v[124:127]
	v_mfma_f32_16x16x32_bf16 v[120:123], v[160:163], v[184:187], v[120:123]
	v_mfma_f32_16x16x32_bf16 v[108:111], v[144:147], v[196:199], v[108:111]
	v_mfma_f32_16x16x32_bf16 v[104:107], v[160:163], v[196:199], v[104:107]
	v_mfma_f32_16x16x32_bf16 v[92:95], v[144:147], v[204:207], v[92:95]
	v_mfma_f32_16x16x32_bf16 v[88:91], v[160:163], v[204:207], v[88:91]
	v_mfma_f32_16x16x32_bf16 v[76:79], v[144:147], v[212:215], v[76:79]
	v_mfma_f32_16x16x32_bf16 v[72:75], v[160:163], v[212:215], v[72:75]
	v_mfma_f32_16x16x32_bf16 v[124:127], v[156:159], v[192:195], v[124:127]
	v_mfma_f32_16x16x32_bf16 v[120:123], v[164:167], v[192:195], v[120:123]
	v_mfma_f32_16x16x32_bf16 v[108:111], v[156:159], v[200:203], v[108:111]
	v_mfma_f32_16x16x32_bf16 v[104:107], v[164:167], v[200:203], v[104:107]
	v_mfma_f32_16x16x32_bf16 v[92:95], v[156:159], v[208:211], v[92:95]
	v_mfma_f32_16x16x32_bf16 v[88:91], v[164:167], v[208:211], v[88:91]
	v_mfma_f32_16x16x32_bf16 v[76:79], v[156:159], v[216:219], v[76:79]
	v_mfma_f32_16x16x32_bf16 v[72:75], v[164:167], v[216:219], v[72:75]
	s_setprio 0
	s_setprio 1
	v_mfma_f32_16x16x32_bf16 v[116:119], v[168:171], v[184:187], v[116:119]
	v_mfma_f32_16x16x32_bf16 v[112:115], v[176:179], v[184:187], v[112:115]
	v_mfma_f32_16x16x32_bf16 v[100:103], v[168:171], v[196:199], v[100:103]
	v_mfma_f32_16x16x32_bf16 v[96:99], v[176:179], v[196:199], v[96:99]
	v_mfma_f32_16x16x32_bf16 v[84:87], v[168:171], v[204:207], v[84:87]
	v_mfma_f32_16x16x32_bf16 v[80:83], v[176:179], v[204:207], v[80:83]
	v_mfma_f32_16x16x32_bf16 v[68:71], v[168:171], v[212:215], v[68:71]
	v_mfma_f32_16x16x32_bf16 v[64:67], v[176:179], v[212:215], v[64:67]
	v_mfma_f32_16x16x32_bf16 v[116:119], v[172:175], v[192:195], v[116:119]
	v_mfma_f32_16x16x32_bf16 v[112:115], v[180:183], v[192:195], v[112:115]
	v_mfma_f32_16x16x32_bf16 v[100:103], v[172:175], v[200:203], v[100:103]
	v_mfma_f32_16x16x32_bf16 v[96:99], v[180:183], v[200:203], v[96:99]
	v_mfma_f32_16x16x32_bf16 v[84:87], v[172:175], v[208:211], v[84:87]
	v_mfma_f32_16x16x32_bf16 v[80:83], v[180:183], v[208:211], v[80:83]
	v_mfma_f32_16x16x32_bf16 v[68:71], v[172:175], v[216:219], v[68:71]
	v_mfma_f32_16x16x32_bf16 v[64:67], v[180:183], v[216:219], v[64:67]
	s_barrier
	s_setprio 0
	s_add_i32 s63, s53, s41
	v_lshl_add_u64 v[188:189], s[36:37], 0, v[130:131]
	s_mov_b32 m0, s63
	ds_read_b128 v[184:187], v153 offset:16384
	ds_read_b128 v[192:195], v153 offset:17408
	ds_read_b128 v[196:199], v153 offset:18432
	ds_read_b128 v[200:203], v153 offset:19456
	ds_read_b128 v[204:207], v153 offset:20480
	ds_read_b128 v[208:211], v153 offset:21504
	ds_read_b128 v[212:215], v153 offset:22528
	ds_read_b128 v[216:219], v153 offset:23552
	global_load_lds_dwordx4 v[188:189], off
	s_add_i32 m0, s63, 0x2000
	s_add_u32 s64, s36, 0x80000
	v_lshl_add_u64 v[220:221], s[36:37], 0, v[134:135]
	s_addc_u32 s65, s37, 0
	s_add_i32 s63, s54, s41
	global_load_lds_dwordx4 v[220:221], off
	v_lshl_add_u64 v[222:223], s[64:65], 0, v[130:131]
	s_mov_b32 m0, s63
	v_lshl_add_u64 v[224:225], s[38:39], 0, v[132:133]
	global_load_lds_dwordx4 v[222:223], off
	v_lshl_add_u64 v[222:223], s[64:65], 0, v[134:135]
	s_add_i32 m0, s63, 0x2000
	s_nop 0
	global_load_lds_dwordx4 v[222:223], off
	v_lshl_add_u64 v[222:223], s[38:39], 0, v[128:129]
	s_mov_b32 m0, s42
	s_nop 0
	global_load_lds_dwordx4 v[222:223], off
	s_mov_b32 m0, s43
	s_nop 0
	global_load_lds_dwordx4 v[224:225], off
	s_waitcnt vmcnt(8)
	s_waitcnt lgkmcnt(0)
	s_setprio 1
	s_barrier
	v_mfma_f32_16x16x32_bf16 v[60:63], v[144:147], v[184:187], v[60:63]
	v_mfma_f32_16x16x32_bf16 v[56:59], v[160:163], v[184:187], v[56:59]
	v_mfma_f32_16x16x32_bf16 v[44:47], v[144:147], v[196:199], v[44:47]
	v_mfma_f32_16x16x32_bf16 v[40:43], v[160:163], v[196:199], v[40:43]
	v_mfma_f32_16x16x32_bf16 v[28:31], v[144:147], v[204:207], v[28:31]
	v_mfma_f32_16x16x32_bf16 v[24:27], v[160:163], v[204:207], v[24:27]
	v_mfma_f32_16x16x32_bf16 v[12:15], v[144:147], v[212:215], v[12:15]
	v_mfma_f32_16x16x32_bf16 v[8:11], v[160:163], v[212:215], v[8:11]
	v_mfma_f32_16x16x32_bf16 v[60:63], v[156:159], v[192:195], v[60:63]
	v_mfma_f32_16x16x32_bf16 v[56:59], v[164:167], v[192:195], v[56:59]
	v_mfma_f32_16x16x32_bf16 v[44:47], v[156:159], v[200:203], v[44:47]
	v_mfma_f32_16x16x32_bf16 v[40:43], v[164:167], v[200:203], v[40:43]
	v_mfma_f32_16x16x32_bf16 v[28:31], v[156:159], v[208:211], v[28:31]
	v_mfma_f32_16x16x32_bf16 v[24:27], v[164:167], v[208:211], v[24:27]
	v_mfma_f32_16x16x32_bf16 v[12:15], v[156:159], v[216:219], v[12:15]
	v_mfma_f32_16x16x32_bf16 v[8:11], v[164:167], v[216:219], v[8:11]
	s_setprio 0
	s_setprio 1
	v_mfma_f32_16x16x32_bf16 v[52:55], v[168:171], v[184:187], v[52:55]
	v_mfma_f32_16x16x32_bf16 v[48:51], v[176:179], v[184:187], v[48:51]
	v_mfma_f32_16x16x32_bf16 v[36:39], v[168:171], v[196:199], v[36:39]
	v_mfma_f32_16x16x32_bf16 v[32:35], v[176:179], v[196:199], v[32:35]
	v_mfma_f32_16x16x32_bf16 v[20:23], v[168:171], v[204:207], v[20:23]
	v_mfma_f32_16x16x32_bf16 v[16:19], v[176:179], v[204:207], v[16:19]
	v_mfma_f32_16x16x32_bf16 v[4:7], v[168:171], v[212:215], v[4:7]
	v_mfma_f32_16x16x32_bf16 v[0:3], v[176:179], v[212:215], v[0:3]
	v_mfma_f32_16x16x32_bf16 v[52:55], v[172:175], v[192:195], v[52:55]
	v_mfma_f32_16x16x32_bf16 v[48:51], v[180:183], v[192:195], v[48:51]
	v_mfma_f32_16x16x32_bf16 v[36:39], v[172:175], v[200:203], v[36:39]
	v_mfma_f32_16x16x32_bf16 v[32:35], v[180:183], v[200:203], v[32:35]
	v_mfma_f32_16x16x32_bf16 v[20:23], v[172:175], v[208:211], v[20:23]
	v_mfma_f32_16x16x32_bf16 v[16:19], v[180:183], v[208:211], v[16:19]
	v_mfma_f32_16x16x32_bf16 v[4:7], v[172:175], v[216:219], v[4:7]
	v_mfma_f32_16x16x32_bf16 v[0:3], v[180:183], v[216:219], v[0:3]
	s_barrier
	s_setprio 0
	s_add_i32 s63, 0, 0x18000
	v_add_u32_e32 v155, s63, v149
	s_add_i32 s64, 0, 0x1c000
	ds_read_b128 v[144:147], v155
	ds_read_b128 v[156:159], v155 offset:1024
	ds_read_b128 v[160:163], v155 offset:2048
	ds_read_b128 v[164:167], v155 offset:3072
	v_add_u32_e32 v155, s64, v149
	ds_read_b128 v[168:171], v155
	ds_read_b128 v[172:175], v155 offset:1024
	ds_read_b128 v[176:179], v155 offset:2048
	ds_read_b128 v[180:183], v155 offset:3072
	s_add_u32 s38, s38, 0x80000
	s_addc_u32 s39, s39, 0
	s_mov_b32 m0, s44
	v_lshl_add_u64 v[226:227], s[38:39], 0, v[128:129]
	ds_read_b128 v[184:187], v153 offset:32768
	ds_read_b128 v[192:195], v153 offset:33792
	ds_read_b128 v[196:199], v153 offset:34816
	ds_read_b128 v[200:203], v153 offset:35840
	ds_read_b128 v[204:207], v153 offset:36864
	ds_read_b128 v[208:211], v153 offset:37888
	ds_read_b128 v[212:215], v153 offset:38912
	ds_read_b128 v[216:219], v153 offset:39936
	global_load_lds_dwordx4 v[226:227], off
	v_lshl_add_u64 v[226:227], s[38:39], 0, v[132:133]
	s_mov_b32 m0, s45
	s_nop 0
	global_load_lds_dwordx4 v[226:227], off
	s_waitcnt vmcnt(8)
	s_waitcnt lgkmcnt(0)
	s_setprio 1
	s_barrier
	v_mfma_f32_16x16x32_bf16 v[124:127], v[144:147], v[184:187], v[124:127]
	v_mfma_f32_16x16x32_bf16 v[120:123], v[160:163], v[184:187], v[120:123]
	v_mfma_f32_16x16x32_bf16 v[108:111], v[144:147], v[196:199], v[108:111]
	v_mfma_f32_16x16x32_bf16 v[104:107], v[160:163], v[196:199], v[104:107]
	v_mfma_f32_16x16x32_bf16 v[92:95], v[144:147], v[204:207], v[92:95]
	v_mfma_f32_16x16x32_bf16 v[88:91], v[160:163], v[204:207], v[88:91]
	v_mfma_f32_16x16x32_bf16 v[76:79], v[144:147], v[212:215], v[76:79]
	v_mfma_f32_16x16x32_bf16 v[72:75], v[160:163], v[212:215], v[72:75]
	v_mfma_f32_16x16x32_bf16 v[124:127], v[156:159], v[192:195], v[124:127]
	v_mfma_f32_16x16x32_bf16 v[120:123], v[164:167], v[192:195], v[120:123]
	v_mfma_f32_16x16x32_bf16 v[108:111], v[156:159], v[200:203], v[108:111]
	v_mfma_f32_16x16x32_bf16 v[104:107], v[164:167], v[200:203], v[104:107]
	v_mfma_f32_16x16x32_bf16 v[92:95], v[156:159], v[208:211], v[92:95]
	v_mfma_f32_16x16x32_bf16 v[88:91], v[164:167], v[208:211], v[88:91]
	v_mfma_f32_16x16x32_bf16 v[76:79], v[156:159], v[216:219], v[76:79]
	v_mfma_f32_16x16x32_bf16 v[72:75], v[164:167], v[216:219], v[72:75]
	s_setprio 0
	s_setprio 1
	v_mfma_f32_16x16x32_bf16 v[116:119], v[168:171], v[184:187], v[116:119]
	v_mfma_f32_16x16x32_bf16 v[112:115], v[176:179], v[184:187], v[112:115]
	v_mfma_f32_16x16x32_bf16 v[100:103], v[168:171], v[196:199], v[100:103]
	v_mfma_f32_16x16x32_bf16 v[96:99], v[176:179], v[196:199], v[96:99]
	v_mfma_f32_16x16x32_bf16 v[84:87], v[168:171], v[204:207], v[84:87]
	v_mfma_f32_16x16x32_bf16 v[80:83], v[176:179], v[204:207], v[80:83]
	v_mfma_f32_16x16x32_bf16 v[68:71], v[168:171], v[212:215], v[68:71]
	v_mfma_f32_16x16x32_bf16 v[64:67], v[176:179], v[212:215], v[64:67]
	v_mfma_f32_16x16x32_bf16 v[116:119], v[172:175], v[192:195], v[116:119]
	v_mfma_f32_16x16x32_bf16 v[112:115], v[180:183], v[192:195], v[112:115]
	v_mfma_f32_16x16x32_bf16 v[100:103], v[172:175], v[200:203], v[100:103]
	v_mfma_f32_16x16x32_bf16 v[96:99], v[180:183], v[200:203], v[96:99]
	v_mfma_f32_16x16x32_bf16 v[84:87], v[172:175], v[208:211], v[84:87]
	v_mfma_f32_16x16x32_bf16 v[80:83], v[180:183], v[208:211], v[80:83]
	v_mfma_f32_16x16x32_bf16 v[68:71], v[172:175], v[216:219], v[68:71]
	v_mfma_f32_16x16x32_bf16 v[64:67], v[180:183], v[216:219], v[64:67]
	s_barrier
	s_setprio 0
	s_add_i32 s38, s63, s41
	v_lshl_add_u64 v[188:189], v[188:189], 0, s[10:11]
	s_mov_b32 m0, s38
	ds_read_b128 v[184:187], v153 offset:49152
	ds_read_b128 v[192:195], v153 offset:50176
	ds_read_b128 v[196:199], v153 offset:51200
	ds_read_b128 v[200:203], v153 offset:52224
	ds_read_b128 v[204:207], v153 offset:53248
	ds_read_b128 v[208:211], v153 offset:54272
	ds_read_b128 v[212:215], v153 offset:55296
	ds_read_b128 v[216:219], v153 offset:56320
	global_load_lds_dwordx4 v[188:189], off
	s_add_i32 m0, s38, 0x2000
	s_add_u32 s36, s36, 0x80080
	v_lshl_add_u64 v[188:189], v[220:221], 0, s[10:11]
	s_addc_u32 s37, s37, 0
	s_add_i32 s38, s64, s41
	global_load_lds_dwordx4 v[188:189], off
	v_lshl_add_u64 v[188:189], s[36:37], 0, v[130:131]
	s_mov_b32 m0, s38
	s_nop 0
	global_load_lds_dwordx4 v[188:189], off
	v_lshl_add_u64 v[188:189], s[36:37], 0, v[134:135]
	s_add_i32 m0, s38, 0x2000
	s_nop 0
	global_load_lds_dwordx4 v[188:189], off
	v_lshl_add_u64 v[188:189], v[222:223], 0, s[10:11]
	s_mov_b32 m0, s47
	s_nop 0
	global_load_lds_dwordx4 v[188:189], off
	v_lshl_add_u64 v[188:189], v[224:225], 0, s[10:11]
	s_mov_b32 m0, s48
	s_nop 0
	global_load_lds_dwordx4 v[188:189], off
	s_waitcnt vmcnt(8)
	s_waitcnt lgkmcnt(0)
	s_setprio 1
	s_barrier
	v_mfma_f32_16x16x32_bf16 v[60:63], v[144:147], v[184:187], v[60:63]
	v_mfma_f32_16x16x32_bf16 v[56:59], v[160:163], v[184:187], v[56:59]
	v_mfma_f32_16x16x32_bf16 v[44:47], v[144:147], v[196:199], v[44:47]
	v_mfma_f32_16x16x32_bf16 v[40:43], v[160:163], v[196:199], v[40:43]
	v_mfma_f32_16x16x32_bf16 v[28:31], v[144:147], v[204:207], v[28:31]
	v_mfma_f32_16x16x32_bf16 v[24:27], v[160:163], v[204:207], v[24:27]
	v_mfma_f32_16x16x32_bf16 v[12:15], v[144:147], v[212:215], v[12:15]
	v_mfma_f32_16x16x32_bf16 v[8:11], v[160:163], v[212:215], v[8:11]
	v_mfma_f32_16x16x32_bf16 v[60:63], v[156:159], v[192:195], v[60:63]
	v_mfma_f32_16x16x32_bf16 v[56:59], v[164:167], v[192:195], v[56:59]
	v_mfma_f32_16x16x32_bf16 v[44:47], v[156:159], v[200:203], v[44:47]
	v_mfma_f32_16x16x32_bf16 v[40:43], v[164:167], v[200:203], v[40:43]
	v_mfma_f32_16x16x32_bf16 v[28:31], v[156:159], v[208:211], v[28:31]
	v_mfma_f32_16x16x32_bf16 v[24:27], v[164:167], v[208:211], v[24:27]
	v_mfma_f32_16x16x32_bf16 v[12:15], v[156:159], v[216:219], v[12:15]
	v_mfma_f32_16x16x32_bf16 v[8:11], v[164:167], v[216:219], v[8:11]
	s_setprio 0
	s_setprio 1
	v_mfma_f32_16x16x32_bf16 v[52:55], v[168:171], v[184:187], v[52:55]
	v_mfma_f32_16x16x32_bf16 v[48:51], v[176:179], v[184:187], v[48:51]
	v_mfma_f32_16x16x32_bf16 v[36:39], v[168:171], v[196:199], v[36:39]
	v_mfma_f32_16x16x32_bf16 v[32:35], v[176:179], v[196:199], v[32:35]
	v_mfma_f32_16x16x32_bf16 v[20:23], v[168:171], v[204:207], v[20:23]
	v_mfma_f32_16x16x32_bf16 v[16:19], v[176:179], v[204:207], v[16:19]
	v_mfma_f32_16x16x32_bf16 v[4:7], v[168:171], v[212:215], v[4:7]
	v_mfma_f32_16x16x32_bf16 v[0:3], v[176:179], v[212:215], v[0:3]
	v_mfma_f32_16x16x32_bf16 v[52:55], v[172:175], v[192:195], v[52:55]
	v_mfma_f32_16x16x32_bf16 v[48:51], v[180:183], v[192:195], v[48:51]
	v_mfma_f32_16x16x32_bf16 v[36:39], v[172:175], v[200:203], v[36:39]
	v_mfma_f32_16x16x32_bf16 v[32:35], v[180:183], v[200:203], v[32:35]
	v_mfma_f32_16x16x32_bf16 v[20:23], v[172:175], v[208:211], v[20:23]
	v_mfma_f32_16x16x32_bf16 v[16:19], v[180:183], v[208:211], v[16:19]
	v_mfma_f32_16x16x32_bf16 v[4:7], v[172:175], v[216:219], v[4:7]
	v_mfma_f32_16x16x32_bf16 v[0:3], v[180:183], v[216:219], v[0:3]
	s_barrier
	s_setprio 0
	s_add_i32 s62, s62, 2
	s_add_u32 s34, s34, 0x100
	s_addc_u32 s35, s35, 0
	s_add_u32 s58, s58, 0x100
	s_addc_u32 s59, s59, 0
	s_cmp_gt_u32 s62, 29
	s_cbranch_scc0 .LBB0_1777
	s_and_b64 vcc, exec, s[14:15]
	s_cbranch_vccz .LBB0_1780
	s_barrier

.LBB0_1912:
	ds_read_b128 v[170:173], v165
	ds_read_b128 v[174:177], v165 offset:1024
	ds_read_b128 v[178:181], v165 offset:2048
	ds_read_b128 v[182:185], v165 offset:3072
	ds_read_b128 v[186:189], v166
	ds_read_b128 v[192:195], v166 offset:1024
	ds_read_b128 v[196:199], v166 offset:2048
	ds_read_b128 v[200:203], v166 offset:3072
	s_add_u32 s40, s38, 0xfff80080
	s_addc_u32 s41, s39, -1
	s_cmp_eq_u32 s63, 28
	s_cselect_b32 s43, s1, s41
	s_cselect_b32 s42, s29, s40
	s_cselect_b32 s41, s21, s62
	s_cselect_b32 s40, s37, s59
	v_lshl_add_u64 v[144:145], s[38:39], 0, v[136:137]
	s_add_i32 m0, s45, 0xc000
	ds_read_b128 v[204:207], v167
	ds_read_b128 v[208:211], v167 offset:1024
	ds_read_b128 v[212:215], v167 offset:2048
	ds_read_b128 v[216:219], v167 offset:3072
	ds_read_b128 v[220:223], v167 offset:4096
	ds_read_b128 v[224:227], v167 offset:5120
	ds_read_b128 v[228:231], v167 offset:6144
	ds_read_b128 v[232:235], v167 offset:7168
	global_load_lds_dwordx4 v[144:145], off
	v_lshl_add_u64 v[144:145], s[38:39], 0, v[138:139]
	s_add_i32 m0, s45, 0xe000
	s_nop 0
	global_load_lds_dwordx4 v[144:145], off
	s_waitcnt vmcnt(8)
	s_waitcnt lgkmcnt(0)
	s_setprio 1
	s_barrier
	v_mfma_f32_16x16x32_bf16 v[124:127], v[170:173], v[204:207], v[124:127]
	v_mfma_f32_16x16x32_bf16 v[120:123], v[178:181], v[204:207], v[120:123]
	v_mfma_f32_16x16x32_bf16 v[108:111], v[170:173], v[212:215], v[108:111]
	v_mfma_f32_16x16x32_bf16 v[104:107], v[178:181], v[212:215], v[104:107]
	v_mfma_f32_16x16x32_bf16 v[92:95], v[170:173], v[220:223], v[92:95]
	v_mfma_f32_16x16x32_bf16 v[88:91], v[178:181], v[220:223], v[88:91]
	v_mfma_f32_16x16x32_bf16 v[76:79], v[170:173], v[228:231], v[76:79]
	v_mfma_f32_16x16x32_bf16 v[72:75], v[178:181], v[228:231], v[72:75]
	v_mfma_f32_16x16x32_bf16 v[124:127], v[174:177], v[208:211], v[124:127]
	v_mfma_f32_16x16x32_bf16 v[120:123], v[182:185], v[208:211], v[120:123]
	v_mfma_f32_16x16x32_bf16 v[108:111], v[174:177], v[216:219], v[108:111]
	v_mfma_f32_16x16x32_bf16 v[104:107], v[182:185], v[216:219], v[104:107]
	v_mfma_f32_16x16x32_bf16 v[92:95], v[174:177], v[224:227], v[92:95]
	v_mfma_f32_16x16x32_bf16 v[88:91], v[182:185], v[224:227], v[88:91]
	v_mfma_f32_16x16x32_bf16 v[76:79], v[174:177], v[232:235], v[76:79]
	v_mfma_f32_16x16x32_bf16 v[72:75], v[182:185], v[232:235], v[72:75]
	s_setprio 0
	s_setprio 1
	v_mfma_f32_16x16x32_bf16 v[116:119], v[186:189], v[204:207], v[116:119]
	v_mfma_f32_16x16x32_bf16 v[112:115], v[196:199], v[204:207], v[112:115]
	v_mfma_f32_16x16x32_bf16 v[100:103], v[186:189], v[212:215], v[100:103]
	v_mfma_f32_16x16x32_bf16 v[96:99], v[196:199], v[212:215], v[96:99]
	v_mfma_f32_16x16x32_bf16 v[84:87], v[186:189], v[220:223], v[84:87]
	v_mfma_f32_16x16x32_bf16 v[80:83], v[196:199], v[220:223], v[80:83]
	v_mfma_f32_16x16x32_bf16 v[68:71], v[186:189], v[228:231], v[68:71]
	v_mfma_f32_16x16x32_bf16 v[64:67], v[196:199], v[228:231], v[64:67]
	v_mfma_f32_16x16x32_bf16 v[116:119], v[192:195], v[208:211], v[116:119]
	v_mfma_f32_16x16x32_bf16 v[112:115], v[200:203], v[208:211], v[112:115]
	v_mfma_f32_16x16x32_bf16 v[100:103], v[192:195], v[216:219], v[100:103]
	v_mfma_f32_16x16x32_bf16 v[96:99], v[200:203], v[216:219], v[96:99]
	v_mfma_f32_16x16x32_bf16 v[84:87], v[192:195], v[224:227], v[84:87]
	v_mfma_f32_16x16x32_bf16 v[80:83], v[200:203], v[224:227], v[80:83]
	v_mfma_f32_16x16x32_bf16 v[68:71], v[192:195], v[232:235], v[68:71]
	v_mfma_f32_16x16x32_bf16 v[64:67], v[200:203], v[232:235], v[64:67]
	s_barrier
	s_setprio 0
	s_add_i32 s64, s57, s44
	v_lshl_add_u64 v[144:145], s[40:41], 0, v[130:131]
	s_mov_b32 m0, s64
	ds_read_b128 v[204:207], v167 offset:16384
	ds_read_b128 v[208:211], v167 offset:17408
	ds_read_b128 v[212:215], v167 offset:18432
	ds_read_b128 v[216:219], v167 offset:19456
	ds_read_b128 v[220:223], v167 offset:20480
	ds_read_b128 v[224:227], v167 offset:21504
	ds_read_b128 v[228:231], v167 offset:22528
	ds_read_b128 v[232:235], v167 offset:23552
	global_load_lds_dwordx4 v[144:145], off
	s_add_i32 m0, s64, 0x2000
	s_add_u32 s64, s40, 0x80000
	v_lshl_add_u64 v[236:237], s[40:41], 0, v[134:135]
	s_addc_u32 s65, s41, 0
	s_add_i32 s66, s58, s44
	global_load_lds_dwordx4 v[236:237], off
	v_lshl_add_u64 v[238:239], s[64:65], 0, v[130:131]
	s_mov_b32 m0, s66
	v_lshl_add_u64 v[240:241], s[42:43], 0, v[132:133]
	global_load_lds_dwordx4 v[238:239], off
	v_lshl_add_u64 v[238:239], s[64:65], 0, v[134:135]
	s_add_i32 m0, s66, 0x2000
	s_nop 0
	global_load_lds_dwordx4 v[238:239], off
	v_lshl_add_u64 v[238:239], s[42:43], 0, v[128:129]
	s_mov_b32 m0, s45
	s_nop 0
	global_load_lds_dwordx4 v[238:239], off
	s_mov_b32 m0, s46
	s_nop 0
	global_load_lds_dwordx4 v[240:241], off
	s_waitcnt vmcnt(8)
	s_waitcnt lgkmcnt(0)
	s_setprio 1
	s_barrier
	v_mfma_f32_16x16x32_bf16 v[60:63], v[170:173], v[204:207], v[60:63]
	v_mfma_f32_16x16x32_bf16 v[56:59], v[178:181], v[204:207], v[56:59]
	v_mfma_f32_16x16x32_bf16 v[44:47], v[170:173], v[212:215], v[44:47]
	v_mfma_f32_16x16x32_bf16 v[40:43], v[178:181], v[212:215], v[40:43]
	v_mfma_f32_16x16x32_bf16 v[28:31], v[170:173], v[220:223], v[28:31]
	v_mfma_f32_16x16x32_bf16 v[24:27], v[178:181], v[220:223], v[24:27]
	v_mfma_f32_16x16x32_bf16 v[12:15], v[170:173], v[228:231], v[12:15]
	v_mfma_f32_16x16x32_bf16 v[8:11], v[178:181], v[228:231], v[8:11]
	v_mfma_f32_16x16x32_bf16 v[60:63], v[174:177], v[208:211], v[60:63]
	v_mfma_f32_16x16x32_bf16 v[56:59], v[182:185], v[208:211], v[56:59]
	v_mfma_f32_16x16x32_bf16 v[44:47], v[174:177], v[216:219], v[44:47]
	v_mfma_f32_16x16x32_bf16 v[40:43], v[182:185], v[216:219], v[40:43]
	v_mfma_f32_16x16x32_bf16 v[28:31], v[174:177], v[224:227], v[28:31]
	v_mfma_f32_16x16x32_bf16 v[24:27], v[182:185], v[224:227], v[24:27]
	v_mfma_f32_16x16x32_bf16 v[12:15], v[174:177], v[232:235], v[12:15]
	v_mfma_f32_16x16x32_bf16 v[8:11], v[182:185], v[232:235], v[8:11]
	s_setprio 0
	s_setprio 1
	v_mfma_f32_16x16x32_bf16 v[52:55], v[186:189], v[204:207], v[52:55]
	v_mfma_f32_16x16x32_bf16 v[48:51], v[196:199], v[204:207], v[48:51]
	v_mfma_f32_16x16x32_bf16 v[36:39], v[186:189], v[212:215], v[36:39]
	v_mfma_f32_16x16x32_bf16 v[32:35], v[196:199], v[212:215], v[32:35]
	v_mfma_f32_16x16x32_bf16 v[20:23], v[186:189], v[220:223], v[20:23]
	v_mfma_f32_16x16x32_bf16 v[16:19], v[196:199], v[220:223], v[16:19]
	v_mfma_f32_16x16x32_bf16 v[4:7], v[186:189], v[228:231], v[4:7]
	v_mfma_f32_16x16x32_bf16 v[0:3], v[196:199], v[228:231], v[0:3]
	v_mfma_f32_16x16x32_bf16 v[52:55], v[192:195], v[208:211], v[52:55]
	v_mfma_f32_16x16x32_bf16 v[48:51], v[200:203], v[208:211], v[48:51]
	v_mfma_f32_16x16x32_bf16 v[36:39], v[192:195], v[216:219], v[36:39]
	v_mfma_f32_16x16x32_bf16 v[32:35], v[200:203], v[216:219], v[32:35]
	v_mfma_f32_16x16x32_bf16 v[20:23], v[192:195], v[224:227], v[20:23]
	v_mfma_f32_16x16x32_bf16 v[16:19], v[200:203], v[224:227], v[16:19]
	v_mfma_f32_16x16x32_bf16 v[4:7], v[192:195], v[232:235], v[4:7]
	v_mfma_f32_16x16x32_bf16 v[0:3], v[200:203], v[232:235], v[0:3]
	s_barrier
	s_setprio 0
	s_add_i32 s64, 0, 0x18000
	s_add_i32 s65, 0, 0x1c000
	v_add_u32_e32 v182, s64, v147
	v_add_u32_e32 v200, s65, v147
	ds_read_b128 v[170:173], v182
	ds_read_b128 v[174:177], v182 offset:1024
	ds_read_b128 v[178:181], v182 offset:2048
	ds_read_b128 v[182:185], v182 offset:3072
	ds_read_b128 v[186:189], v200
	ds_read_b128 v[192:195], v200 offset:1024
	ds_read_b128 v[196:199], v200 offset:2048
	ds_read_b128 v[200:203], v200 offset:3072
	s_add_u32 s42, s42, 0x80000
	s_addc_u32 s43, s43, 0
	s_mov_b32 m0, s47
	v_lshl_add_u64 v[242:243], s[42:43], 0, v[128:129]
	ds_read_b128 v[204:207], v167 offset:32768
	ds_read_b128 v[208:211], v167 offset:33792
	ds_read_b128 v[212:215], v167 offset:34816
	ds_read_b128 v[216:219], v167 offset:35840
	ds_read_b128 v[220:223], v167 offset:36864
	ds_read_b128 v[224:227], v167 offset:37888
	ds_read_b128 v[228:231], v167 offset:38912
	ds_read_b128 v[232:235], v167 offset:39936
	global_load_lds_dwordx4 v[242:243], off
	v_lshl_add_u64 v[242:243], s[42:43], 0, v[132:133]
	s_mov_b32 m0, s48
	s_nop 0
	global_load_lds_dwordx4 v[242:243], off
	s_waitcnt vmcnt(8)
	s_waitcnt lgkmcnt(0)
	s_setprio 1
	s_barrier
	v_mfma_f32_16x16x32_bf16 v[124:127], v[170:173], v[204:207], v[124:127]
	v_mfma_f32_16x16x32_bf16 v[120:123], v[178:181], v[204:207], v[120:123]
	v_mfma_f32_16x16x32_bf16 v[108:111], v[170:173], v[212:215], v[108:111]
	v_mfma_f32_16x16x32_bf16 v[104:107], v[178:181], v[212:215], v[104:107]
	v_mfma_f32_16x16x32_bf16 v[92:95], v[170:173], v[220:223], v[92:95]
	v_mfma_f32_16x16x32_bf16 v[88:91], v[178:181], v[220:223], v[88:91]
	v_mfma_f32_16x16x32_bf16 v[76:79], v[170:173], v[228:231], v[76:79]
	v_mfma_f32_16x16x32_bf16 v[72:75], v[178:181], v[228:231], v[72:75]
	v_mfma_f32_16x16x32_bf16 v[124:127], v[174:177], v[208:211], v[124:127]
	v_mfma_f32_16x16x32_bf16 v[120:123], v[182:185], v[208:211], v[120:123]
	v_mfma_f32_16x16x32_bf16 v[108:111], v[174:177], v[216:219], v[108:111]
	v_mfma_f32_16x16x32_bf16 v[104:107], v[182:185], v[216:219], v[104:107]
	v_mfma_f32_16x16x32_bf16 v[92:95], v[174:177], v[224:227], v[92:95]
	v_mfma_f32_16x16x32_bf16 v[88:91], v[182:185], v[224:227], v[88:91]
	v_mfma_f32_16x16x32_bf16 v[76:79], v[174:177], v[232:235], v[76:79]
	v_mfma_f32_16x16x32_bf16 v[72:75], v[182:185], v[232:235], v[72:75]
	s_setprio 0
	s_setprio 1
	v_mfma_f32_16x16x32_bf16 v[116:119], v[186:189], v[204:207], v[116:119]
	v_mfma_f32_16x16x32_bf16 v[112:115], v[196:199], v[204:207], v[112:115]
	v_mfma_f32_16x16x32_bf16 v[100:103], v[186:189], v[212:215], v[100:103]
	v_mfma_f32_16x16x32_bf16 v[96:99], v[196:199], v[212:215], v[96:99]
	v_mfma_f32_16x16x32_bf16 v[84:87], v[186:189], v[220:223], v[84:87]
	v_mfma_f32_16x16x32_bf16 v[80:83], v[196:199], v[220:223], v[80:83]
	v_mfma_f32_16x16x32_bf16 v[68:71], v[186:189], v[228:231], v[68:71]
	v_mfma_f32_16x16x32_bf16 v[64:67], v[196:199], v[228:231], v[64:67]
	v_mfma_f32_16x16x32_bf16 v[116:119], v[192:195], v[208:211], v[116:119]
	v_mfma_f32_16x16x32_bf16 v[112:115], v[200:203], v[208:211], v[112:115]
	v_mfma_f32_16x16x32_bf16 v[100:103], v[192:195], v[216:219], v[100:103]
	v_mfma_f32_16x16x32_bf16 v[96:99], v[200:203], v[216:219], v[96:99]
	v_mfma_f32_16x16x32_bf16 v[84:87], v[192:195], v[224:227], v[84:87]
	v_mfma_f32_16x16x32_bf16 v[80:83], v[200:203], v[224:227], v[80:83]
	v_mfma_f32_16x16x32_bf16 v[68:71], v[192:195], v[232:235], v[68:71]
	v_mfma_f32_16x16x32_bf16 v[64:67], v[200:203], v[232:235], v[64:67]
	s_barrier
	s_setprio 0
	s_add_i32 s42, s64, s44
	v_lshl_add_u64 v[144:145], v[144:145], 0, s[16:17]
	s_mov_b32 m0, s42
	ds_read_b128 v[204:207], v167 offset:49152
	ds_read_b128 v[208:211], v167 offset:50176
	ds_read_b128 v[212:215], v167 offset:51200
	ds_read_b128 v[216:219], v167 offset:52224
	ds_read_b128 v[220:223], v167 offset:53248
	ds_read_b128 v[224:227], v167 offset:54272
	ds_read_b128 v[228:231], v167 offset:55296
	ds_read_b128 v[232:235], v167 offset:56320
	global_load_lds_dwordx4 v[144:145], off
	s_add_i32 m0, s42, 0x2000
	s_add_u32 s40, s40, 0x80080
	v_lshl_add_u64 v[144:145], v[236:237], 0, s[16:17]
	s_addc_u32 s41, s41, 0
	s_add_i32 s42, s65, s44
	global_load_lds_dwordx4 v[144:145], off
	v_lshl_add_u64 v[144:145], s[40:41], 0, v[130:131]
	s_mov_b32 m0, s42
	s_nop 0
	global_load_lds_dwordx4 v[144:145], off
	v_lshl_add_u64 v[144:145], s[40:41], 0, v[134:135]
	s_add_i32 m0, s42, 0x2000
	s_nop 0
	global_load_lds_dwordx4 v[144:145], off
	v_lshl_add_u64 v[144:145], v[238:239], 0, s[16:17]
	s_mov_b32 m0, s52
	s_nop 0
	global_load_lds_dwordx4 v[144:145], off
	v_lshl_add_u64 v[144:145], v[240:241], 0, s[16:17]
	s_mov_b32 m0, s53
	s_nop 0
	global_load_lds_dwordx4 v[144:145], off
	s_waitcnt vmcnt(8)
	s_waitcnt lgkmcnt(0)
	s_setprio 1
	s_barrier
	v_mfma_f32_16x16x32_bf16 v[60:63], v[170:173], v[204:207], v[60:63]
	v_mfma_f32_16x16x32_bf16 v[56:59], v[178:181], v[204:207], v[56:59]
	v_mfma_f32_16x16x32_bf16 v[44:47], v[170:173], v[212:215], v[44:47]
	v_mfma_f32_16x16x32_bf16 v[40:43], v[178:181], v[212:215], v[40:43]
	v_mfma_f32_16x16x32_bf16 v[28:31], v[170:173], v[220:223], v[28:31]
	v_mfma_f32_16x16x32_bf16 v[24:27], v[178:181], v[220:223], v[24:27]
	v_mfma_f32_16x16x32_bf16 v[12:15], v[170:173], v[228:231], v[12:15]
	v_mfma_f32_16x16x32_bf16 v[8:11], v[178:181], v[228:231], v[8:11]
	v_mfma_f32_16x16x32_bf16 v[60:63], v[174:177], v[208:211], v[60:63]
	v_mfma_f32_16x16x32_bf16 v[56:59], v[182:185], v[208:211], v[56:59]
	v_mfma_f32_16x16x32_bf16 v[44:47], v[174:177], v[216:219], v[44:47]
	v_mfma_f32_16x16x32_bf16 v[40:43], v[182:185], v[216:219], v[40:43]
	v_mfma_f32_16x16x32_bf16 v[28:31], v[174:177], v[224:227], v[28:31]
	v_mfma_f32_16x16x32_bf16 v[24:27], v[182:185], v[224:227], v[24:27]
	v_mfma_f32_16x16x32_bf16 v[12:15], v[174:177], v[232:235], v[12:15]
	v_mfma_f32_16x16x32_bf16 v[8:11], v[182:185], v[232:235], v[8:11]
	s_setprio 0
	s_setprio 1
	v_mfma_f32_16x16x32_bf16 v[52:55], v[186:189], v[204:207], v[52:55]
	v_mfma_f32_16x16x32_bf16 v[48:51], v[196:199], v[204:207], v[48:51]
	v_mfma_f32_16x16x32_bf16 v[36:39], v[186:189], v[212:215], v[36:39]
	v_mfma_f32_16x16x32_bf16 v[32:35], v[196:199], v[212:215], v[32:35]
	v_mfma_f32_16x16x32_bf16 v[20:23], v[186:189], v[220:223], v[20:23]
	v_mfma_f32_16x16x32_bf16 v[16:19], v[196:199], v[220:223], v[16:19]
	v_mfma_f32_16x16x32_bf16 v[4:7], v[186:189], v[228:231], v[4:7]
	v_mfma_f32_16x16x32_bf16 v[0:3], v[196:199], v[228:231], v[0:3]
	v_mfma_f32_16x16x32_bf16 v[52:55], v[192:195], v[208:211], v[52:55]
	v_mfma_f32_16x16x32_bf16 v[48:51], v[200:203], v[208:211], v[48:51]
	v_mfma_f32_16x16x32_bf16 v[36:39], v[192:195], v[216:219], v[36:39]
	v_mfma_f32_16x16x32_bf16 v[32:35], v[200:203], v[216:219], v[32:35]
	v_mfma_f32_16x16x32_bf16 v[20:23], v[192:195], v[224:227], v[20:23]
	v_mfma_f32_16x16x32_bf16 v[16:19], v[200:203], v[224:227], v[16:19]
	v_mfma_f32_16x16x32_bf16 v[4:7], v[192:195], v[232:235], v[4:7]
	v_mfma_f32_16x16x32_bf16 v[0:3], v[200:203], v[232:235], v[0:3]
	s_barrier
	s_setprio 0
	s_add_i32 s63, s63, 2
	s_add_u32 s38, s38, 0x100
	s_addc_u32 s39, s39, 0
	s_add_u32 s59, s59, 0x100
	s_addc_u32 s62, s62, 0
	s_cmp_gt_u32 s63, 29
	s_cbranch_scc0 .LBB0_1912
	s_and_b64 vcc, exec, s[18:19]
	s_cbranch_vccz .LBB0_1915
	s_barrier

.LBB0_1998:
	ds_read_b128 v[144:147], v153
	ds_read_b128 v[158:161], v153 offset:1024
	ds_read_b128 v[162:165], v153 offset:2048
	ds_read_b128 v[166:169], v153 offset:3072
	ds_read_b128 v[170:173], v154
	ds_read_b128 v[174:177], v154 offset:1024
	ds_read_b128 v[178:181], v154 offset:2048
	ds_read_b128 v[182:185], v154 offset:3072
	s_add_u32 s28, s22, 0xfff80080
	s_addc_u32 s29, s23, -1
	s_cmp_eq_u32 s56, 28
	s_cselect_b32 s31, s17, s29
	s_cselect_b32 s30, s52, s28
	s_cselect_b32 s29, s15, s55
	s_cselect_b32 s28, s53, s54
	v_lshl_add_u64 v[148:149], s[22:23], 0, v[136:137]
	s_add_i32 m0, s37, 0xc000
	ds_read_b128 v[186:189], v155
	ds_read_b128 v[192:195], v155 offset:1024
	ds_read_b128 v[196:199], v155 offset:2048
	ds_read_b128 v[200:203], v155 offset:3072
	ds_read_b128 v[204:207], v155 offset:4096
	ds_read_b128 v[208:211], v155 offset:5120
	ds_read_b128 v[212:215], v155 offset:6144
	ds_read_b128 v[216:219], v155 offset:7168
	global_load_lds_dwordx4 v[148:149], off
	v_lshl_add_u64 v[148:149], s[22:23], 0, v[138:139]
	s_add_i32 m0, s37, 0xe000
	s_nop 0
	global_load_lds_dwordx4 v[148:149], off
	s_waitcnt vmcnt(8)
	s_waitcnt lgkmcnt(0)
	s_setprio 1
	s_barrier
	v_mfma_f32_16x16x32_bf16 v[124:127], v[144:147], v[186:189], v[124:127]
	v_mfma_f32_16x16x32_bf16 v[120:123], v[162:165], v[186:189], v[120:123]
	v_mfma_f32_16x16x32_bf16 v[108:111], v[144:147], v[196:199], v[108:111]
	v_mfma_f32_16x16x32_bf16 v[104:107], v[162:165], v[196:199], v[104:107]
	v_mfma_f32_16x16x32_bf16 v[92:95], v[144:147], v[204:207], v[92:95]
	v_mfma_f32_16x16x32_bf16 v[88:91], v[162:165], v[204:207], v[88:91]
	v_mfma_f32_16x16x32_bf16 v[76:79], v[144:147], v[212:215], v[76:79]
	v_mfma_f32_16x16x32_bf16 v[72:75], v[162:165], v[212:215], v[72:75]
	v_mfma_f32_16x16x32_bf16 v[124:127], v[158:161], v[192:195], v[124:127]
	v_mfma_f32_16x16x32_bf16 v[120:123], v[166:169], v[192:195], v[120:123]
	v_mfma_f32_16x16x32_bf16 v[108:111], v[158:161], v[200:203], v[108:111]
	v_mfma_f32_16x16x32_bf16 v[104:107], v[166:169], v[200:203], v[104:107]
	v_mfma_f32_16x16x32_bf16 v[92:95], v[158:161], v[208:211], v[92:95]
	v_mfma_f32_16x16x32_bf16 v[88:91], v[166:169], v[208:211], v[88:91]
	v_mfma_f32_16x16x32_bf16 v[76:79], v[158:161], v[216:219], v[76:79]
	v_mfma_f32_16x16x32_bf16 v[72:75], v[166:169], v[216:219], v[72:75]
	s_setprio 0
	s_setprio 1
	v_mfma_f32_16x16x32_bf16 v[116:119], v[170:173], v[186:189], v[116:119]
	v_mfma_f32_16x16x32_bf16 v[112:115], v[178:181], v[186:189], v[112:115]
	v_mfma_f32_16x16x32_bf16 v[100:103], v[170:173], v[196:199], v[100:103]
	v_mfma_f32_16x16x32_bf16 v[96:99], v[178:181], v[196:199], v[96:99]
	v_mfma_f32_16x16x32_bf16 v[84:87], v[170:173], v[204:207], v[84:87]
	v_mfma_f32_16x16x32_bf16 v[80:83], v[178:181], v[204:207], v[80:83]
	v_mfma_f32_16x16x32_bf16 v[68:71], v[170:173], v[212:215], v[68:71]
	v_mfma_f32_16x16x32_bf16 v[64:67], v[178:181], v[212:215], v[64:67]
	v_mfma_f32_16x16x32_bf16 v[116:119], v[174:177], v[192:195], v[116:119]
	v_mfma_f32_16x16x32_bf16 v[112:115], v[182:185], v[192:195], v[112:115]
	v_mfma_f32_16x16x32_bf16 v[100:103], v[174:177], v[200:203], v[100:103]
	v_mfma_f32_16x16x32_bf16 v[96:99], v[182:185], v[200:203], v[96:99]
	v_mfma_f32_16x16x32_bf16 v[84:87], v[174:177], v[208:211], v[84:87]
	v_mfma_f32_16x16x32_bf16 v[80:83], v[182:185], v[208:211], v[80:83]
	v_mfma_f32_16x16x32_bf16 v[68:71], v[174:177], v[216:219], v[68:71]
	v_mfma_f32_16x16x32_bf16 v[64:67], v[182:185], v[216:219], v[64:67]
	s_barrier
	s_setprio 0
	s_add_i32 s57, s46, s34
	v_lshl_add_u64 v[148:149], s[28:29], 0, v[132:133]
	s_mov_b32 m0, s57
	ds_read_b128 v[186:189], v155 offset:16384
	ds_read_b128 v[192:195], v155 offset:17408
	ds_read_b128 v[196:199], v155 offset:18432
	ds_read_b128 v[200:203], v155 offset:19456
	ds_read_b128 v[204:207], v155 offset:20480
	ds_read_b128 v[208:211], v155 offset:21504
	ds_read_b128 v[212:215], v155 offset:22528
	ds_read_b128 v[216:219], v155 offset:23552
	global_load_lds_dwordx4 v[148:149], off
	s_add_i32 m0, s57, 0x2000
	s_add_u32 s58, s28, 0x80000
	v_lshl_add_u64 v[220:221], s[28:29], 0, v[128:129]
	s_addc_u32 s59, s29, 0
	s_add_i32 s57, s47, s34
	global_load_lds_dwordx4 v[220:221], off
	v_lshl_add_u64 v[222:223], s[58:59], 0, v[132:133]
	s_mov_b32 m0, s57
	v_lshl_add_u64 v[224:225], s[30:31], 0, v[130:131]
	global_load_lds_dwordx4 v[222:223], off
	v_lshl_add_u64 v[222:223], s[58:59], 0, v[128:129]
	s_add_i32 m0, s57, 0x2000
	s_nop 0
	global_load_lds_dwordx4 v[222:223], off
	v_lshl_add_u64 v[222:223], s[30:31], 0, v[134:135]
	s_mov_b32 m0, s37
	s_nop 0
	global_load_lds_dwordx4 v[222:223], off
	s_mov_b32 m0, s38
	s_nop 0
	global_load_lds_dwordx4 v[224:225], off
	s_waitcnt vmcnt(8)
	s_waitcnt lgkmcnt(0)
	s_setprio 1
	s_barrier
	v_mfma_f32_16x16x32_bf16 v[60:63], v[144:147], v[186:189], v[60:63]
	v_mfma_f32_16x16x32_bf16 v[56:59], v[162:165], v[186:189], v[56:59]
	v_mfma_f32_16x16x32_bf16 v[44:47], v[144:147], v[196:199], v[44:47]
	v_mfma_f32_16x16x32_bf16 v[40:43], v[162:165], v[196:199], v[40:43]
	v_mfma_f32_16x16x32_bf16 v[28:31], v[144:147], v[204:207], v[28:31]
	v_mfma_f32_16x16x32_bf16 v[24:27], v[162:165], v[204:207], v[24:27]
	v_mfma_f32_16x16x32_bf16 v[12:15], v[144:147], v[212:215], v[12:15]
	v_mfma_f32_16x16x32_bf16 v[8:11], v[162:165], v[212:215], v[8:11]
	v_mfma_f32_16x16x32_bf16 v[60:63], v[158:161], v[192:195], v[60:63]
	v_mfma_f32_16x16x32_bf16 v[56:59], v[166:169], v[192:195], v[56:59]
	v_mfma_f32_16x16x32_bf16 v[44:47], v[158:161], v[200:203], v[44:47]
	v_mfma_f32_16x16x32_bf16 v[40:43], v[166:169], v[200:203], v[40:43]
	v_mfma_f32_16x16x32_bf16 v[28:31], v[158:161], v[208:211], v[28:31]
	v_mfma_f32_16x16x32_bf16 v[24:27], v[166:169], v[208:211], v[24:27]
	v_mfma_f32_16x16x32_bf16 v[12:15], v[158:161], v[216:219], v[12:15]
	v_mfma_f32_16x16x32_bf16 v[8:11], v[166:169], v[216:219], v[8:11]
	s_setprio 0
	s_setprio 1
	v_mfma_f32_16x16x32_bf16 v[52:55], v[170:173], v[186:189], v[52:55]
	v_mfma_f32_16x16x32_bf16 v[48:51], v[178:181], v[186:189], v[48:51]
	v_mfma_f32_16x16x32_bf16 v[36:39], v[170:173], v[196:199], v[36:39]
	v_mfma_f32_16x16x32_bf16 v[32:35], v[178:181], v[196:199], v[32:35]
	v_mfma_f32_16x16x32_bf16 v[20:23], v[170:173], v[204:207], v[20:23]
	v_mfma_f32_16x16x32_bf16 v[16:19], v[178:181], v[204:207], v[16:19]
	v_mfma_f32_16x16x32_bf16 v[4:7], v[170:173], v[212:215], v[4:7]
	v_mfma_f32_16x16x32_bf16 v[0:3], v[178:181], v[212:215], v[0:3]
	v_mfma_f32_16x16x32_bf16 v[52:55], v[174:177], v[192:195], v[52:55]
	v_mfma_f32_16x16x32_bf16 v[48:51], v[182:185], v[192:195], v[48:51]
	v_mfma_f32_16x16x32_bf16 v[36:39], v[174:177], v[200:203], v[36:39]
	v_mfma_f32_16x16x32_bf16 v[32:35], v[182:185], v[200:203], v[32:35]
	v_mfma_f32_16x16x32_bf16 v[20:23], v[174:177], v[208:211], v[20:23]
	v_mfma_f32_16x16x32_bf16 v[16:19], v[182:185], v[208:211], v[16:19]
	v_mfma_f32_16x16x32_bf16 v[4:7], v[174:177], v[216:219], v[4:7]
	v_mfma_f32_16x16x32_bf16 v[0:3], v[182:185], v[216:219], v[0:3]
	s_barrier
	s_setprio 0
	s_add_i32 s57, 0, 0x18000
	v_add_u32_e32 v157, s57, v151
	s_add_i32 s58, 0, 0x1c000
	ds_read_b128 v[144:147], v157
	ds_read_b128 v[158:161], v157 offset:1024
	ds_read_b128 v[162:165], v157 offset:2048
	ds_read_b128 v[166:169], v157 offset:3072
	v_add_u32_e32 v157, s58, v151
	ds_read_b128 v[170:173], v157
	ds_read_b128 v[174:177], v157 offset:1024
	ds_read_b128 v[178:181], v157 offset:2048
	ds_read_b128 v[182:185], v157 offset:3072
	s_add_u32 s30, s30, 0x80000
	s_addc_u32 s31, s31, 0
	s_mov_b32 m0, s39
	v_lshl_add_u64 v[226:227], s[30:31], 0, v[134:135]
	ds_read_b128 v[186:189], v155 offset:32768
	ds_read_b128 v[192:195], v155 offset:33792
	ds_read_b128 v[196:199], v155 offset:34816
	ds_read_b128 v[200:203], v155 offset:35840
	ds_read_b128 v[204:207], v155 offset:36864
	ds_read_b128 v[208:211], v155 offset:37888
	ds_read_b128 v[212:215], v155 offset:38912
	ds_read_b128 v[216:219], v155 offset:39936
	global_load_lds_dwordx4 v[226:227], off
	v_lshl_add_u64 v[226:227], s[30:31], 0, v[130:131]
	s_mov_b32 m0, s40
	s_nop 0
	global_load_lds_dwordx4 v[226:227], off
	s_waitcnt vmcnt(8)
	s_waitcnt lgkmcnt(0)
	s_setprio 1
	s_barrier
	v_mfma_f32_16x16x32_bf16 v[124:127], v[144:147], v[186:189], v[124:127]
	v_mfma_f32_16x16x32_bf16 v[120:123], v[162:165], v[186:189], v[120:123]
	v_mfma_f32_16x16x32_bf16 v[108:111], v[144:147], v[196:199], v[108:111]
	v_mfma_f32_16x16x32_bf16 v[104:107], v[162:165], v[196:199], v[104:107]
	v_mfma_f32_16x16x32_bf16 v[92:95], v[144:147], v[204:207], v[92:95]
	v_mfma_f32_16x16x32_bf16 v[88:91], v[162:165], v[204:207], v[88:91]
	v_mfma_f32_16x16x32_bf16 v[76:79], v[144:147], v[212:215], v[76:79]
	v_mfma_f32_16x16x32_bf16 v[72:75], v[162:165], v[212:215], v[72:75]
	v_mfma_f32_16x16x32_bf16 v[124:127], v[158:161], v[192:195], v[124:127]
	v_mfma_f32_16x16x32_bf16 v[120:123], v[166:169], v[192:195], v[120:123]
	v_mfma_f32_16x16x32_bf16 v[108:111], v[158:161], v[200:203], v[108:111]
	v_mfma_f32_16x16x32_bf16 v[104:107], v[166:169], v[200:203], v[104:107]
	v_mfma_f32_16x16x32_bf16 v[92:95], v[158:161], v[208:211], v[92:95]
	v_mfma_f32_16x16x32_bf16 v[88:91], v[166:169], v[208:211], v[88:91]
	v_mfma_f32_16x16x32_bf16 v[76:79], v[158:161], v[216:219], v[76:79]
	v_mfma_f32_16x16x32_bf16 v[72:75], v[166:169], v[216:219], v[72:75]
	s_setprio 0
	s_setprio 1
	v_mfma_f32_16x16x32_bf16 v[116:119], v[170:173], v[186:189], v[116:119]
	v_mfma_f32_16x16x32_bf16 v[112:115], v[178:181], v[186:189], v[112:115]
	v_mfma_f32_16x16x32_bf16 v[100:103], v[170:173], v[196:199], v[100:103]
	v_mfma_f32_16x16x32_bf16 v[96:99], v[178:181], v[196:199], v[96:99]
	v_mfma_f32_16x16x32_bf16 v[84:87], v[170:173], v[204:207], v[84:87]
	v_mfma_f32_16x16x32_bf16 v[80:83], v[178:181], v[204:207], v[80:83]
	v_mfma_f32_16x16x32_bf16 v[68:71], v[170:173], v[212:215], v[68:71]
	v_mfma_f32_16x16x32_bf16 v[64:67], v[178:181], v[212:215], v[64:67]
	v_mfma_f32_16x16x32_bf16 v[116:119], v[174:177], v[192:195], v[116:119]
	v_mfma_f32_16x16x32_bf16 v[112:115], v[182:185], v[192:195], v[112:115]
	v_mfma_f32_16x16x32_bf16 v[100:103], v[174:177], v[200:203], v[100:103]
	v_mfma_f32_16x16x32_bf16 v[96:99], v[182:185], v[200:203], v[96:99]
	v_mfma_f32_16x16x32_bf16 v[84:87], v[174:177], v[208:211], v[84:87]
	v_mfma_f32_16x16x32_bf16 v[80:83], v[182:185], v[208:211], v[80:83]
	v_mfma_f32_16x16x32_bf16 v[68:71], v[174:177], v[216:219], v[68:71]
	v_mfma_f32_16x16x32_bf16 v[64:67], v[182:185], v[216:219], v[64:67]
	s_barrier
	s_setprio 0
	s_add_i32 s30, s57, s34
	v_lshl_add_u64 v[148:149], v[148:149], 0, s[8:9]
	s_mov_b32 m0, s30
	ds_read_b128 v[186:189], v155 offset:49152
	ds_read_b128 v[192:195], v155 offset:50176
	ds_read_b128 v[196:199], v155 offset:51200
	ds_read_b128 v[200:203], v155 offset:52224
	ds_read_b128 v[204:207], v155 offset:53248
	ds_read_b128 v[208:211], v155 offset:54272
	ds_read_b128 v[212:215], v155 offset:55296
	ds_read_b128 v[216:219], v155 offset:56320
	global_load_lds_dwordx4 v[148:149], off
	s_add_i32 m0, s30, 0x2000
	s_add_u32 s28, s28, 0x80080
	v_lshl_add_u64 v[148:149], v[220:221], 0, s[8:9]
	s_addc_u32 s29, s29, 0
	s_add_i32 s30, s58, s34
	global_load_lds_dwordx4 v[148:149], off
	v_lshl_add_u64 v[148:149], s[28:29], 0, v[132:133]
	s_mov_b32 m0, s30
	s_nop 0
	global_load_lds_dwordx4 v[148:149], off
	v_lshl_add_u64 v[148:149], s[28:29], 0, v[128:129]
	s_add_i32 m0, s30, 0x2000
	s_nop 0
	global_load_lds_dwordx4 v[148:149], off
	v_lshl_add_u64 v[148:149], v[222:223], 0, s[8:9]
	s_mov_b32 m0, s42
	s_nop 0
	global_load_lds_dwordx4 v[148:149], off
	v_lshl_add_u64 v[148:149], v[224:225], 0, s[8:9]
	s_mov_b32 m0, s43
	s_nop 0
	global_load_lds_dwordx4 v[148:149], off
	s_waitcnt vmcnt(8)
	s_waitcnt lgkmcnt(0)
	s_setprio 1
	s_barrier
	v_mfma_f32_16x16x32_bf16 v[60:63], v[144:147], v[186:189], v[60:63]
	v_mfma_f32_16x16x32_bf16 v[56:59], v[162:165], v[186:189], v[56:59]
	v_mfma_f32_16x16x32_bf16 v[44:47], v[144:147], v[196:199], v[44:47]
	v_mfma_f32_16x16x32_bf16 v[40:43], v[162:165], v[196:199], v[40:43]
	v_mfma_f32_16x16x32_bf16 v[28:31], v[144:147], v[204:207], v[28:31]
	v_mfma_f32_16x16x32_bf16 v[24:27], v[162:165], v[204:207], v[24:27]
	v_mfma_f32_16x16x32_bf16 v[12:15], v[144:147], v[212:215], v[12:15]
	v_mfma_f32_16x16x32_bf16 v[8:11], v[162:165], v[212:215], v[8:11]
	v_mfma_f32_16x16x32_bf16 v[60:63], v[158:161], v[192:195], v[60:63]
	v_mfma_f32_16x16x32_bf16 v[56:59], v[166:169], v[192:195], v[56:59]
	v_mfma_f32_16x16x32_bf16 v[44:47], v[158:161], v[200:203], v[44:47]
	v_mfma_f32_16x16x32_bf16 v[40:43], v[166:169], v[200:203], v[40:43]
	v_mfma_f32_16x16x32_bf16 v[28:31], v[158:161], v[208:211], v[28:31]
	v_mfma_f32_16x16x32_bf16 v[24:27], v[166:169], v[208:211], v[24:27]
	v_mfma_f32_16x16x32_bf16 v[12:15], v[158:161], v[216:219], v[12:15]
	v_mfma_f32_16x16x32_bf16 v[8:11], v[166:169], v[216:219], v[8:11]
	s_setprio 0
	s_setprio 1
	v_mfma_f32_16x16x32_bf16 v[52:55], v[170:173], v[186:189], v[52:55]
	v_mfma_f32_16x16x32_bf16 v[48:51], v[178:181], v[186:189], v[48:51]
	v_mfma_f32_16x16x32_bf16 v[36:39], v[170:173], v[196:199], v[36:39]
	v_mfma_f32_16x16x32_bf16 v[32:35], v[178:181], v[196:199], v[32:35]
	v_mfma_f32_16x16x32_bf16 v[20:23], v[170:173], v[204:207], v[20:23]
	v_mfma_f32_16x16x32_bf16 v[16:19], v[178:181], v[204:207], v[16:19]
	v_mfma_f32_16x16x32_bf16 v[4:7], v[170:173], v[212:215], v[4:7]
	v_mfma_f32_16x16x32_bf16 v[0:3], v[178:181], v[212:215], v[0:3]
	v_mfma_f32_16x16x32_bf16 v[52:55], v[174:177], v[192:195], v[52:55]
	v_mfma_f32_16x16x32_bf16 v[48:51], v[182:185], v[192:195], v[48:51]
	v_mfma_f32_16x16x32_bf16 v[36:39], v[174:177], v[200:203], v[36:39]
	v_mfma_f32_16x16x32_bf16 v[32:35], v[182:185], v[200:203], v[32:35]
	v_mfma_f32_16x16x32_bf16 v[20:23], v[174:177], v[208:211], v[20:23]
	v_mfma_f32_16x16x32_bf16 v[16:19], v[182:185], v[208:211], v[16:19]
	v_mfma_f32_16x16x32_bf16 v[4:7], v[174:177], v[216:219], v[4:7]
	v_mfma_f32_16x16x32_bf16 v[0:3], v[182:185], v[216:219], v[0:3]
	s_barrier
	s_setprio 0
	s_add_i32 s56, s56, 2
	s_add_u32 s22, s22, 0x100
	s_addc_u32 s23, s23, 0
	s_add_u32 s54, s54, 0x100
	s_addc_u32 s55, s55, 0
	s_cmp_gt_u32 s56, 29
	s_cbranch_scc0 .LBB0_1998
	s_and_b64 vcc, exec, s[10:11]
	s_cbranch_vccz .LBB0_2001
	s_barrier

.LBB0_2078:
	ds_read_b128 v[144:147], v151
	ds_read_b128 v[154:157], v151 offset:1024
	ds_read_b128 v[158:161], v151 offset:2048
	ds_read_b128 v[162:165], v151 offset:3072
	ds_read_b128 v[166:169], v152
	ds_read_b128 v[170:173], v152 offset:1024
	ds_read_b128 v[174:177], v152 offset:2048
	ds_read_b128 v[178:181], v152 offset:3072
	s_add_u32 s16, s14, 0x100
	s_addc_u32 s17, s15, 0
	s_cmpk_eq_i32 s45, 0x52
	s_cselect_b32 s21, s1, s17
	s_cselect_b32 s20, s0, s16
	s_cselect_b32 s19, s13, s44
	s_cselect_b32 s18, s12, s43
	v_lshl_add_u64 v[216:217], s[14:15], 0, v[136:137]
	s_add_i32 m0, s24, 0xc000
	ds_read_b128 v[182:185], v153
	ds_read_b128 v[186:189], v153 offset:1024
	ds_read_b128 v[192:195], v153 offset:2048
	ds_read_b128 v[196:199], v153 offset:3072
	ds_read_b128 v[200:203], v153 offset:4096
	ds_read_b128 v[204:207], v153 offset:5120
	ds_read_b128 v[208:211], v153 offset:6144
	ds_read_b128 v[212:215], v153 offset:7168
	global_load_lds_dwordx4 v[216:217], off
	v_lshl_add_u64 v[216:217], s[14:15], 0, v[138:139]
	s_add_i32 m0, s24, 0xe000
	s_nop 0
	global_load_lds_dwordx4 v[216:217], off
	s_waitcnt vmcnt(8)
	s_waitcnt lgkmcnt(0)
	s_setprio 1
	s_barrier
	v_mfma_f32_16x16x32_bf16 v[124:127], v[144:147], v[182:185], v[124:127]
	v_mfma_f32_16x16x32_bf16 v[120:123], v[158:161], v[182:185], v[120:123]
	v_mfma_f32_16x16x32_bf16 v[108:111], v[144:147], v[192:195], v[108:111]
	v_mfma_f32_16x16x32_bf16 v[104:107], v[158:161], v[192:195], v[104:107]
	v_mfma_f32_16x16x32_bf16 v[92:95], v[144:147], v[200:203], v[92:95]
	v_mfma_f32_16x16x32_bf16 v[88:91], v[158:161], v[200:203], v[88:91]
	v_mfma_f32_16x16x32_bf16 v[76:79], v[144:147], v[208:211], v[76:79]
	v_mfma_f32_16x16x32_bf16 v[72:75], v[158:161], v[208:211], v[72:75]
	v_mfma_f32_16x16x32_bf16 v[124:127], v[154:157], v[186:189], v[124:127]
	v_mfma_f32_16x16x32_bf16 v[120:123], v[162:165], v[186:189], v[120:123]
	v_mfma_f32_16x16x32_bf16 v[108:111], v[154:157], v[196:199], v[108:111]
	v_mfma_f32_16x16x32_bf16 v[104:107], v[162:165], v[196:199], v[104:107]
	v_mfma_f32_16x16x32_bf16 v[92:95], v[154:157], v[204:207], v[92:95]
	v_mfma_f32_16x16x32_bf16 v[88:91], v[162:165], v[204:207], v[88:91]
	v_mfma_f32_16x16x32_bf16 v[76:79], v[154:157], v[212:215], v[76:79]
	v_mfma_f32_16x16x32_bf16 v[72:75], v[162:165], v[212:215], v[72:75]
	s_setprio 0
	s_setprio 1
	v_mfma_f32_16x16x32_bf16 v[116:119], v[166:169], v[182:185], v[116:119]
	v_mfma_f32_16x16x32_bf16 v[112:115], v[174:177], v[182:185], v[112:115]
	v_mfma_f32_16x16x32_bf16 v[100:103], v[166:169], v[192:195], v[100:103]
	v_mfma_f32_16x16x32_bf16 v[96:99], v[174:177], v[192:195], v[96:99]
	v_mfma_f32_16x16x32_bf16 v[84:87], v[166:169], v[200:203], v[84:87]
	v_mfma_f32_16x16x32_bf16 v[80:83], v[174:177], v[200:203], v[80:83]
	v_mfma_f32_16x16x32_bf16 v[68:71], v[166:169], v[208:211], v[68:71]
	v_mfma_f32_16x16x32_bf16 v[64:67], v[174:177], v[208:211], v[64:67]
	v_mfma_f32_16x16x32_bf16 v[116:119], v[170:173], v[186:189], v[116:119]
	v_mfma_f32_16x16x32_bf16 v[112:115], v[178:181], v[186:189], v[112:115]
	v_mfma_f32_16x16x32_bf16 v[100:103], v[170:173], v[196:199], v[100:103]
	v_mfma_f32_16x16x32_bf16 v[96:99], v[178:181], v[196:199], v[96:99]
	v_mfma_f32_16x16x32_bf16 v[84:87], v[170:173], v[204:207], v[84:87]
	v_mfma_f32_16x16x32_bf16 v[80:83], v[178:181], v[204:207], v[80:83]
	v_mfma_f32_16x16x32_bf16 v[68:71], v[170:173], v[212:215], v[68:71]
	v_mfma_f32_16x16x32_bf16 v[64:67], v[178:181], v[212:215], v[64:67]
	s_barrier
	s_setprio 0
	s_add_i32 s14, s37, s23
	v_lshl_add_u64 v[216:217], s[18:19], 0, v[130:131]
	s_mov_b32 m0, s14
	ds_read_b128 v[182:185], v153 offset:16384
	ds_read_b128 v[186:189], v153 offset:17408
	ds_read_b128 v[192:195], v153 offset:18432
	ds_read_b128 v[196:199], v153 offset:19456
	ds_read_b128 v[200:203], v153 offset:20480
	ds_read_b128 v[204:207], v153 offset:21504
	ds_read_b128 v[208:211], v153 offset:22528
	ds_read_b128 v[212:215], v153 offset:23552
	global_load_lds_dwordx4 v[216:217], off
	s_add_i32 m0, s14, 0x2000
	s_add_u32 s14, s18, 0x158000
	v_lshl_add_u64 v[218:219], s[18:19], 0, v[134:135]
	s_addc_u32 s15, s19, 0
	s_add_i32 s46, s38, s23
	global_load_lds_dwordx4 v[218:219], off
	v_lshl_add_u64 v[220:221], s[14:15], 0, v[130:131]
	s_mov_b32 m0, s46
	v_lshl_add_u64 v[222:223], s[20:21], 0, v[132:133]
	global_load_lds_dwordx4 v[220:221], off
	v_lshl_add_u64 v[220:221], s[14:15], 0, v[134:135]
	s_add_i32 m0, s46, 0x2000
	s_nop 0
	global_load_lds_dwordx4 v[220:221], off
	v_lshl_add_u64 v[220:221], s[20:21], 0, v[128:129]
	s_mov_b32 m0, s24
	s_nop 0
	global_load_lds_dwordx4 v[220:221], off
	s_mov_b32 m0, s25
	s_nop 0
	global_load_lds_dwordx4 v[222:223], off
	s_waitcnt vmcnt(8)
	s_waitcnt lgkmcnt(0)
	s_setprio 1
	s_barrier
	v_mfma_f32_16x16x32_bf16 v[60:63], v[144:147], v[182:185], v[60:63]
	v_mfma_f32_16x16x32_bf16 v[56:59], v[158:161], v[182:185], v[56:59]
	v_mfma_f32_16x16x32_bf16 v[44:47], v[144:147], v[192:195], v[44:47]
	v_mfma_f32_16x16x32_bf16 v[40:43], v[158:161], v[192:195], v[40:43]
	v_mfma_f32_16x16x32_bf16 v[28:31], v[144:147], v[200:203], v[28:31]
	v_mfma_f32_16x16x32_bf16 v[24:27], v[158:161], v[200:203], v[24:27]
	v_mfma_f32_16x16x32_bf16 v[12:15], v[144:147], v[208:211], v[12:15]
	v_mfma_f32_16x16x32_bf16 v[8:11], v[158:161], v[208:211], v[8:11]
	v_mfma_f32_16x16x32_bf16 v[60:63], v[154:157], v[186:189], v[60:63]
	v_mfma_f32_16x16x32_bf16 v[56:59], v[162:165], v[186:189], v[56:59]
	v_mfma_f32_16x16x32_bf16 v[44:47], v[154:157], v[196:199], v[44:47]
	v_mfma_f32_16x16x32_bf16 v[40:43], v[162:165], v[196:199], v[40:43]
	v_mfma_f32_16x16x32_bf16 v[28:31], v[154:157], v[204:207], v[28:31]
	v_mfma_f32_16x16x32_bf16 v[24:27], v[162:165], v[204:207], v[24:27]
	v_mfma_f32_16x16x32_bf16 v[12:15], v[154:157], v[212:215], v[12:15]
	v_mfma_f32_16x16x32_bf16 v[8:11], v[162:165], v[212:215], v[8:11]
	s_setprio 0
	s_setprio 1
	v_mfma_f32_16x16x32_bf16 v[52:55], v[166:169], v[182:185], v[52:55]
	v_mfma_f32_16x16x32_bf16 v[48:51], v[174:177], v[182:185], v[48:51]
	v_mfma_f32_16x16x32_bf16 v[36:39], v[166:169], v[192:195], v[36:39]
	v_mfma_f32_16x16x32_bf16 v[32:35], v[174:177], v[192:195], v[32:35]
	v_mfma_f32_16x16x32_bf16 v[20:23], v[166:169], v[200:203], v[20:23]
	v_mfma_f32_16x16x32_bf16 v[16:19], v[174:177], v[200:203], v[16:19]
	v_mfma_f32_16x16x32_bf16 v[4:7], v[166:169], v[208:211], v[4:7]
	v_mfma_f32_16x16x32_bf16 v[0:3], v[174:177], v[208:211], v[0:3]
	v_mfma_f32_16x16x32_bf16 v[52:55], v[170:173], v[186:189], v[52:55]
	v_mfma_f32_16x16x32_bf16 v[48:51], v[178:181], v[186:189], v[48:51]
	v_mfma_f32_16x16x32_bf16 v[36:39], v[170:173], v[196:199], v[36:39]
	v_mfma_f32_16x16x32_bf16 v[32:35], v[178:181], v[196:199], v[32:35]
	v_mfma_f32_16x16x32_bf16 v[20:23], v[170:173], v[204:207], v[20:23]
	v_mfma_f32_16x16x32_bf16 v[16:19], v[178:181], v[204:207], v[16:19]
	v_mfma_f32_16x16x32_bf16 v[4:7], v[170:173], v[212:215], v[4:7]
	v_mfma_f32_16x16x32_bf16 v[0:3], v[178:181], v[212:215], v[0:3]
	s_barrier
	s_setprio 0
	s_add_i32 s46, 0, 0x18000
	s_add_i32 s47, 0, 0x1c000
	v_add_u32_e32 v162, s46, v149
	v_add_u32_e32 v178, s47, v149
	ds_read_b128 v[144:147], v162
	ds_read_b128 v[154:157], v162 offset:1024
	ds_read_b128 v[158:161], v162 offset:2048
	ds_read_b128 v[162:165], v162 offset:3072
	ds_read_b128 v[166:169], v178
	ds_read_b128 v[170:173], v178 offset:1024
	ds_read_b128 v[174:177], v178 offset:2048
	ds_read_b128 v[178:181], v178 offset:3072
	s_add_u32 s14, s20, 0x158000
	s_addc_u32 s15, s21, 0
	s_mov_b32 m0, s28
	v_lshl_add_u64 v[224:225], s[14:15], 0, v[128:129]
	ds_read_b128 v[182:185], v153 offset:32768
	ds_read_b128 v[186:189], v153 offset:33792
	ds_read_b128 v[192:195], v153 offset:34816
	ds_read_b128 v[196:199], v153 offset:35840
	ds_read_b128 v[200:203], v153 offset:36864
	ds_read_b128 v[204:207], v153 offset:37888
	ds_read_b128 v[208:211], v153 offset:38912
	ds_read_b128 v[212:215], v153 offset:39936
	global_load_lds_dwordx4 v[224:225], off
	v_lshl_add_u64 v[224:225], s[14:15], 0, v[132:133]
	s_mov_b32 m0, s29
	s_nop 0
	global_load_lds_dwordx4 v[224:225], off
	s_waitcnt vmcnt(8)
	s_waitcnt lgkmcnt(0)
	s_setprio 1
	s_barrier
	v_mfma_f32_16x16x32_bf16 v[124:127], v[144:147], v[182:185], v[124:127]
	v_mfma_f32_16x16x32_bf16 v[120:123], v[158:161], v[182:185], v[120:123]
	v_mfma_f32_16x16x32_bf16 v[108:111], v[144:147], v[192:195], v[108:111]
	v_mfma_f32_16x16x32_bf16 v[104:107], v[158:161], v[192:195], v[104:107]
	v_mfma_f32_16x16x32_bf16 v[92:95], v[144:147], v[200:203], v[92:95]
	v_mfma_f32_16x16x32_bf16 v[88:91], v[158:161], v[200:203], v[88:91]
	v_mfma_f32_16x16x32_bf16 v[76:79], v[144:147], v[208:211], v[76:79]
	v_mfma_f32_16x16x32_bf16 v[72:75], v[158:161], v[208:211], v[72:75]
	v_mfma_f32_16x16x32_bf16 v[124:127], v[154:157], v[186:189], v[124:127]
	v_mfma_f32_16x16x32_bf16 v[120:123], v[162:165], v[186:189], v[120:123]
	v_mfma_f32_16x16x32_bf16 v[108:111], v[154:157], v[196:199], v[108:111]
	v_mfma_f32_16x16x32_bf16 v[104:107], v[162:165], v[196:199], v[104:107]
	v_mfma_f32_16x16x32_bf16 v[92:95], v[154:157], v[204:207], v[92:95]
	v_mfma_f32_16x16x32_bf16 v[88:91], v[162:165], v[204:207], v[88:91]
	v_mfma_f32_16x16x32_bf16 v[76:79], v[154:157], v[212:215], v[76:79]
	v_mfma_f32_16x16x32_bf16 v[72:75], v[162:165], v[212:215], v[72:75]
	s_setprio 0
	s_setprio 1
	v_mfma_f32_16x16x32_bf16 v[116:119], v[166:169], v[182:185], v[116:119]
	v_mfma_f32_16x16x32_bf16 v[112:115], v[174:177], v[182:185], v[112:115]
	v_mfma_f32_16x16x32_bf16 v[100:103], v[166:169], v[192:195], v[100:103]
	v_mfma_f32_16x16x32_bf16 v[96:99], v[174:177], v[192:195], v[96:99]
	v_mfma_f32_16x16x32_bf16 v[84:87], v[166:169], v[200:203], v[84:87]
	v_mfma_f32_16x16x32_bf16 v[80:83], v[174:177], v[200:203], v[80:83]
	v_mfma_f32_16x16x32_bf16 v[68:71], v[166:169], v[208:211], v[68:71]
	v_mfma_f32_16x16x32_bf16 v[64:67], v[174:177], v[208:211], v[64:67]
	v_mfma_f32_16x16x32_bf16 v[116:119], v[170:173], v[186:189], v[116:119]
	v_mfma_f32_16x16x32_bf16 v[112:115], v[178:181], v[186:189], v[112:115]
	v_mfma_f32_16x16x32_bf16 v[100:103], v[170:173], v[196:199], v[100:103]
	v_mfma_f32_16x16x32_bf16 v[96:99], v[178:181], v[196:199], v[96:99]
	v_mfma_f32_16x16x32_bf16 v[84:87], v[170:173], v[204:207], v[84:87]
	v_mfma_f32_16x16x32_bf16 v[80:83], v[178:181], v[204:207], v[80:83]
	v_mfma_f32_16x16x32_bf16 v[68:71], v[170:173], v[212:215], v[68:71]
	v_mfma_f32_16x16x32_bf16 v[64:67], v[178:181], v[212:215], v[64:67]
	s_barrier
	s_setprio 0
	s_add_i32 s14, s46, s23
	v_lshl_add_u64 v[216:217], v[216:217], 0, s[8:9]
	s_mov_b32 m0, s14
	ds_read_b128 v[182:185], v153 offset:49152
	ds_read_b128 v[186:189], v153 offset:50176
	ds_read_b128 v[192:195], v153 offset:51200
	ds_read_b128 v[196:199], v153 offset:52224
	ds_read_b128 v[200:203], v153 offset:53248
	ds_read_b128 v[204:207], v153 offset:54272
	ds_read_b128 v[208:211], v153 offset:55296
	ds_read_b128 v[212:215], v153 offset:56320
	global_load_lds_dwordx4 v[216:217], off
	s_add_i32 m0, s14, 0x2000
	s_add_u32 s14, s18, 0x158080
	v_lshl_add_u64 v[216:217], v[218:219], 0, s[8:9]
	s_addc_u32 s15, s19, 0
	s_add_i32 s18, s47, s23
	global_load_lds_dwordx4 v[216:217], off
	v_lshl_add_u64 v[216:217], s[14:15], 0, v[130:131]
	s_mov_b32 m0, s18
	s_nop 0
	global_load_lds_dwordx4 v[216:217], off
	v_lshl_add_u64 v[216:217], s[14:15], 0, v[134:135]
	s_add_i32 m0, s18, 0x2000
	s_nop 0
	global_load_lds_dwordx4 v[216:217], off
	v_lshl_add_u64 v[216:217], v[220:221], 0, s[8:9]
	s_mov_b32 m0, s31
	s_nop 0
	global_load_lds_dwordx4 v[216:217], off
	v_lshl_add_u64 v[216:217], v[222:223], 0, s[8:9]
	s_mov_b32 m0, s34
	s_nop 0
	global_load_lds_dwordx4 v[216:217], off
	s_waitcnt vmcnt(8)
	s_waitcnt lgkmcnt(0)
	s_setprio 1
	s_barrier
	v_mfma_f32_16x16x32_bf16 v[60:63], v[144:147], v[182:185], v[60:63]
	v_mfma_f32_16x16x32_bf16 v[56:59], v[158:161], v[182:185], v[56:59]
	v_mfma_f32_16x16x32_bf16 v[44:47], v[144:147], v[192:195], v[44:47]
	v_mfma_f32_16x16x32_bf16 v[40:43], v[158:161], v[192:195], v[40:43]
	v_mfma_f32_16x16x32_bf16 v[28:31], v[144:147], v[200:203], v[28:31]
	v_mfma_f32_16x16x32_bf16 v[24:27], v[158:161], v[200:203], v[24:27]
	v_mfma_f32_16x16x32_bf16 v[12:15], v[144:147], v[208:211], v[12:15]
	v_mfma_f32_16x16x32_bf16 v[8:11], v[158:161], v[208:211], v[8:11]
	v_mfma_f32_16x16x32_bf16 v[60:63], v[154:157], v[186:189], v[60:63]
	v_mfma_f32_16x16x32_bf16 v[56:59], v[162:165], v[186:189], v[56:59]
	v_mfma_f32_16x16x32_bf16 v[44:47], v[154:157], v[196:199], v[44:47]
	v_mfma_f32_16x16x32_bf16 v[40:43], v[162:165], v[196:199], v[40:43]
	v_mfma_f32_16x16x32_bf16 v[28:31], v[154:157], v[204:207], v[28:31]
	v_mfma_f32_16x16x32_bf16 v[24:27], v[162:165], v[204:207], v[24:27]
	v_mfma_f32_16x16x32_bf16 v[12:15], v[154:157], v[212:215], v[12:15]
	v_mfma_f32_16x16x32_bf16 v[8:11], v[162:165], v[212:215], v[8:11]
	s_setprio 0
	s_setprio 1
	v_mfma_f32_16x16x32_bf16 v[52:55], v[166:169], v[182:185], v[52:55]
	v_mfma_f32_16x16x32_bf16 v[48:51], v[174:177], v[182:185], v[48:51]
	v_mfma_f32_16x16x32_bf16 v[36:39], v[166:169], v[192:195], v[36:39]
	v_mfma_f32_16x16x32_bf16 v[32:35], v[174:177], v[192:195], v[32:35]
	v_mfma_f32_16x16x32_bf16 v[20:23], v[166:169], v[200:203], v[20:23]
	v_mfma_f32_16x16x32_bf16 v[16:19], v[174:177], v[200:203], v[16:19]
	v_mfma_f32_16x16x32_bf16 v[4:7], v[166:169], v[208:211], v[4:7]
	v_mfma_f32_16x16x32_bf16 v[0:3], v[174:177], v[208:211], v[0:3]
	v_mfma_f32_16x16x32_bf16 v[52:55], v[170:173], v[186:189], v[52:55]
	v_mfma_f32_16x16x32_bf16 v[48:51], v[178:181], v[186:189], v[48:51]
	v_mfma_f32_16x16x32_bf16 v[36:39], v[170:173], v[196:199], v[36:39]
	v_mfma_f32_16x16x32_bf16 v[32:35], v[178:181], v[196:199], v[32:35]
	v_mfma_f32_16x16x32_bf16 v[20:23], v[170:173], v[204:207], v[20:23]
	v_mfma_f32_16x16x32_bf16 v[16:19], v[178:181], v[204:207], v[16:19]
	v_mfma_f32_16x16x32_bf16 v[4:7], v[170:173], v[212:215], v[4:7]
	v_mfma_f32_16x16x32_bf16 v[0:3], v[178:181], v[212:215], v[0:3]
	s_barrier
	s_setprio 0
	s_add_i32 s45, s45, 2
	s_add_u32 s43, s43, 0x100
	s_addc_u32 s44, s44, 0
	s_cmpk_gt_u32 s45, 0x53
	s_mov_b64 s[14:15], s[16:17]
	s_cbranch_scc0 .LBB0_2078
	s_and_b64 vcc, exec, s[10:11]
	s_cbranch_vccz .LBB0_2081
	s_barrier
